# gemm160 phases: LDS-DMA ring continues across tiles (last two K iterations fetch the next tile's first two K-tiles), own tile prologue
# speedup vs baseline: 1.0296x; 1.0079x over previous
.LBB0_231:
	v_readlane_b32 s6, v254, 0
	v_readlane_b32 s7, v254, 1
	s_load_dwordx2 s[6:7], s[6:7], 0xe0
	s_xor_b64 s[4:5], s[4:5], -1
	s_waitcnt vmcnt(0)
	v_mov_b32_e32 v6, v222
	v_writelane_b32 v254, s4, 17
	s_waitcnt lgkmcnt(0)
	s_ashr_i32 s71, s70, 31
	s_mul_i32 s8, s70, 0x15e0000
	v_lshrrev_b32_e32 v7, 4, v6
	v_ashrrev_i32_e32 v0, 3, v6
	v_writelane_b32 v254, s5, 18
	s_mul_hi_i32 s9, s70, 0x15e0000
	s_add_u32 s4, s6, s8
	v_xor_b32_e32 v8, v7, v6
	v_ashrrev_i32_e32 v1, 31, v0
	v_writelane_b32 v254, s8, 19
	s_addc_u32 s5, s7, s9
	v_lshlrev_b64 v[0:1], 11, v[0:1]
	v_lshlrev_b32_e32 v8, 4, v8
	v_lshl_add_u64 v[2:3], s[4:5], 0, v[0:1]
	v_and_b32_e32 v128, 0x70, v8
	v_and_b32_e32 v94, 15, v6
	v_bfe_u32 v9, v6, 1, 3
	v_lshl_add_u64 v[82:83], v[2:3], 0, v[128:129]
	v_bfe_u32 v2, v6, 4, 2
	v_ashrrev_i32_e32 v4, 1, v6
	v_lshlrev_b32_e32 v97, 7, v94
	v_bitop3_b32 v3, v7, v9, 3 bitop3:0x6c
	v_bitop3_b32 v2, v2, v9, 4 bitop3:0x36
	v_and_b32_e32 v10, 0xffffffe0, v4
	v_lshlrev_b32_e32 v98, 4, v3
	v_lshlrev_b32_e32 v99, 4, v2
	v_add_u32_e32 v2, 0, v97
	v_or_b32_e32 v4, v10, v94
	v_add_u32_e32 v101, v2, v98
	v_add_u32_e32 v103, v2, v99
	v_lshrrev_b32_e32 v2, 2, v6
	v_lshlrev_b32_e32 v95, 7, v4
	v_lshl_add_u64 v[4:5], s[6:7], 0, v[0:1]
	v_and_or_b32 v105, v2, 12, v10
	v_bitop3_b32 v2, v7, 7, v6 bitop3:0x48
	v_lshl_add_u64 v[4:5], v[4:5], 0, v[128:129]
	s_mov_b64 s[4:5], 0x2c31000
	v_lshl_or_b32 v0, v2, 4, v0
	v_mov_b32_e32 v2, 0x15e0000
	v_writelane_b32 v254, s9, 20
	s_add_u32 s8, s6, 0x7c31000
	v_lshl_add_u64 v[80:81], v[4:5], 0, s[4:5]
	s_movk_i32 s4, 0x100
	v_lshl_add_u32 v96, v6, 4, 0
	v_add_u32_e32 v3, 0, v95
	v_lshl_add_u64 v[84:85], s[6:7], 0, v[0:1]
	v_mad_i64_i32 v[0:1], s[10:11], s70, v2, v[0:1]
	s_addc_u32 s9, s7, 0
	v_cmp_gt_i32_e64 s[4:5], s4, v6
	v_add_u32_e32 v100, 0xd000, v3
	v_add_u32_e32 v102, 0xd000, v101
	v_add_u32_e32 v104, 0xd000, v103
	v_lshl_add_u64 v[86:87], s[6:7], 0, v[0:1]
	v_add_u32_e32 v106, 0x2000, v96
	v_add_u32_e32 v107, 0x4000, v96
	v_add_u32_e32 v108, 0x5000, v96
	v_add_u32_e32 v109, 0x7000, v96
	v_add_u32_e32 v110, 0x9000, v96
	v_add_u32_e32 v111, 0xb000, v96
	s_mov_b32 s99, 0
	s_mov_b32 s100, 0
	s_mov_b32 s14, s45
	s_branch .LBB0_234
.LBB0_232:
	s_or_b64 exec, exec, s[10:11]
	s_add_i32 s14, s14, 1
	s_mov_b32 s100, s101
	s_mov_b64 s[6:7], 0

.LBB0_239:
	s_mul_hi_i32 s6, s10, 0x66666667
	s_lshr_b32 s7, s6, 31
	s_ashr_i32 s6, s6, 4
	s_add_i32 s6, s6, s7
	s_lshl_b32 s11, s6, 3
	s_and_b32 s12, s10, 7
	s_or_b32 s15, s11, s12
	s_ashr_i32 s6, s10, 3
	s_mul_hi_i32 s7, s6, 0x66666667
	s_lshr_b32 s10, s7, 31
	s_ashr_i32 s7, s7, 1
	s_add_i32 s7, s7, s10
	s_mul_i32 s7, s7, 5
	s_sub_i32 s6, s6, s7
	s_ashr_i32 s7, s6, 31
	s_lshl_b64 s[16:17], s[6:7], 19
	v_mad_i64_i32 v[88:89], s[18:19], s15, v224, v[84:85]
	v_lshl_add_u64 v[90:91], v[86:87], 0, s[16:17]
	s_add_i32 s11, s14, 1
	s_lshl_b32 s12, s11, 8
	s_add_i32 s12, s12, s89
	s_mul_i32 s13, s11, s60
	s_add_i32 s13, s13, s2
	s_cmp_eq_u64 s[64:65], 0
	s_cselect_b32 s12, s12, s13
	s_cmpk_le_i32 s12, 0x4ff
	s_cselect_b32 s101, 1, 0
	s_mul_hi_i32 s13, s12, 0x66666667
	s_lshr_b32 s18, s13, 31
	s_ashr_i32 s13, s13, 4
	s_add_i32 s13, s13, s18
	s_lshl_b32 s13, s13, 3
	s_and_b32 s18, s12, 7
	s_or_b32 s13, s13, s18
	s_ashr_i32 s16, s12, 3
	s_mul_hi_i32 s17, s16, 0x66666667
	s_lshr_b32 s18, s17, 31
	s_ashr_i32 s17, s17, 1
	s_add_i32 s17, s17, s18
	s_mul_i32 s17, s17, 5
	s_sub_i32 s16, s16, s17
	s_ashr_i32 s17, s16, 31
	s_lshl_b64 s[16:17], s[16:17], 19
	v_mad_i64_i32 v[106:107], s[18:19], s13, v224, v[84:85]
	v_lshl_add_u64 v[108:109], v[86:87], 0, s[16:17]
	s_mov_b64 s[10:11], 0
	v_mov_b32_e32 v0, 0
	v_mov_b32_e32 v1, v0
	v_mov_b32_e32 v2, v0
	v_mov_b32_e32 v3, v0
	v_mov_b32_e32 v4, v0
	v_mov_b32_e32 v5, v0
	v_mov_b32_e32 v6, v0
	v_mov_b32_e32 v7, v0
	v_mov_b32_e32 v8, v0
	v_mov_b32_e32 v9, v0
	v_mov_b32_e32 v10, v0
	v_mov_b32_e32 v11, v0
	v_mov_b32_e32 v12, v0
	v_mov_b32_e32 v13, v0
	v_mov_b32_e32 v14, v0
	v_mov_b32_e32 v15, v0
	v_mov_b32_e32 v16, v0
	v_mov_b32_e32 v17, v0
	v_mov_b32_e32 v18, v0
	v_mov_b32_e32 v19, v0
	v_mov_b32_e32 v20, v0
	v_mov_b32_e32 v21, v0
	v_mov_b32_e32 v22, v0
	v_mov_b32_e32 v23, v0
	v_mov_b32_e32 v24, v0
	v_mov_b32_e32 v25, v0
	v_mov_b32_e32 v26, v0
	v_mov_b32_e32 v27, v0
	v_mov_b32_e32 v28, v0
	v_mov_b32_e32 v29, v0
	v_mov_b32_e32 v30, v0
	v_mov_b32_e32 v31, v0
	v_mov_b32_e32 v32, v0
	v_mov_b32_e32 v33, v0
	v_mov_b32_e32 v34, v0
	v_mov_b32_e32 v35, v0
	v_mov_b32_e32 v36, v0
	v_mov_b32_e32 v37, v0
	v_mov_b32_e32 v38, v0
	v_mov_b32_e32 v39, v0
	v_mov_b32_e32 v40, v0
	v_mov_b32_e32 v41, v0
	v_mov_b32_e32 v42, v0
	v_mov_b32_e32 v43, v0
	v_mov_b32_e32 v44, v0
	v_mov_b32_e32 v45, v0
	v_mov_b32_e32 v46, v0
	v_mov_b32_e32 v47, v0
	v_mov_b32_e32 v48, v0
	v_mov_b32_e32 v49, v0
	v_mov_b32_e32 v50, v0
	v_mov_b32_e32 v51, v0
	v_mov_b32_e32 v52, v0
	v_mov_b32_e32 v53, v0
	v_mov_b32_e32 v54, v0
	v_mov_b32_e32 v55, v0
	v_mov_b32_e32 v56, v0
	v_mov_b32_e32 v57, v0
	v_mov_b32_e32 v58, v0
	v_mov_b32_e32 v59, v0
	v_mov_b32_e32 v60, v0
	v_mov_b32_e32 v61, v0
	v_mov_b32_e32 v62, v0
	v_mov_b32_e32 v63, v0
	v_mov_b32_e32 v64, v0
	v_mov_b32_e32 v65, v0
	v_mov_b32_e32 v66, v0
	v_mov_b32_e32 v67, v0
	v_mov_b32_e32 v68, v0
	v_mov_b32_e32 v69, v0
	v_mov_b32_e32 v70, v0
	v_mov_b32_e32 v71, v0
	v_mov_b32_e32 v72, v0
	v_mov_b32_e32 v73, v0
	v_mov_b32_e32 v74, v0
	v_mov_b32_e32 v75, v0
	v_mov_b32_e32 v76, v0
	v_mov_b32_e32 v77, v0
	v_mov_b32_e32 v78, v0
	v_mov_b32_e32 v79, v0
	s_cmp_eq_u32 s100, 0
	s_cbranch_scc0 .Lgxi_go
	s_add_u32 s12, s99, 0x0
	s_cmp_ge_u32 s12, 0x27000
	s_cselect_b32 s13, 0x27000, 0
	s_sub_u32 s12, s12, s13
	v_add_u32_e32 v172, s12, v96
	s_mov_b32 s12, 0xffffff80
	s_mov_b32 s13, -1
	v_lshl_add_u64 v[92:93], v[88:89], 0, s[12:13]
	v_lshl_add_u64 v[190:191], v[90:91], 0, s[12:13]
	v_readfirstlane_b32 s98, v172
	v_lshl_add_u64 v[192:193], v[92:93], 0, s[78:79]
	s_mov_b32 m0, s98
	s_nop 0
	global_load_lds_dwordx4 v[192:193], off
	v_lshl_add_u64 v[192:193], v[92:93], 0, s[80:81]
	s_add_u32 m0, s98, 0x2000
	s_nop 0
	global_load_lds_dwordx4 v[192:193], off
	s_cmp_eq_u64 s[4:5], 0
	s_cbranch_scc1 .Lgxi_ps0
	v_lshl_add_u64 v[192:193], v[92:93], 0, s[82:83]
	s_add_u32 m0, s98, 0x4000
	s_nop 0
	global_load_lds_dwordx4 v[192:193], off
.Lgxi_ps0:
	s_mov_b64 s[12:13], 0x80
	v_lshl_add_u64 v[192:193], v[190:191], 0, s[12:13]
	s_add_u32 m0, s98, 0x5000
	s_nop 0
	global_load_lds_dwordx4 v[192:193], off
	s_mov_b64 s[12:13], 0x20080
	v_lshl_add_u64 v[192:193], v[190:191], 0, s[12:13]
	s_add_u32 m0, s98, 0x7000
	s_nop 0
	global_load_lds_dwordx4 v[192:193], off
	s_mov_b64 s[12:13], 0x40080
	v_lshl_add_u64 v[192:193], v[190:191], 0, s[12:13]
	s_add_u32 m0, s98, 0x9000
	s_nop 0
	global_load_lds_dwordx4 v[192:193], off
	s_mov_b64 s[12:13], 0x60080
	v_lshl_add_u64 v[192:193], v[190:191], 0, s[12:13]
	s_add_u32 m0, s98, 0xb000
	s_nop 0
	global_load_lds_dwordx4 v[192:193], off
	s_add_u32 s12, s99, 0xd000
	s_cmp_ge_u32 s12, 0x27000
	s_cselect_b32 s13, 0x27000, 0
	s_sub_u32 s12, s12, s13
	v_add_u32_e32 v172, s12, v96
	s_mov_b64 s[12:13], 0
	v_lshl_add_u64 v[92:93], v[88:89], 0, s[12:13]
	v_lshl_add_u64 v[190:191], v[90:91], 0, s[12:13]
	v_readfirstlane_b32 s98, v172
	v_lshl_add_u64 v[192:193], v[92:93], 0, s[78:79]
	s_mov_b32 m0, s98
	s_nop 0
	global_load_lds_dwordx4 v[192:193], off
	v_lshl_add_u64 v[192:193], v[92:93], 0, s[80:81]
	s_add_u32 m0, s98, 0x2000
	s_nop 0
	global_load_lds_dwordx4 v[192:193], off
	s_cmp_eq_u64 s[4:5], 0
	s_cbranch_scc1 .Lgxi_ps1
	v_lshl_add_u64 v[192:193], v[92:93], 0, s[82:83]
	s_add_u32 m0, s98, 0x4000
	s_nop 0
	global_load_lds_dwordx4 v[192:193], off
.Lgxi_ps1:
	s_mov_b64 s[12:13], 0x80
	v_lshl_add_u64 v[192:193], v[190:191], 0, s[12:13]
	s_add_u32 m0, s98, 0x5000
	s_nop 0
	global_load_lds_dwordx4 v[192:193], off
	s_mov_b64 s[12:13], 0x20080
	v_lshl_add_u64 v[192:193], v[190:191], 0, s[12:13]
	s_add_u32 m0, s98, 0x7000
	s_nop 0
	global_load_lds_dwordx4 v[192:193], off
	s_mov_b64 s[12:13], 0x40080
	v_lshl_add_u64 v[192:193], v[190:191], 0, s[12:13]
	s_add_u32 m0, s98, 0x9000
	s_nop 0
	global_load_lds_dwordx4 v[192:193], off
	s_mov_b64 s[12:13], 0x60080
	v_lshl_add_u64 v[192:193], v[190:191], 0, s[12:13]
	s_add_u32 m0, s98, 0xb000
	s_nop 0
	global_load_lds_dwordx4 v[192:193], off
.Lgxi_go:
	s_cmp_eq_u64 s[4:5], 0
	s_cbranch_scc1 .Lgxi_q
.Lgxi_p:
	v_add_u32_e32 v168, s99, v95
	v_add_u32_e32 v169, s99, v97
	v_add_u32_e32 v196, v168, v99
	v_add_u32_e32 v200, v169, v99
	v_add_u32_e32 v168, v168, v98
	v_add_u32_e32 v169, v169, v98
	s_waitcnt vmcnt(7) lgkmcnt(0)
	s_barrier
	ds_read_b128 v[156:159], v168 offset:20480
	ds_read_b128 v[160:163], v168 offset:22528
	ds_read_b128 v[112:115], v169
	ds_read_b128 v[116:119], v169 offset:2048
	ds_read_b128 v[120:123], v169 offset:4096
	ds_read_b128 v[124:127], v169 offset:6144
	ds_read_b128 v[132:135], v169 offset:8192
	ds_read_b128 v[136:139], v169 offset:10240
	ds_read_b128 v[140:143], v169 offset:12288
	ds_read_b128 v[144:147], v169 offset:14336
	ds_read_b128 v[148:151], v169 offset:16384
	ds_read_b128 v[152:155], v169 offset:18432
	s_waitcnt lgkmcnt(9)
	v_mfma_f32_16x16x32_bf16 v[76:79], v[156:159], v[112:115], v[76:79]
	v_mfma_f32_16x16x32_bf16 v[72:75], v[160:163], v[112:115], v[72:75]
	ds_read_b128 v[204:207], v196 offset:20480
	s_waitcnt lgkmcnt(9)
	v_mfma_f32_16x16x32_bf16 v[68:71], v[156:159], v[116:119], v[68:71]
	v_mfma_f32_16x16x32_bf16 v[64:67], v[160:163], v[116:119], v[64:67]
	ds_read_b128 v[208:211], v196 offset:22528
	s_waitcnt lgkmcnt(9)
	v_mfma_f32_16x16x32_bf16 v[60:63], v[156:159], v[120:123], v[60:63]
	v_mfma_f32_16x16x32_bf16 v[56:59], v[160:163], v[120:123], v[56:59]
	ds_read_b128 v[164:167], v200
	s_waitcnt lgkmcnt(9)
	v_mfma_f32_16x16x32_bf16 v[52:55], v[156:159], v[124:127], v[52:55]
	v_mfma_f32_16x16x32_bf16 v[48:51], v[160:163], v[124:127], v[48:51]
	ds_read_b128 v[168:171], v200 offset:2048
	s_waitcnt lgkmcnt(9)
	v_mfma_f32_16x16x32_bf16 v[44:47], v[156:159], v[132:135], v[44:47]
	v_mfma_f32_16x16x32_bf16 v[40:43], v[160:163], v[132:135], v[40:43]
	ds_read_b128 v[172:175], v200 offset:4096
	s_waitcnt lgkmcnt(9)
	v_mfma_f32_16x16x32_bf16 v[36:39], v[156:159], v[136:139], v[36:39]
	v_mfma_f32_16x16x32_bf16 v[32:35], v[160:163], v[136:139], v[32:35]
	ds_read_b128 v[176:179], v200 offset:6144
	s_waitcnt lgkmcnt(9)
	v_mfma_f32_16x16x32_bf16 v[28:31], v[156:159], v[140:143], v[28:31]
	v_mfma_f32_16x16x32_bf16 v[24:27], v[160:163], v[140:143], v[24:27]
	ds_read_b128 v[180:183], v200 offset:8192
	s_waitcnt lgkmcnt(9)
	v_mfma_f32_16x16x32_bf16 v[20:23], v[156:159], v[144:147], v[20:23]
	v_mfma_f32_16x16x32_bf16 v[16:19], v[160:163], v[144:147], v[16:19]
	ds_read_b128 v[184:187], v200 offset:10240
	s_waitcnt lgkmcnt(9)
	v_mfma_f32_16x16x32_bf16 v[12:15], v[156:159], v[148:151], v[12:15]
	v_mfma_f32_16x16x32_bf16 v[8:11], v[160:163], v[148:151], v[8:11]
	ds_read_b128 v[188:191], v200 offset:12288
	s_waitcnt lgkmcnt(9)
	v_mfma_f32_16x16x32_bf16 v[4:7], v[156:159], v[152:155], v[4:7]
	v_mfma_f32_16x16x32_bf16 v[0:3], v[160:163], v[152:155], v[0:3]
	ds_read_b128 v[192:195], v200 offset:14336
	ds_read_b128 v[196:199], v200 offset:16384
	ds_read_b128 v[200:203], v200 offset:18432
	s_waitcnt lgkmcnt(9)
	v_mfma_f32_16x16x32_bf16 v[76:79], v[204:207], v[164:167], v[76:79]
	v_mfma_f32_16x16x32_bf16 v[72:75], v[208:211], v[164:167], v[72:75]
	s_waitcnt lgkmcnt(8)
	v_mfma_f32_16x16x32_bf16 v[68:71], v[204:207], v[168:171], v[68:71]
	v_mfma_f32_16x16x32_bf16 v[64:67], v[208:211], v[168:171], v[64:67]
	s_waitcnt lgkmcnt(7)
	v_mfma_f32_16x16x32_bf16 v[60:63], v[204:207], v[172:175], v[60:63]
	v_mfma_f32_16x16x32_bf16 v[56:59], v[208:211], v[172:175], v[56:59]
	s_waitcnt lgkmcnt(6)
	v_mfma_f32_16x16x32_bf16 v[52:55], v[204:207], v[176:179], v[52:55]
	v_mfma_f32_16x16x32_bf16 v[48:51], v[208:211], v[176:179], v[48:51]
	s_waitcnt lgkmcnt(5)
	v_mfma_f32_16x16x32_bf16 v[44:47], v[204:207], v[180:183], v[44:47]
	v_mfma_f32_16x16x32_bf16 v[40:43], v[208:211], v[180:183], v[40:43]
	s_waitcnt lgkmcnt(4)
	v_mfma_f32_16x16x32_bf16 v[36:39], v[204:207], v[184:187], v[36:39]
	v_mfma_f32_16x16x32_bf16 v[32:35], v[208:211], v[184:187], v[32:35]
	s_waitcnt lgkmcnt(3)
	v_mfma_f32_16x16x32_bf16 v[28:31], v[204:207], v[188:191], v[28:31]
	v_mfma_f32_16x16x32_bf16 v[24:27], v[208:211], v[188:191], v[24:27]
	s_waitcnt lgkmcnt(2)
	v_mfma_f32_16x16x32_bf16 v[20:23], v[204:207], v[192:195], v[20:23]
	v_mfma_f32_16x16x32_bf16 v[16:19], v[208:211], v[192:195], v[16:19]
	s_waitcnt lgkmcnt(1)
	v_mfma_f32_16x16x32_bf16 v[12:15], v[204:207], v[196:199], v[12:15]
	v_mfma_f32_16x16x32_bf16 v[8:11], v[208:211], v[196:199], v[8:11]
	s_waitcnt lgkmcnt(0)
	v_mfma_f32_16x16x32_bf16 v[4:7], v[204:207], v[200:203], v[4:7]
	v_mfma_f32_16x16x32_bf16 v[0:3], v[208:211], v[200:203], v[0:3]
	s_add_u32 s12, s99, 0x1a000
	s_cmp_ge_u32 s12, 0x27000
	s_cselect_b32 s13, 0x27000, 0
	s_sub_u32 s12, s12, s13
	v_add_u32_e32 v172, s12, v96
	s_add_u32 s12, s10, 0x80
	s_addc_u32 s13, s11, 0
	v_lshl_add_u64 v[92:93], v[88:89], 0, s[12:13]
	v_lshl_add_u64 v[190:191], v[90:91], 0, s[12:13]
	v_readfirstlane_b32 s98, v172
	v_lshl_add_u64 v[192:193], v[92:93], 0, s[78:79]
	s_mov_b32 m0, s98
	s_nop 0
	global_load_lds_dwordx4 v[192:193], off
	v_lshl_add_u64 v[192:193], v[92:93], 0, s[80:81]
	s_add_u32 m0, s98, 0x2000
	s_nop 0
	global_load_lds_dwordx4 v[192:193], off
	v_lshl_add_u64 v[192:193], v[92:93], 0, s[82:83]
	s_add_u32 m0, s98, 0x4000
	s_nop 0
	global_load_lds_dwordx4 v[192:193], off
	s_mov_b64 s[12:13], 0x80
	v_lshl_add_u64 v[192:193], v[190:191], 0, s[12:13]
	s_add_u32 m0, s98, 0x5000
	s_nop 0
	global_load_lds_dwordx4 v[192:193], off
	s_mov_b64 s[12:13], 0x20080
	v_lshl_add_u64 v[192:193], v[190:191], 0, s[12:13]
	s_add_u32 m0, s98, 0x7000
	s_nop 0
	global_load_lds_dwordx4 v[192:193], off
	s_mov_b64 s[12:13], 0x40080
	v_lshl_add_u64 v[192:193], v[190:191], 0, s[12:13]
	s_add_u32 m0, s98, 0x9000
	s_nop 0
	global_load_lds_dwordx4 v[192:193], off
	s_mov_b64 s[12:13], 0x60080
	v_lshl_add_u64 v[192:193], v[190:191], 0, s[12:13]
	s_add_u32 m0, s98, 0xb000
	s_nop 0
	global_load_lds_dwordx4 v[192:193], off
	s_add_u32 s99, s99, 0xd000
	s_cmp_eq_u32 s99, 0x27000
	s_cselect_b32 s99, 0, s99
	s_add_u32 s10, s10, 0x80
	s_addc_u32 s11, s11, 0
	s_cmpk_eq_i32 s10, 0x700
	s_cbranch_scc0 .Lgxi_p
	v_add_u32_e32 v168, s99, v95
	v_add_u32_e32 v169, s99, v97
	v_add_u32_e32 v196, v168, v99
	v_add_u32_e32 v200, v169, v99
	v_add_u32_e32 v168, v168, v98
	v_add_u32_e32 v169, v169, v98
	s_waitcnt vmcnt(7) lgkmcnt(0)
	s_barrier
	ds_read_b128 v[156:159], v168 offset:20480
	ds_read_b128 v[160:163], v168 offset:22528
	ds_read_b128 v[112:115], v169
	ds_read_b128 v[116:119], v169 offset:2048
	ds_read_b128 v[120:123], v169 offset:4096
	ds_read_b128 v[124:127], v169 offset:6144
	ds_read_b128 v[132:135], v169 offset:8192
	ds_read_b128 v[136:139], v169 offset:10240
	ds_read_b128 v[140:143], v169 offset:12288
	ds_read_b128 v[144:147], v169 offset:14336
	ds_read_b128 v[148:151], v169 offset:16384
	ds_read_b128 v[152:155], v169 offset:18432
	s_waitcnt lgkmcnt(9)
	v_mfma_f32_16x16x32_bf16 v[76:79], v[156:159], v[112:115], v[76:79]
	v_mfma_f32_16x16x32_bf16 v[72:75], v[160:163], v[112:115], v[72:75]
	ds_read_b128 v[204:207], v196 offset:20480
	s_waitcnt lgkmcnt(9)
	v_mfma_f32_16x16x32_bf16 v[68:71], v[156:159], v[116:119], v[68:71]
	v_mfma_f32_16x16x32_bf16 v[64:67], v[160:163], v[116:119], v[64:67]
	ds_read_b128 v[208:211], v196 offset:22528
	s_waitcnt lgkmcnt(9)
	v_mfma_f32_16x16x32_bf16 v[60:63], v[156:159], v[120:123], v[60:63]
	v_mfma_f32_16x16x32_bf16 v[56:59], v[160:163], v[120:123], v[56:59]
	ds_read_b128 v[164:167], v200
	s_waitcnt lgkmcnt(9)
	v_mfma_f32_16x16x32_bf16 v[52:55], v[156:159], v[124:127], v[52:55]
	v_mfma_f32_16x16x32_bf16 v[48:51], v[160:163], v[124:127], v[48:51]
	ds_read_b128 v[168:171], v200 offset:2048
	s_waitcnt lgkmcnt(9)
	v_mfma_f32_16x16x32_bf16 v[44:47], v[156:159], v[132:135], v[44:47]
	v_mfma_f32_16x16x32_bf16 v[40:43], v[160:163], v[132:135], v[40:43]
	ds_read_b128 v[172:175], v200 offset:4096
	s_waitcnt lgkmcnt(9)
	v_mfma_f32_16x16x32_bf16 v[36:39], v[156:159], v[136:139], v[36:39]
	v_mfma_f32_16x16x32_bf16 v[32:35], v[160:163], v[136:139], v[32:35]
	ds_read_b128 v[176:179], v200 offset:6144
	s_waitcnt lgkmcnt(9)
	v_mfma_f32_16x16x32_bf16 v[28:31], v[156:159], v[140:143], v[28:31]
	v_mfma_f32_16x16x32_bf16 v[24:27], v[160:163], v[140:143], v[24:27]
	ds_read_b128 v[180:183], v200 offset:8192
	s_waitcnt lgkmcnt(9)
	v_mfma_f32_16x16x32_bf16 v[20:23], v[156:159], v[144:147], v[20:23]
	v_mfma_f32_16x16x32_bf16 v[16:19], v[160:163], v[144:147], v[16:19]
	ds_read_b128 v[184:187], v200 offset:10240
	s_waitcnt lgkmcnt(9)
	v_mfma_f32_16x16x32_bf16 v[12:15], v[156:159], v[148:151], v[12:15]
	v_mfma_f32_16x16x32_bf16 v[8:11], v[160:163], v[148:151], v[8:11]
	ds_read_b128 v[188:191], v200 offset:12288
	s_waitcnt lgkmcnt(9)
	v_mfma_f32_16x16x32_bf16 v[4:7], v[156:159], v[152:155], v[4:7]
	v_mfma_f32_16x16x32_bf16 v[0:3], v[160:163], v[152:155], v[0:3]
	ds_read_b128 v[192:195], v200 offset:14336
	ds_read_b128 v[196:199], v200 offset:16384
	ds_read_b128 v[200:203], v200 offset:18432
	s_waitcnt lgkmcnt(9)
	v_mfma_f32_16x16x32_bf16 v[76:79], v[204:207], v[164:167], v[76:79]
	v_mfma_f32_16x16x32_bf16 v[72:75], v[208:211], v[164:167], v[72:75]
	s_waitcnt lgkmcnt(8)
	v_mfma_f32_16x16x32_bf16 v[68:71], v[204:207], v[168:171], v[68:71]
	v_mfma_f32_16x16x32_bf16 v[64:67], v[208:211], v[168:171], v[64:67]
	s_waitcnt lgkmcnt(7)
	v_mfma_f32_16x16x32_bf16 v[60:63], v[204:207], v[172:175], v[60:63]
	v_mfma_f32_16x16x32_bf16 v[56:59], v[208:211], v[172:175], v[56:59]
	s_waitcnt lgkmcnt(6)
	v_mfma_f32_16x16x32_bf16 v[52:55], v[204:207], v[176:179], v[52:55]
	v_mfma_f32_16x16x32_bf16 v[48:51], v[208:211], v[176:179], v[48:51]
	s_waitcnt lgkmcnt(5)
	v_mfma_f32_16x16x32_bf16 v[44:47], v[204:207], v[180:183], v[44:47]
	v_mfma_f32_16x16x32_bf16 v[40:43], v[208:211], v[180:183], v[40:43]
	s_waitcnt lgkmcnt(4)
	v_mfma_f32_16x16x32_bf16 v[36:39], v[204:207], v[184:187], v[36:39]
	v_mfma_f32_16x16x32_bf16 v[32:35], v[208:211], v[184:187], v[32:35]
	s_waitcnt lgkmcnt(3)
	v_mfma_f32_16x16x32_bf16 v[28:31], v[204:207], v[188:191], v[28:31]
	v_mfma_f32_16x16x32_bf16 v[24:27], v[208:211], v[188:191], v[24:27]
	s_waitcnt lgkmcnt(2)
	v_mfma_f32_16x16x32_bf16 v[20:23], v[204:207], v[192:195], v[20:23]
	v_mfma_f32_16x16x32_bf16 v[16:19], v[208:211], v[192:195], v[16:19]
	s_waitcnt lgkmcnt(1)
	v_mfma_f32_16x16x32_bf16 v[12:15], v[204:207], v[196:199], v[12:15]
	v_mfma_f32_16x16x32_bf16 v[8:11], v[208:211], v[196:199], v[8:11]
	s_waitcnt lgkmcnt(0)
	v_mfma_f32_16x16x32_bf16 v[4:7], v[204:207], v[200:203], v[4:7]
	v_mfma_f32_16x16x32_bf16 v[0:3], v[208:211], v[200:203], v[0:3]
	s_cmp_eq_u32 s101, 0
	s_cbranch_scc1 .Lgxi_pbb
	s_add_u32 s12, s99, 0x1a000
	s_cmp_ge_u32 s12, 0x27000
	s_cselect_b32 s13, 0x27000, 0
	s_sub_u32 s12, s12, s13
	v_add_u32_e32 v172, s12, v96
	s_mov_b32 s12, 0xffffff80
	s_mov_b32 s13, -1
	v_lshl_add_u64 v[92:93], v[106:107], 0, s[12:13]
	v_lshl_add_u64 v[190:191], v[108:109], 0, s[12:13]
	v_readfirstlane_b32 s98, v172
	v_lshl_add_u64 v[192:193], v[92:93], 0, s[78:79]
	s_mov_b32 m0, s98
	s_nop 0
	global_load_lds_dwordx4 v[192:193], off
	v_lshl_add_u64 v[192:193], v[92:93], 0, s[80:81]
	s_add_u32 m0, s98, 0x2000
	s_nop 0
	global_load_lds_dwordx4 v[192:193], off
	v_lshl_add_u64 v[192:193], v[92:93], 0, s[82:83]
	s_add_u32 m0, s98, 0x4000
	s_nop 0
	global_load_lds_dwordx4 v[192:193], off
	s_mov_b64 s[12:13], 0x80
	v_lshl_add_u64 v[192:193], v[190:191], 0, s[12:13]
	s_add_u32 m0, s98, 0x5000
	s_nop 0
	global_load_lds_dwordx4 v[192:193], off
	s_mov_b64 s[12:13], 0x20080
	v_lshl_add_u64 v[192:193], v[190:191], 0, s[12:13]
	s_add_u32 m0, s98, 0x7000
	s_nop 0
	global_load_lds_dwordx4 v[192:193], off
	s_mov_b64 s[12:13], 0x40080
	v_lshl_add_u64 v[192:193], v[190:191], 0, s[12:13]
	s_add_u32 m0, s98, 0x9000
	s_nop 0
	global_load_lds_dwordx4 v[192:193], off
	s_mov_b64 s[12:13], 0x60080
	v_lshl_add_u64 v[192:193], v[190:191], 0, s[12:13]
	s_add_u32 m0, s98, 0xb000
	s_nop 0
	global_load_lds_dwordx4 v[192:193], off
.Lgxi_pbb:
	s_add_u32 s99, s99, 0xd000
	s_cmp_eq_u32 s99, 0x27000
	s_cselect_b32 s99, 0, s99
	v_add_u32_e32 v168, s99, v95
	v_add_u32_e32 v169, s99, v97
	v_add_u32_e32 v196, v168, v99
	v_add_u32_e32 v200, v169, v99
	v_add_u32_e32 v168, v168, v98
	v_add_u32_e32 v169, v169, v98
	s_cmp_eq_u32 s101, 0
	s_cbranch_scc1 .Lgxi_pcw0
	s_waitcnt vmcnt(7)
	s_branch .Lgxi_pcw1

.Lgxi_pcw1:
	s_waitcnt lgkmcnt(0)
	s_barrier
	ds_read_b128 v[156:159], v168 offset:20480
	ds_read_b128 v[160:163], v168 offset:22528
	ds_read_b128 v[112:115], v169
	ds_read_b128 v[116:119], v169 offset:2048
	ds_read_b128 v[120:123], v169 offset:4096
	ds_read_b128 v[124:127], v169 offset:6144
	ds_read_b128 v[132:135], v169 offset:8192
	ds_read_b128 v[136:139], v169 offset:10240
	ds_read_b128 v[140:143], v169 offset:12288
	ds_read_b128 v[144:147], v169 offset:14336
	ds_read_b128 v[148:151], v169 offset:16384
	ds_read_b128 v[152:155], v169 offset:18432
	s_waitcnt lgkmcnt(9)
	v_mfma_f32_16x16x32_bf16 v[76:79], v[156:159], v[112:115], v[76:79]
	v_mfma_f32_16x16x32_bf16 v[72:75], v[160:163], v[112:115], v[72:75]
	ds_read_b128 v[204:207], v196 offset:20480
	s_waitcnt lgkmcnt(9)
	v_mfma_f32_16x16x32_bf16 v[68:71], v[156:159], v[116:119], v[68:71]
	v_mfma_f32_16x16x32_bf16 v[64:67], v[160:163], v[116:119], v[64:67]
	ds_read_b128 v[208:211], v196 offset:22528
	s_waitcnt lgkmcnt(9)
	v_mfma_f32_16x16x32_bf16 v[60:63], v[156:159], v[120:123], v[60:63]
	v_mfma_f32_16x16x32_bf16 v[56:59], v[160:163], v[120:123], v[56:59]
	ds_read_b128 v[164:167], v200
	s_waitcnt lgkmcnt(9)
	v_mfma_f32_16x16x32_bf16 v[52:55], v[156:159], v[124:127], v[52:55]
	v_mfma_f32_16x16x32_bf16 v[48:51], v[160:163], v[124:127], v[48:51]
	ds_read_b128 v[168:171], v200 offset:2048
	s_waitcnt lgkmcnt(9)
	v_mfma_f32_16x16x32_bf16 v[44:47], v[156:159], v[132:135], v[44:47]
	v_mfma_f32_16x16x32_bf16 v[40:43], v[160:163], v[132:135], v[40:43]
	ds_read_b128 v[172:175], v200 offset:4096
	s_waitcnt lgkmcnt(9)
	v_mfma_f32_16x16x32_bf16 v[36:39], v[156:159], v[136:139], v[36:39]
	v_mfma_f32_16x16x32_bf16 v[32:35], v[160:163], v[136:139], v[32:35]
	ds_read_b128 v[176:179], v200 offset:6144
	s_waitcnt lgkmcnt(9)
	v_mfma_f32_16x16x32_bf16 v[28:31], v[156:159], v[140:143], v[28:31]
	v_mfma_f32_16x16x32_bf16 v[24:27], v[160:163], v[140:143], v[24:27]
	ds_read_b128 v[180:183], v200 offset:8192
	s_waitcnt lgkmcnt(9)
	v_mfma_f32_16x16x32_bf16 v[20:23], v[156:159], v[144:147], v[20:23]
	v_mfma_f32_16x16x32_bf16 v[16:19], v[160:163], v[144:147], v[16:19]
	ds_read_b128 v[184:187], v200 offset:10240
	s_waitcnt lgkmcnt(9)
	v_mfma_f32_16x16x32_bf16 v[12:15], v[156:159], v[148:151], v[12:15]
	v_mfma_f32_16x16x32_bf16 v[8:11], v[160:163], v[148:151], v[8:11]
	ds_read_b128 v[188:191], v200 offset:12288
	s_waitcnt lgkmcnt(9)
	v_mfma_f32_16x16x32_bf16 v[4:7], v[156:159], v[152:155], v[4:7]
	v_mfma_f32_16x16x32_bf16 v[0:3], v[160:163], v[152:155], v[0:3]
	ds_read_b128 v[192:195], v200 offset:14336
	ds_read_b128 v[196:199], v200 offset:16384
	ds_read_b128 v[200:203], v200 offset:18432
	s_waitcnt lgkmcnt(9)
	v_mfma_f32_16x16x32_bf16 v[76:79], v[204:207], v[164:167], v[76:79]
	v_mfma_f32_16x16x32_bf16 v[72:75], v[208:211], v[164:167], v[72:75]
	s_waitcnt lgkmcnt(8)
	v_mfma_f32_16x16x32_bf16 v[68:71], v[204:207], v[168:171], v[68:71]
	v_mfma_f32_16x16x32_bf16 v[64:67], v[208:211], v[168:171], v[64:67]
	s_waitcnt lgkmcnt(7)
	v_mfma_f32_16x16x32_bf16 v[60:63], v[204:207], v[172:175], v[60:63]
	v_mfma_f32_16x16x32_bf16 v[56:59], v[208:211], v[172:175], v[56:59]
	s_waitcnt lgkmcnt(6)
	v_mfma_f32_16x16x32_bf16 v[52:55], v[204:207], v[176:179], v[52:55]
	v_mfma_f32_16x16x32_bf16 v[48:51], v[208:211], v[176:179], v[48:51]
	s_waitcnt lgkmcnt(5)
	v_mfma_f32_16x16x32_bf16 v[44:47], v[204:207], v[180:183], v[44:47]
	v_mfma_f32_16x16x32_bf16 v[40:43], v[208:211], v[180:183], v[40:43]
	s_waitcnt lgkmcnt(4)
	v_mfma_f32_16x16x32_bf16 v[36:39], v[204:207], v[184:187], v[36:39]
	v_mfma_f32_16x16x32_bf16 v[32:35], v[208:211], v[184:187], v[32:35]
	s_waitcnt lgkmcnt(3)
	v_mfma_f32_16x16x32_bf16 v[28:31], v[204:207], v[188:191], v[28:31]
	v_mfma_f32_16x16x32_bf16 v[24:27], v[208:211], v[188:191], v[24:27]
	s_waitcnt lgkmcnt(2)
	v_mfma_f32_16x16x32_bf16 v[20:23], v[204:207], v[192:195], v[20:23]
	v_mfma_f32_16x16x32_bf16 v[16:19], v[208:211], v[192:195], v[16:19]
	s_waitcnt lgkmcnt(1)
	v_mfma_f32_16x16x32_bf16 v[12:15], v[204:207], v[196:199], v[12:15]
	v_mfma_f32_16x16x32_bf16 v[8:11], v[208:211], v[196:199], v[8:11]
	s_waitcnt lgkmcnt(0)
	v_mfma_f32_16x16x32_bf16 v[4:7], v[204:207], v[200:203], v[4:7]
	v_mfma_f32_16x16x32_bf16 v[0:3], v[208:211], v[200:203], v[0:3]
	s_cmp_eq_u32 s101, 0
	s_cbranch_scc1 .Lgxi_pcb
	s_add_u32 s12, s99, 0x1a000
	s_cmp_ge_u32 s12, 0x27000
	s_cselect_b32 s13, 0x27000, 0
	s_sub_u32 s12, s12, s13
	v_add_u32_e32 v172, s12, v96
	s_mov_b64 s[12:13], 0
	v_lshl_add_u64 v[92:93], v[106:107], 0, s[12:13]
	v_lshl_add_u64 v[190:191], v[108:109], 0, s[12:13]
	v_readfirstlane_b32 s98, v172
	v_lshl_add_u64 v[192:193], v[92:93], 0, s[78:79]
	s_mov_b32 m0, s98
	s_nop 0
	global_load_lds_dwordx4 v[192:193], off
	v_lshl_add_u64 v[192:193], v[92:93], 0, s[80:81]
	s_add_u32 m0, s98, 0x2000
	s_nop 0
	global_load_lds_dwordx4 v[192:193], off
	v_lshl_add_u64 v[192:193], v[92:93], 0, s[82:83]
	s_add_u32 m0, s98, 0x4000
	s_nop 0
	global_load_lds_dwordx4 v[192:193], off
	s_mov_b64 s[12:13], 0x80
	v_lshl_add_u64 v[192:193], v[190:191], 0, s[12:13]
	s_add_u32 m0, s98, 0x5000
	s_nop 0
	global_load_lds_dwordx4 v[192:193], off
	s_mov_b64 s[12:13], 0x20080
	v_lshl_add_u64 v[192:193], v[190:191], 0, s[12:13]
	s_add_u32 m0, s98, 0x7000
	s_nop 0
	global_load_lds_dwordx4 v[192:193], off
	s_mov_b64 s[12:13], 0x40080
	v_lshl_add_u64 v[192:193], v[190:191], 0, s[12:13]
	s_add_u32 m0, s98, 0x9000
	s_nop 0
	global_load_lds_dwordx4 v[192:193], off
	s_mov_b64 s[12:13], 0x60080
	v_lshl_add_u64 v[192:193], v[190:191], 0, s[12:13]
	s_add_u32 m0, s98, 0xb000
	s_nop 0
	global_load_lds_dwordx4 v[192:193], off
.Lgxi_pcb:
	s_add_u32 s99, s99, 0xd000
	s_cmp_eq_u32 s99, 0x27000
	s_cselect_b32 s99, 0, s99
	s_branch .Lg160i_epi
.Lgxi_q:
	s_add_u32 s12, s99, 0x1a000
	s_cmp_ge_u32 s12, 0x27000
	s_cselect_b32 s13, 0x27000, 0
	s_sub_u32 s12, s12, s13
	v_add_u32_e32 v172, s12, v96
	s_add_u32 s12, s10, 0x80
	s_addc_u32 s13, s11, 0
	v_lshl_add_u64 v[92:93], v[88:89], 0, s[12:13]
	v_lshl_add_u64 v[190:191], v[90:91], 0, s[12:13]
	v_readfirstlane_b32 s98, v172
	v_add_u32_e32 v168, s99, v95
	v_add_u32_e32 v169, s99, v97
	v_add_u32_e32 v196, v168, v99
	v_add_u32_e32 v200, v169, v99
	v_add_u32_e32 v168, v168, v98
	v_add_u32_e32 v169, v169, v98
	s_waitcnt vmcnt(6) lgkmcnt(0)
	s_barrier
	v_lshl_add_u64 v[192:193], v[92:93], 0, s[78:79]
	s_mov_b32 m0, s98
	s_nop 0
	global_load_lds_dwordx4 v[192:193], off
	v_lshl_add_u64 v[192:193], v[92:93], 0, s[80:81]
	s_add_u32 m0, s98, 0x2000
	s_nop 0
	global_load_lds_dwordx4 v[192:193], off
	s_mov_b64 s[12:13], 0x80
	v_lshl_add_u64 v[192:193], v[190:191], 0, s[12:13]
	s_add_u32 m0, s98, 0x5000
	s_nop 0
	global_load_lds_dwordx4 v[192:193], off
	s_mov_b64 s[12:13], 0x20080
	v_lshl_add_u64 v[192:193], v[190:191], 0, s[12:13]
	s_add_u32 m0, s98, 0x7000
	s_nop 0
	global_load_lds_dwordx4 v[192:193], off
	s_mov_b64 s[12:13], 0x40080
	v_lshl_add_u64 v[192:193], v[190:191], 0, s[12:13]
	s_add_u32 m0, s98, 0x9000
	s_nop 0
	global_load_lds_dwordx4 v[192:193], off
	s_mov_b64 s[12:13], 0x60080
	v_lshl_add_u64 v[192:193], v[190:191], 0, s[12:13]
	s_add_u32 m0, s98, 0xb000
	s_nop 0
	global_load_lds_dwordx4 v[192:193], off
	ds_read_b128 v[156:159], v168 offset:20480
	ds_read_b128 v[160:163], v168 offset:22528
	ds_read_b128 v[112:115], v169
	ds_read_b128 v[116:119], v169 offset:2048
	ds_read_b128 v[120:123], v169 offset:4096
	ds_read_b128 v[124:127], v169 offset:6144
	ds_read_b128 v[132:135], v169 offset:8192
	ds_read_b128 v[136:139], v169 offset:10240
	ds_read_b128 v[140:143], v169 offset:12288
	ds_read_b128 v[144:147], v169 offset:14336
	ds_read_b128 v[148:151], v169 offset:16384
	ds_read_b128 v[152:155], v169 offset:18432
	s_waitcnt lgkmcnt(9)
	v_mfma_f32_16x16x32_bf16 v[76:79], v[156:159], v[112:115], v[76:79]
	v_mfma_f32_16x16x32_bf16 v[72:75], v[160:163], v[112:115], v[72:75]
	ds_read_b128 v[204:207], v196 offset:20480
	s_waitcnt lgkmcnt(9)
	v_mfma_f32_16x16x32_bf16 v[68:71], v[156:159], v[116:119], v[68:71]
	v_mfma_f32_16x16x32_bf16 v[64:67], v[160:163], v[116:119], v[64:67]
	ds_read_b128 v[208:211], v196 offset:22528
	s_waitcnt lgkmcnt(9)
	v_mfma_f32_16x16x32_bf16 v[60:63], v[156:159], v[120:123], v[60:63]
	v_mfma_f32_16x16x32_bf16 v[56:59], v[160:163], v[120:123], v[56:59]
	ds_read_b128 v[164:167], v200
	s_waitcnt lgkmcnt(9)
	v_mfma_f32_16x16x32_bf16 v[52:55], v[156:159], v[124:127], v[52:55]
	v_mfma_f32_16x16x32_bf16 v[48:51], v[160:163], v[124:127], v[48:51]
	ds_read_b128 v[168:171], v200 offset:2048
	s_waitcnt lgkmcnt(9)
	v_mfma_f32_16x16x32_bf16 v[44:47], v[156:159], v[132:135], v[44:47]
	v_mfma_f32_16x16x32_bf16 v[40:43], v[160:163], v[132:135], v[40:43]
	ds_read_b128 v[172:175], v200 offset:4096
	s_waitcnt lgkmcnt(9)
	v_mfma_f32_16x16x32_bf16 v[36:39], v[156:159], v[136:139], v[36:39]
	v_mfma_f32_16x16x32_bf16 v[32:35], v[160:163], v[136:139], v[32:35]
	ds_read_b128 v[176:179], v200 offset:6144
	s_waitcnt lgkmcnt(9)
	v_mfma_f32_16x16x32_bf16 v[28:31], v[156:159], v[140:143], v[28:31]
	v_mfma_f32_16x16x32_bf16 v[24:27], v[160:163], v[140:143], v[24:27]
	ds_read_b128 v[180:183], v200 offset:8192
	s_waitcnt lgkmcnt(9)
	v_mfma_f32_16x16x32_bf16 v[20:23], v[156:159], v[144:147], v[20:23]
	v_mfma_f32_16x16x32_bf16 v[16:19], v[160:163], v[144:147], v[16:19]
	ds_read_b128 v[184:187], v200 offset:10240
	s_waitcnt lgkmcnt(9)
	v_mfma_f32_16x16x32_bf16 v[12:15], v[156:159], v[148:151], v[12:15]
	v_mfma_f32_16x16x32_bf16 v[8:11], v[160:163], v[148:151], v[8:11]
	ds_read_b128 v[188:191], v200 offset:12288
	s_waitcnt lgkmcnt(9)
	v_mfma_f32_16x16x32_bf16 v[4:7], v[156:159], v[152:155], v[4:7]
	v_mfma_f32_16x16x32_bf16 v[0:3], v[160:163], v[152:155], v[0:3]
	ds_read_b128 v[192:195], v200 offset:14336
	ds_read_b128 v[196:199], v200 offset:16384
	ds_read_b128 v[200:203], v200 offset:18432
	s_waitcnt lgkmcnt(9)
	v_mfma_f32_16x16x32_bf16 v[76:79], v[204:207], v[164:167], v[76:79]
	v_mfma_f32_16x16x32_bf16 v[72:75], v[208:211], v[164:167], v[72:75]
	s_waitcnt lgkmcnt(8)
	v_mfma_f32_16x16x32_bf16 v[68:71], v[204:207], v[168:171], v[68:71]
	v_mfma_f32_16x16x32_bf16 v[64:67], v[208:211], v[168:171], v[64:67]
	s_waitcnt lgkmcnt(7)
	v_mfma_f32_16x16x32_bf16 v[60:63], v[204:207], v[172:175], v[60:63]
	v_mfma_f32_16x16x32_bf16 v[56:59], v[208:211], v[172:175], v[56:59]
	s_waitcnt lgkmcnt(6)
	v_mfma_f32_16x16x32_bf16 v[52:55], v[204:207], v[176:179], v[52:55]
	v_mfma_f32_16x16x32_bf16 v[48:51], v[208:211], v[176:179], v[48:51]
	s_waitcnt lgkmcnt(5)
	v_mfma_f32_16x16x32_bf16 v[44:47], v[204:207], v[180:183], v[44:47]
	v_mfma_f32_16x16x32_bf16 v[40:43], v[208:211], v[180:183], v[40:43]
	s_waitcnt lgkmcnt(4)
	v_mfma_f32_16x16x32_bf16 v[36:39], v[204:207], v[184:187], v[36:39]
	v_mfma_f32_16x16x32_bf16 v[32:35], v[208:211], v[184:187], v[32:35]
	s_waitcnt lgkmcnt(3)
	v_mfma_f32_16x16x32_bf16 v[28:31], v[204:207], v[188:191], v[28:31]
	v_mfma_f32_16x16x32_bf16 v[24:27], v[208:211], v[188:191], v[24:27]
	s_waitcnt lgkmcnt(2)
	v_mfma_f32_16x16x32_bf16 v[20:23], v[204:207], v[192:195], v[20:23]
	v_mfma_f32_16x16x32_bf16 v[16:19], v[208:211], v[192:195], v[16:19]
	s_waitcnt lgkmcnt(1)
	v_mfma_f32_16x16x32_bf16 v[12:15], v[204:207], v[196:199], v[12:15]
	v_mfma_f32_16x16x32_bf16 v[8:11], v[208:211], v[196:199], v[8:11]
	s_waitcnt lgkmcnt(0)
	v_mfma_f32_16x16x32_bf16 v[4:7], v[204:207], v[200:203], v[4:7]
	v_mfma_f32_16x16x32_bf16 v[0:3], v[208:211], v[200:203], v[0:3]
	s_add_u32 s99, s99, 0xd000
	s_cmp_eq_u32 s99, 0x27000
	s_cselect_b32 s99, 0, s99
	s_add_u32 s10, s10, 0x80
	s_addc_u32 s11, s11, 0
	s_cmpk_eq_i32 s10, 0x700
	s_cbranch_scc0 .Lgxi_q
	s_cmp_eq_u32 s101, 0
	s_cbranch_scc1 .Lgxi_qbp
	s_add_u32 s12, s99, 0x1a000
	s_cmp_ge_u32 s12, 0x27000
	s_cselect_b32 s13, 0x27000, 0
	s_sub_u32 s12, s12, s13
	v_add_u32_e32 v172, s12, v96
	s_mov_b32 s12, 0xffffff80
	s_mov_b32 s13, -1
	v_lshl_add_u64 v[92:93], v[106:107], 0, s[12:13]
	v_lshl_add_u64 v[190:191], v[108:109], 0, s[12:13]
	v_readfirstlane_b32 s98, v172
.Lgxi_qbp:
	v_add_u32_e32 v168, s99, v95
	v_add_u32_e32 v169, s99, v97
	v_add_u32_e32 v196, v168, v99
	v_add_u32_e32 v200, v169, v99
	v_add_u32_e32 v168, v168, v98
	v_add_u32_e32 v169, v169, v98
	s_waitcnt vmcnt(6) lgkmcnt(0)
	s_barrier
	s_cmp_eq_u32 s101, 0
	s_cbranch_scc1 .Lgxi_qbb
	v_lshl_add_u64 v[192:193], v[92:93], 0, s[78:79]
	s_mov_b32 m0, s98
	s_nop 0
	global_load_lds_dwordx4 v[192:193], off
	v_lshl_add_u64 v[192:193], v[92:93], 0, s[80:81]
	s_add_u32 m0, s98, 0x2000
	s_nop 0
	global_load_lds_dwordx4 v[192:193], off
	s_mov_b64 s[12:13], 0x80
	v_lshl_add_u64 v[192:193], v[190:191], 0, s[12:13]
	s_add_u32 m0, s98, 0x5000
	s_nop 0
	global_load_lds_dwordx4 v[192:193], off
	s_mov_b64 s[12:13], 0x20080
	v_lshl_add_u64 v[192:193], v[190:191], 0, s[12:13]
	s_add_u32 m0, s98, 0x7000
	s_nop 0
	global_load_lds_dwordx4 v[192:193], off
	s_mov_b64 s[12:13], 0x40080
	v_lshl_add_u64 v[192:193], v[190:191], 0, s[12:13]
	s_add_u32 m0, s98, 0x9000
	s_nop 0
	global_load_lds_dwordx4 v[192:193], off
	s_mov_b64 s[12:13], 0x60080
	v_lshl_add_u64 v[192:193], v[190:191], 0, s[12:13]
	s_add_u32 m0, s98, 0xb000
	s_nop 0
	global_load_lds_dwordx4 v[192:193], off
.Lgxi_qbb:
	ds_read_b128 v[156:159], v168 offset:20480
	ds_read_b128 v[160:163], v168 offset:22528
	ds_read_b128 v[112:115], v169
	ds_read_b128 v[116:119], v169 offset:2048
	ds_read_b128 v[120:123], v169 offset:4096
	ds_read_b128 v[124:127], v169 offset:6144
	ds_read_b128 v[132:135], v169 offset:8192
	ds_read_b128 v[136:139], v169 offset:10240
	ds_read_b128 v[140:143], v169 offset:12288
	ds_read_b128 v[144:147], v169 offset:14336
	ds_read_b128 v[148:151], v169 offset:16384
	ds_read_b128 v[152:155], v169 offset:18432
	s_waitcnt lgkmcnt(9)
	v_mfma_f32_16x16x32_bf16 v[76:79], v[156:159], v[112:115], v[76:79]
	v_mfma_f32_16x16x32_bf16 v[72:75], v[160:163], v[112:115], v[72:75]
	ds_read_b128 v[204:207], v196 offset:20480
	s_waitcnt lgkmcnt(9)
	v_mfma_f32_16x16x32_bf16 v[68:71], v[156:159], v[116:119], v[68:71]
	v_mfma_f32_16x16x32_bf16 v[64:67], v[160:163], v[116:119], v[64:67]
	ds_read_b128 v[208:211], v196 offset:22528
	s_waitcnt lgkmcnt(9)
	v_mfma_f32_16x16x32_bf16 v[60:63], v[156:159], v[120:123], v[60:63]
	v_mfma_f32_16x16x32_bf16 v[56:59], v[160:163], v[120:123], v[56:59]
	ds_read_b128 v[164:167], v200
	s_waitcnt lgkmcnt(9)
	v_mfma_f32_16x16x32_bf16 v[52:55], v[156:159], v[124:127], v[52:55]
	v_mfma_f32_16x16x32_bf16 v[48:51], v[160:163], v[124:127], v[48:51]
	ds_read_b128 v[168:171], v200 offset:2048
	s_waitcnt lgkmcnt(9)
	v_mfma_f32_16x16x32_bf16 v[44:47], v[156:159], v[132:135], v[44:47]
	v_mfma_f32_16x16x32_bf16 v[40:43], v[160:163], v[132:135], v[40:43]
	ds_read_b128 v[172:175], v200 offset:4096
	s_waitcnt lgkmcnt(9)
	v_mfma_f32_16x16x32_bf16 v[36:39], v[156:159], v[136:139], v[36:39]
	v_mfma_f32_16x16x32_bf16 v[32:35], v[160:163], v[136:139], v[32:35]
	ds_read_b128 v[176:179], v200 offset:6144
	s_waitcnt lgkmcnt(9)
	v_mfma_f32_16x16x32_bf16 v[28:31], v[156:159], v[140:143], v[28:31]
	v_mfma_f32_16x16x32_bf16 v[24:27], v[160:163], v[140:143], v[24:27]
	ds_read_b128 v[180:183], v200 offset:8192
	s_waitcnt lgkmcnt(9)
	v_mfma_f32_16x16x32_bf16 v[20:23], v[156:159], v[144:147], v[20:23]
	v_mfma_f32_16x16x32_bf16 v[16:19], v[160:163], v[144:147], v[16:19]
	ds_read_b128 v[184:187], v200 offset:10240
	s_waitcnt lgkmcnt(9)
	v_mfma_f32_16x16x32_bf16 v[12:15], v[156:159], v[148:151], v[12:15]
	v_mfma_f32_16x16x32_bf16 v[8:11], v[160:163], v[148:151], v[8:11]
	ds_read_b128 v[188:191], v200 offset:12288
	s_waitcnt lgkmcnt(9)
	v_mfma_f32_16x16x32_bf16 v[4:7], v[156:159], v[152:155], v[4:7]
	v_mfma_f32_16x16x32_bf16 v[0:3], v[160:163], v[152:155], v[0:3]
	ds_read_b128 v[192:195], v200 offset:14336
	ds_read_b128 v[196:199], v200 offset:16384
	ds_read_b128 v[200:203], v200 offset:18432
	s_waitcnt lgkmcnt(9)
	v_mfma_f32_16x16x32_bf16 v[76:79], v[204:207], v[164:167], v[76:79]
	v_mfma_f32_16x16x32_bf16 v[72:75], v[208:211], v[164:167], v[72:75]
	s_waitcnt lgkmcnt(8)
	v_mfma_f32_16x16x32_bf16 v[68:71], v[204:207], v[168:171], v[68:71]
	v_mfma_f32_16x16x32_bf16 v[64:67], v[208:211], v[168:171], v[64:67]
	s_waitcnt lgkmcnt(7)
	v_mfma_f32_16x16x32_bf16 v[60:63], v[204:207], v[172:175], v[60:63]
	v_mfma_f32_16x16x32_bf16 v[56:59], v[208:211], v[172:175], v[56:59]
	s_waitcnt lgkmcnt(6)
	v_mfma_f32_16x16x32_bf16 v[52:55], v[204:207], v[176:179], v[52:55]
	v_mfma_f32_16x16x32_bf16 v[48:51], v[208:211], v[176:179], v[48:51]
	s_waitcnt lgkmcnt(5)
	v_mfma_f32_16x16x32_bf16 v[44:47], v[204:207], v[180:183], v[44:47]
	v_mfma_f32_16x16x32_bf16 v[40:43], v[208:211], v[180:183], v[40:43]
	s_waitcnt lgkmcnt(4)
	v_mfma_f32_16x16x32_bf16 v[36:39], v[204:207], v[184:187], v[36:39]
	v_mfma_f32_16x16x32_bf16 v[32:35], v[208:211], v[184:187], v[32:35]
	s_waitcnt lgkmcnt(3)
	v_mfma_f32_16x16x32_bf16 v[28:31], v[204:207], v[188:191], v[28:31]
	v_mfma_f32_16x16x32_bf16 v[24:27], v[208:211], v[188:191], v[24:27]
	s_waitcnt lgkmcnt(2)
	v_mfma_f32_16x16x32_bf16 v[20:23], v[204:207], v[192:195], v[20:23]
	v_mfma_f32_16x16x32_bf16 v[16:19], v[208:211], v[192:195], v[16:19]
	s_waitcnt lgkmcnt(1)
	v_mfma_f32_16x16x32_bf16 v[12:15], v[204:207], v[196:199], v[12:15]
	v_mfma_f32_16x16x32_bf16 v[8:11], v[208:211], v[196:199], v[8:11]
	s_waitcnt lgkmcnt(0)
	v_mfma_f32_16x16x32_bf16 v[4:7], v[204:207], v[200:203], v[4:7]
	v_mfma_f32_16x16x32_bf16 v[0:3], v[208:211], v[200:203], v[0:3]
	s_add_u32 s99, s99, 0xd000
	s_cmp_eq_u32 s99, 0x27000
	s_cselect_b32 s99, 0, s99
	s_cmp_eq_u32 s101, 0
	s_cbranch_scc1 .Lgxi_qcp
	s_add_u32 s12, s99, 0x1a000
	s_cmp_ge_u32 s12, 0x27000
	s_cselect_b32 s13, 0x27000, 0
	s_sub_u32 s12, s12, s13
	v_add_u32_e32 v172, s12, v96
	s_mov_b64 s[12:13], 0
	v_lshl_add_u64 v[92:93], v[106:107], 0, s[12:13]
	v_lshl_add_u64 v[190:191], v[108:109], 0, s[12:13]
	v_readfirstlane_b32 s98, v172
.Lgxi_qcp:
	v_add_u32_e32 v168, s99, v95
	v_add_u32_e32 v169, s99, v97
	v_add_u32_e32 v196, v168, v99
	v_add_u32_e32 v200, v169, v99
	v_add_u32_e32 v168, v168, v98
	v_add_u32_e32 v169, v169, v98
	s_cmp_eq_u32 s101, 0
	s_cbranch_scc1 .Lgxi_qcw0
	s_waitcnt vmcnt(6)
	s_branch .Lgxi_qcw1

.Lgxi_qcw1:
	s_waitcnt lgkmcnt(0)
	s_barrier
	s_cmp_eq_u32 s101, 0
	s_cbranch_scc1 .Lgxi_qcb
	v_lshl_add_u64 v[192:193], v[92:93], 0, s[78:79]
	s_mov_b32 m0, s98
	s_nop 0
	global_load_lds_dwordx4 v[192:193], off
	v_lshl_add_u64 v[192:193], v[92:93], 0, s[80:81]
	s_add_u32 m0, s98, 0x2000
	s_nop 0
	global_load_lds_dwordx4 v[192:193], off
	s_mov_b64 s[12:13], 0x80
	v_lshl_add_u64 v[192:193], v[190:191], 0, s[12:13]
	s_add_u32 m0, s98, 0x5000
	s_nop 0
	global_load_lds_dwordx4 v[192:193], off
	s_mov_b64 s[12:13], 0x20080
	v_lshl_add_u64 v[192:193], v[190:191], 0, s[12:13]
	s_add_u32 m0, s98, 0x7000
	s_nop 0
	global_load_lds_dwordx4 v[192:193], off
	s_mov_b64 s[12:13], 0x40080
	v_lshl_add_u64 v[192:193], v[190:191], 0, s[12:13]
	s_add_u32 m0, s98, 0x9000
	s_nop 0
	global_load_lds_dwordx4 v[192:193], off
	s_mov_b64 s[12:13], 0x60080
	v_lshl_add_u64 v[192:193], v[190:191], 0, s[12:13]
	s_add_u32 m0, s98, 0xb000
	s_nop 0
	global_load_lds_dwordx4 v[192:193], off
.Lgxi_qcb:
	ds_read_b128 v[156:159], v168 offset:20480
	ds_read_b128 v[160:163], v168 offset:22528
	ds_read_b128 v[112:115], v169
	ds_read_b128 v[116:119], v169 offset:2048
	ds_read_b128 v[120:123], v169 offset:4096
	ds_read_b128 v[124:127], v169 offset:6144
	ds_read_b128 v[132:135], v169 offset:8192
	ds_read_b128 v[136:139], v169 offset:10240
	ds_read_b128 v[140:143], v169 offset:12288
	ds_read_b128 v[144:147], v169 offset:14336
	ds_read_b128 v[148:151], v169 offset:16384
	ds_read_b128 v[152:155], v169 offset:18432
	s_waitcnt lgkmcnt(9)
	v_mfma_f32_16x16x32_bf16 v[76:79], v[156:159], v[112:115], v[76:79]
	v_mfma_f32_16x16x32_bf16 v[72:75], v[160:163], v[112:115], v[72:75]
	ds_read_b128 v[204:207], v196 offset:20480
	s_waitcnt lgkmcnt(9)
	v_mfma_f32_16x16x32_bf16 v[68:71], v[156:159], v[116:119], v[68:71]
	v_mfma_f32_16x16x32_bf16 v[64:67], v[160:163], v[116:119], v[64:67]
	ds_read_b128 v[208:211], v196 offset:22528
	s_waitcnt lgkmcnt(9)
	v_mfma_f32_16x16x32_bf16 v[60:63], v[156:159], v[120:123], v[60:63]
	v_mfma_f32_16x16x32_bf16 v[56:59], v[160:163], v[120:123], v[56:59]
	ds_read_b128 v[164:167], v200
	s_waitcnt lgkmcnt(9)
	v_mfma_f32_16x16x32_bf16 v[52:55], v[156:159], v[124:127], v[52:55]
	v_mfma_f32_16x16x32_bf16 v[48:51], v[160:163], v[124:127], v[48:51]
	ds_read_b128 v[168:171], v200 offset:2048
	s_waitcnt lgkmcnt(9)
	v_mfma_f32_16x16x32_bf16 v[44:47], v[156:159], v[132:135], v[44:47]
	v_mfma_f32_16x16x32_bf16 v[40:43], v[160:163], v[132:135], v[40:43]
	ds_read_b128 v[172:175], v200 offset:4096
	s_waitcnt lgkmcnt(9)
	v_mfma_f32_16x16x32_bf16 v[36:39], v[156:159], v[136:139], v[36:39]
	v_mfma_f32_16x16x32_bf16 v[32:35], v[160:163], v[136:139], v[32:35]
	ds_read_b128 v[176:179], v200 offset:6144
	s_waitcnt lgkmcnt(9)
	v_mfma_f32_16x16x32_bf16 v[28:31], v[156:159], v[140:143], v[28:31]
	v_mfma_f32_16x16x32_bf16 v[24:27], v[160:163], v[140:143], v[24:27]
	ds_read_b128 v[180:183], v200 offset:8192
	s_waitcnt lgkmcnt(9)
	v_mfma_f32_16x16x32_bf16 v[20:23], v[156:159], v[144:147], v[20:23]
	v_mfma_f32_16x16x32_bf16 v[16:19], v[160:163], v[144:147], v[16:19]
	ds_read_b128 v[184:187], v200 offset:10240
	s_waitcnt lgkmcnt(9)
	v_mfma_f32_16x16x32_bf16 v[12:15], v[156:159], v[148:151], v[12:15]
	v_mfma_f32_16x16x32_bf16 v[8:11], v[160:163], v[148:151], v[8:11]
	ds_read_b128 v[188:191], v200 offset:12288
	s_waitcnt lgkmcnt(9)
	v_mfma_f32_16x16x32_bf16 v[4:7], v[156:159], v[152:155], v[4:7]
	v_mfma_f32_16x16x32_bf16 v[0:3], v[160:163], v[152:155], v[0:3]
	ds_read_b128 v[192:195], v200 offset:14336
	ds_read_b128 v[196:199], v200 offset:16384
	ds_read_b128 v[200:203], v200 offset:18432
	s_waitcnt lgkmcnt(9)
	v_mfma_f32_16x16x32_bf16 v[76:79], v[204:207], v[164:167], v[76:79]
	v_mfma_f32_16x16x32_bf16 v[72:75], v[208:211], v[164:167], v[72:75]
	s_waitcnt lgkmcnt(8)
	v_mfma_f32_16x16x32_bf16 v[68:71], v[204:207], v[168:171], v[68:71]
	v_mfma_f32_16x16x32_bf16 v[64:67], v[208:211], v[168:171], v[64:67]
	s_waitcnt lgkmcnt(7)
	v_mfma_f32_16x16x32_bf16 v[60:63], v[204:207], v[172:175], v[60:63]
	v_mfma_f32_16x16x32_bf16 v[56:59], v[208:211], v[172:175], v[56:59]
	s_waitcnt lgkmcnt(6)
	v_mfma_f32_16x16x32_bf16 v[52:55], v[204:207], v[176:179], v[52:55]
	v_mfma_f32_16x16x32_bf16 v[48:51], v[208:211], v[176:179], v[48:51]
	s_waitcnt lgkmcnt(5)
	v_mfma_f32_16x16x32_bf16 v[44:47], v[204:207], v[180:183], v[44:47]
	v_mfma_f32_16x16x32_bf16 v[40:43], v[208:211], v[180:183], v[40:43]
	s_waitcnt lgkmcnt(4)
	v_mfma_f32_16x16x32_bf16 v[36:39], v[204:207], v[184:187], v[36:39]
	v_mfma_f32_16x16x32_bf16 v[32:35], v[208:211], v[184:187], v[32:35]
	s_waitcnt lgkmcnt(3)
	v_mfma_f32_16x16x32_bf16 v[28:31], v[204:207], v[188:191], v[28:31]
	v_mfma_f32_16x16x32_bf16 v[24:27], v[208:211], v[188:191], v[24:27]
	s_waitcnt lgkmcnt(2)
	v_mfma_f32_16x16x32_bf16 v[20:23], v[204:207], v[192:195], v[20:23]
	v_mfma_f32_16x16x32_bf16 v[16:19], v[208:211], v[192:195], v[16:19]
	s_waitcnt lgkmcnt(1)
	v_mfma_f32_16x16x32_bf16 v[12:15], v[204:207], v[196:199], v[12:15]
	v_mfma_f32_16x16x32_bf16 v[8:11], v[208:211], v[196:199], v[8:11]
	s_waitcnt lgkmcnt(0)
	v_mfma_f32_16x16x32_bf16 v[4:7], v[204:207], v[200:203], v[4:7]
	v_mfma_f32_16x16x32_bf16 v[0:3], v[208:211], v[200:203], v[0:3]
	s_add_u32 s99, s99, 0xd000
	s_cmp_eq_u32 s99, 0x27000
	s_cselect_b32 s99, 0, s99
	s_branch .Lg160i_epi

.LBB0_677:
	s_or_b64 exec, exec, s[36:37]
	v_readlane_b32 s4, v254, 0
	v_readlane_b32 s5, v254, 1
	s_waitcnt lgkmcnt(0)
	s_barrier
	s_load_dwordx2 s[8:9], s[4:5], 0xe0
	v_mov_b32_e32 v6, v222
	s_waitcnt lgkmcnt(0)
	s_add_u32 s6, s8, 0x15831000
	v_lshrrev_b32_e32 v7, 4, v6
	v_ashrrev_i32_e32 v0, 3, v6
	v_ashrrev_i32_e32 v4, 1, v6
	v_and_b32_e32 v96, 15, v6
	s_addc_u32 s7, s9, 0
	v_readlane_b32 s4, v254, 19
	v_xor_b32_e32 v8, v7, v6
	v_ashrrev_i32_e32 v1, 31, v0
	v_and_b32_e32 v10, 0xffffffe0, v4
	v_readlane_b32 s5, v254, 20
	s_add_u32 s10, s8, s4
	v_lshlrev_b64 v[0:1], 11, v[0:1]
	v_or_b32_e32 v4, v10, v96
	v_lshlrev_b32_e32 v8, 4, v8
	s_addc_u32 s11, s9, s5
	v_lshlrev_b32_e32 v97, 7, v4
	v_lshl_add_u64 v[4:5], s[8:9], 0, v[0:1]
	v_and_b32_e32 v128, 0x70, v8
	v_lshl_add_u64 v[2:3], s[10:11], 0, v[0:1]
	v_lshl_add_u64 v[4:5], v[4:5], 0, v[128:129]
	s_mov_b64 s[4:5], 0x2c31000
	v_lshl_add_u64 v[80:81], v[4:5], 0, s[4:5]
	v_lshl_add_u64 v[2:3], v[2:3], 0, v[128:129]
	s_mov_b64 s[4:5], 0x360000
	v_bfe_u32 v9, v6, 1, 3
	v_lshl_add_u64 v[82:83], v[2:3], 0, s[4:5]
	v_bfe_u32 v2, v6, 4, 2
	v_bitop3_b32 v2, v2, v9, 4 bitop3:0x36
	v_lshlrev_b32_e32 v99, 7, v96
	v_bitop3_b32 v3, v7, v9, 3 bitop3:0x6c
	v_lshlrev_b32_e32 v101, 4, v2
	v_lshrrev_b32_e32 v2, 2, v6
	v_lshlrev_b32_e32 v100, 4, v3
	v_and_or_b32 v84, v2, 12, v10
	v_add_u32_e32 v2, 0, v99
	v_add_u32_e32 v103, v2, v100
	v_add_u32_e32 v105, v2, v101
	v_bitop3_b32 v2, v7, 7, v6 bitop3:0x48
	s_movk_i32 s4, 0x100
	v_add_u32_e32 v3, 0, v97
	v_lshl_or_b32 v0, v2, 4, v0
	v_cmp_gt_i32_e64 s[4:5], s4, v6
	v_lshl_add_u32 v98, v6, 4, 0
	v_ashrrev_i32_e32 v85, 31, v10
	v_add_u32_e32 v102, 0xd000, v3
	v_add_u32_e32 v104, 0xd000, v103
	v_add_u32_e32 v106, 0xd000, v105
	v_lshl_add_u64 v[86:87], s[8:9], 0, v[0:1]
	v_lshl_add_u64 v[88:89], s[10:11], 0, v[0:1]
	s_mov_b32 s99, 0
	s_mov_b32 s100, 0
	s_mov_b32 s14, 0
	s_branch .LBB0_680
.Lg160o_epi:
	s_mulk_i32 s15, 0xa0
	v_or_b32_e32 v90, s15, v96
	s_mov_b32 s9, s45
	v_ashrrev_i32_e32 v91, 31, v90
	v_lshl_add_u64 v[92:93], v[84:85], 0, s[8:9]
	v_lshlrev_b64 v[94:95], 10, v[90:91]
	v_lshl_add_u64 v[94:95], v[94:95], 0, v[92:93]
	s_barrier
	v_cvt_pk_bf16_f32 v72, v72, v73
	v_lshl_add_u64 v[94:95], v[94:95], 1, s[6:7]
	v_cvt_pk_bf16_f32 v73, v74, v75
	flat_store_dwordx2 v[94:95], v[72:73] offset:32
	v_or_b32_e32 v72, 16, v90
	v_ashrrev_i32_e32 v73, 31, v72
	v_cvt_pk_bf16_f32 v76, v76, v77
	v_cvt_pk_bf16_f32 v77, v78, v79
	v_lshlrev_b64 v[72:73], 10, v[72:73]
	flat_store_dwordx2 v[94:95], v[76:77]
	v_lshl_add_u64 v[72:73], v[72:73], 0, v[92:93]
	v_cvt_pk_bf16_f32 v64, v64, v65
	v_lshl_add_u64 v[72:73], v[72:73], 1, s[6:7]
	v_cvt_pk_bf16_f32 v65, v66, v67
	flat_store_dwordx2 v[72:73], v[64:65] offset:32
	v_add_u32_e32 v64, 32, v90
	v_ashrrev_i32_e32 v65, 31, v64
	v_cvt_pk_bf16_f32 v68, v68, v69
	v_cvt_pk_bf16_f32 v69, v70, v71
	v_lshlrev_b64 v[64:65], 10, v[64:65]
	flat_store_dwordx2 v[72:73], v[68:69]
	v_lshl_add_u64 v[64:65], v[64:65], 0, v[92:93]
	v_cvt_pk_bf16_f32 v56, v56, v57
	v_lshl_add_u64 v[64:65], v[64:65], 1, s[6:7]
	v_cvt_pk_bf16_f32 v57, v58, v59
	flat_store_dwordx2 v[64:65], v[56:57] offset:32
	v_add_u32_e32 v56, 48, v90
	v_ashrrev_i32_e32 v57, 31, v56
	v_cvt_pk_bf16_f32 v60, v60, v61
	v_cvt_pk_bf16_f32 v61, v62, v63
	v_lshlrev_b64 v[56:57], 10, v[56:57]
	flat_store_dwordx2 v[64:65], v[60:61]
	v_lshl_add_u64 v[56:57], v[56:57], 0, v[92:93]
	v_cvt_pk_bf16_f32 v48, v48, v49
	v_lshl_add_u64 v[56:57], v[56:57], 1, s[6:7]
	v_cvt_pk_bf16_f32 v49, v50, v51
	flat_store_dwordx2 v[56:57], v[48:49] offset:32
	v_add_u32_e32 v48, 64, v90
	v_ashrrev_i32_e32 v49, 31, v48
	v_cvt_pk_bf16_f32 v52, v52, v53
	v_cvt_pk_bf16_f32 v53, v54, v55
	v_lshlrev_b64 v[48:49], 10, v[48:49]
	flat_store_dwordx2 v[56:57], v[52:53]
	v_lshl_add_u64 v[48:49], v[48:49], 0, v[92:93]
	v_cvt_pk_bf16_f32 v40, v40, v41
	v_lshl_add_u64 v[48:49], v[48:49], 1, s[6:7]
	v_cvt_pk_bf16_f32 v41, v42, v43
	flat_store_dwordx2 v[48:49], v[40:41] offset:32
	v_add_u32_e32 v40, 0x50, v90
	v_ashrrev_i32_e32 v41, 31, v40
	v_cvt_pk_bf16_f32 v44, v44, v45
	v_cvt_pk_bf16_f32 v45, v46, v47
	v_lshlrev_b64 v[40:41], 10, v[40:41]
	flat_store_dwordx2 v[48:49], v[44:45]
	v_lshl_add_u64 v[40:41], v[40:41], 0, v[92:93]
	v_cvt_pk_bf16_f32 v32, v32, v33
	v_lshl_add_u64 v[40:41], v[40:41], 1, s[6:7]
	v_cvt_pk_bf16_f32 v33, v34, v35
	flat_store_dwordx2 v[40:41], v[32:33] offset:32
	v_add_u32_e32 v32, 0x60, v90
	v_ashrrev_i32_e32 v33, 31, v32
	v_cvt_pk_bf16_f32 v36, v36, v37
	v_cvt_pk_bf16_f32 v37, v38, v39
	v_lshlrev_b64 v[32:33], 10, v[32:33]
	flat_store_dwordx2 v[40:41], v[36:37]
	v_lshl_add_u64 v[32:33], v[32:33], 0, v[92:93]
	v_cvt_pk_bf16_f32 v24, v24, v25
	v_lshl_add_u64 v[32:33], v[32:33], 1, s[6:7]
	v_cvt_pk_bf16_f32 v25, v26, v27
	flat_store_dwordx2 v[32:33], v[24:25] offset:32
	v_add_u32_e32 v24, 0x70, v90
	v_ashrrev_i32_e32 v25, 31, v24
	v_cvt_pk_bf16_f32 v28, v28, v29
	v_cvt_pk_bf16_f32 v29, v30, v31
	v_lshlrev_b64 v[24:25], 10, v[24:25]
	flat_store_dwordx2 v[32:33], v[28:29]
	v_lshl_add_u64 v[24:25], v[24:25], 0, v[92:93]
	v_cvt_pk_bf16_f32 v16, v16, v17
	v_lshl_add_u64 v[24:25], v[24:25], 1, s[6:7]
	v_cvt_pk_bf16_f32 v17, v18, v19
	flat_store_dwordx2 v[24:25], v[16:17] offset:32
	v_add_u32_e32 v16, 0x80, v90
	v_ashrrev_i32_e32 v17, 31, v16
	v_cvt_pk_bf16_f32 v20, v20, v21
	v_cvt_pk_bf16_f32 v21, v22, v23
	v_lshlrev_b64 v[16:17], 10, v[16:17]
	flat_store_dwordx2 v[24:25], v[20:21]
	v_lshl_add_u64 v[16:17], v[16:17], 0, v[92:93]
	v_cvt_pk_bf16_f32 v8, v8, v9
	v_lshl_add_u64 v[16:17], v[16:17], 1, s[6:7]
	v_cvt_pk_bf16_f32 v9, v10, v11
	flat_store_dwordx2 v[16:17], v[8:9] offset:32
	v_add_u32_e32 v8, 0x90, v90
	v_ashrrev_i32_e32 v9, 31, v8
	v_cvt_pk_bf16_f32 v12, v12, v13
	v_cvt_pk_bf16_f32 v13, v14, v15
	v_lshlrev_b64 v[8:9], 10, v[8:9]
	flat_store_dwordx2 v[16:17], v[12:13]
	v_lshl_add_u64 v[8:9], v[8:9], 0, v[92:93]
	v_cvt_pk_bf16_f32 v4, v4, v5
	v_lshl_add_u64 v[8:9], v[8:9], 1, s[6:7]
	v_cvt_pk_bf16_f32 v5, v6, v7
	v_cvt_pk_bf16_f32 v0, v0, v1
	v_cvt_pk_bf16_f32 v1, v2, v3
	s_add_i32 s14, s14, 1
	s_mov_b32 s100, s101
	s_mov_b64 s[8:9], 0
	flat_store_dwordx2 v[8:9], v[4:5]
	flat_store_dwordx2 v[8:9], v[0:1] offset:32

.LBB0_685:
	s_ashr_i32 s8, s10, 2
	s_and_b32 s11, s8, -8
	s_and_b32 s12, s10, 7
	s_or_b32 s15, s11, s12
	s_lshl_b32 s9, s10, 16
	s_and_b32 s44, s9, 0x180000
	s_lshl_b32 s8, s10, 5
	s_and_b32 s8, s8, 0x300
	v_mad_i64_i32 v[90:91], s[16:17], s15, v224, v[86:87]
	v_lshl_add_u64 v[92:93], v[88:89], 0, s[44:45]
	s_add_i32 s11, s14, 1
	s_lshl_b32 s12, s11, 8
	s_add_i32 s12, s12, s89
	s_mul_i32 s13, s11, s60
	s_add_i32 s13, s13, s2
	s_cmp_eq_u64 s[64:65], 0
	s_cselect_b32 s12, s12, s13
	s_cmpk_le_i32 s12, 0x3ff
	s_cselect_b32 s101, 1, 0
	s_ashr_i32 s13, s12, 2
	s_and_b32 s13, s13, -8
	s_and_b32 s11, s12, 7
	s_or_b32 s13, s13, s11
	v_mad_i64_i32 v[102:103], s[16:17], s13, v224, v[86:87]
	s_lshl_b32 s11, s12, 16
	s_and_b32 s44, s11, 0x180000
	v_lshl_add_u64 v[104:105], v[88:89], 0, s[44:45]
	s_mov_b64 s[10:11], 0
	v_mov_b32_e32 v0, 0
	v_mov_b32_e32 v1, v0
	v_mov_b32_e32 v2, v0
	v_mov_b32_e32 v3, v0
	v_mov_b32_e32 v4, v0
	v_mov_b32_e32 v5, v0
	v_mov_b32_e32 v6, v0
	v_mov_b32_e32 v7, v0
	v_mov_b32_e32 v8, v0
	v_mov_b32_e32 v9, v0
	v_mov_b32_e32 v10, v0
	v_mov_b32_e32 v11, v0
	v_mov_b32_e32 v12, v0
	v_mov_b32_e32 v13, v0
	v_mov_b32_e32 v14, v0
	v_mov_b32_e32 v15, v0
	v_mov_b32_e32 v16, v0
	v_mov_b32_e32 v17, v0
	v_mov_b32_e32 v18, v0
	v_mov_b32_e32 v19, v0
	v_mov_b32_e32 v20, v0
	v_mov_b32_e32 v21, v0
	v_mov_b32_e32 v22, v0
	v_mov_b32_e32 v23, v0
	v_mov_b32_e32 v24, v0
	v_mov_b32_e32 v25, v0
	v_mov_b32_e32 v26, v0
	v_mov_b32_e32 v27, v0
	v_mov_b32_e32 v28, v0
	v_mov_b32_e32 v29, v0
	v_mov_b32_e32 v30, v0
	v_mov_b32_e32 v31, v0
	v_mov_b32_e32 v32, v0
	v_mov_b32_e32 v33, v0
	v_mov_b32_e32 v34, v0
	v_mov_b32_e32 v35, v0
	v_mov_b32_e32 v36, v0
	v_mov_b32_e32 v37, v0
	v_mov_b32_e32 v38, v0
	v_mov_b32_e32 v39, v0
	v_mov_b32_e32 v40, v0
	v_mov_b32_e32 v41, v0
	v_mov_b32_e32 v42, v0
	v_mov_b32_e32 v43, v0
	v_mov_b32_e32 v44, v0
	v_mov_b32_e32 v45, v0
	v_mov_b32_e32 v46, v0
	v_mov_b32_e32 v47, v0
	v_mov_b32_e32 v48, v0
	v_mov_b32_e32 v49, v0
	v_mov_b32_e32 v50, v0
	v_mov_b32_e32 v51, v0
	v_mov_b32_e32 v52, v0
	v_mov_b32_e32 v53, v0
	v_mov_b32_e32 v54, v0
	v_mov_b32_e32 v55, v0
	v_mov_b32_e32 v56, v0
	v_mov_b32_e32 v57, v0
	v_mov_b32_e32 v58, v0
	v_mov_b32_e32 v59, v0
	v_mov_b32_e32 v60, v0
	v_mov_b32_e32 v61, v0
	v_mov_b32_e32 v62, v0
	v_mov_b32_e32 v63, v0
	v_mov_b32_e32 v64, v0
	v_mov_b32_e32 v65, v0
	v_mov_b32_e32 v66, v0
	v_mov_b32_e32 v67, v0
	v_mov_b32_e32 v68, v0
	v_mov_b32_e32 v69, v0
	v_mov_b32_e32 v70, v0
	v_mov_b32_e32 v71, v0
	v_mov_b32_e32 v72, v0
	v_mov_b32_e32 v73, v0
	v_mov_b32_e32 v74, v0
	v_mov_b32_e32 v75, v0
	v_mov_b32_e32 v76, v0
	v_mov_b32_e32 v77, v0
	v_mov_b32_e32 v78, v0
	v_mov_b32_e32 v79, v0
	s_cmp_eq_u32 s100, 0
	s_cbranch_scc0 .Lgxo_go
	s_add_u32 s12, s99, 0x0
	s_cmp_ge_u32 s12, 0x27000
	s_cselect_b32 s13, 0x27000, 0
	s_sub_u32 s12, s12, s13
	v_add_u32_e32 v168, s12, v98
	s_mov_b32 s12, 0xffffff80
	s_mov_b32 s13, -1
	v_lshl_add_u64 v[94:95], v[90:91], 0, s[12:13]
	v_lshl_add_u64 v[186:187], v[92:93], 0, s[12:13]
	v_readfirstlane_b32 s98, v168
	v_lshl_add_u64 v[188:189], v[94:95], 0, s[78:79]
	s_mov_b32 m0, s98
	s_nop 0
	global_load_lds_dwordx4 v[188:189], off
	v_lshl_add_u64 v[188:189], v[94:95], 0, s[80:81]
	s_add_u32 m0, s98, 0x2000
	s_nop 0
	global_load_lds_dwordx4 v[188:189], off
	s_cmp_eq_u64 s[4:5], 0
	s_cbranch_scc1 .Lgxo_ps0
	v_lshl_add_u64 v[188:189], v[94:95], 0, s[82:83]
	s_add_u32 m0, s98, 0x4000
	s_nop 0
	global_load_lds_dwordx4 v[188:189], off
.Lgxo_ps0:
	s_mov_b64 s[12:13], 0x360080
	v_lshl_add_u64 v[188:189], v[186:187], 0, s[12:13]
	s_add_u32 m0, s98, 0x5000
	s_nop 0
	global_load_lds_dwordx4 v[188:189], off
	s_mov_b64 s[12:13], 0x380080
	v_lshl_add_u64 v[188:189], v[186:187], 0, s[12:13]
	s_add_u32 m0, s98, 0x7000
	s_nop 0
	global_load_lds_dwordx4 v[188:189], off
	s_mov_b64 s[12:13], 0x3a0080
	v_lshl_add_u64 v[188:189], v[186:187], 0, s[12:13]
	s_add_u32 m0, s98, 0x9000
	s_nop 0
	global_load_lds_dwordx4 v[188:189], off
	s_mov_b64 s[12:13], 0x3c0080
	v_lshl_add_u64 v[188:189], v[186:187], 0, s[12:13]
	s_add_u32 m0, s98, 0xb000
	s_nop 0
	global_load_lds_dwordx4 v[188:189], off
	s_add_u32 s12, s99, 0xd000
	s_cmp_ge_u32 s12, 0x27000
	s_cselect_b32 s13, 0x27000, 0
	s_sub_u32 s12, s12, s13
	v_add_u32_e32 v168, s12, v98
	s_mov_b64 s[12:13], 0
	v_lshl_add_u64 v[94:95], v[90:91], 0, s[12:13]
	v_lshl_add_u64 v[186:187], v[92:93], 0, s[12:13]
	v_readfirstlane_b32 s98, v168
	v_lshl_add_u64 v[188:189], v[94:95], 0, s[78:79]
	s_mov_b32 m0, s98
	s_nop 0
	global_load_lds_dwordx4 v[188:189], off
	v_lshl_add_u64 v[188:189], v[94:95], 0, s[80:81]
	s_add_u32 m0, s98, 0x2000
	s_nop 0
	global_load_lds_dwordx4 v[188:189], off
	s_cmp_eq_u64 s[4:5], 0
	s_cbranch_scc1 .Lgxo_ps1
	v_lshl_add_u64 v[188:189], v[94:95], 0, s[82:83]
	s_add_u32 m0, s98, 0x4000
	s_nop 0
	global_load_lds_dwordx4 v[188:189], off
.Lgxo_ps1:
	s_mov_b64 s[12:13], 0x360080
	v_lshl_add_u64 v[188:189], v[186:187], 0, s[12:13]
	s_add_u32 m0, s98, 0x5000
	s_nop 0
	global_load_lds_dwordx4 v[188:189], off
	s_mov_b64 s[12:13], 0x380080
	v_lshl_add_u64 v[188:189], v[186:187], 0, s[12:13]
	s_add_u32 m0, s98, 0x7000
	s_nop 0
	global_load_lds_dwordx4 v[188:189], off
	s_mov_b64 s[12:13], 0x3a0080
	v_lshl_add_u64 v[188:189], v[186:187], 0, s[12:13]
	s_add_u32 m0, s98, 0x9000
	s_nop 0
	global_load_lds_dwordx4 v[188:189], off
	s_mov_b64 s[12:13], 0x3c0080
	v_lshl_add_u64 v[188:189], v[186:187], 0, s[12:13]
	s_add_u32 m0, s98, 0xb000
	s_nop 0
	global_load_lds_dwordx4 v[188:189], off

.Lgxo_p:
	v_add_u32_e32 v164, s99, v97
	v_add_u32_e32 v165, s99, v99
	v_add_u32_e32 v192, v164, v101
	v_add_u32_e32 v196, v165, v101
	v_add_u32_e32 v164, v164, v100
	v_add_u32_e32 v165, v165, v100
	s_waitcnt vmcnt(7) lgkmcnt(0)
	s_barrier
	ds_read_b128 v[152:155], v164 offset:20480
	ds_read_b128 v[156:159], v164 offset:22528
	ds_read_b128 v[108:111], v165
	ds_read_b128 v[112:115], v165 offset:2048
	ds_read_b128 v[116:119], v165 offset:4096
	ds_read_b128 v[120:123], v165 offset:6144
	ds_read_b128 v[124:127], v165 offset:8192
	ds_read_b128 v[132:135], v165 offset:10240
	ds_read_b128 v[136:139], v165 offset:12288
	ds_read_b128 v[140:143], v165 offset:14336
	ds_read_b128 v[144:147], v165 offset:16384
	ds_read_b128 v[148:151], v165 offset:18432
	s_waitcnt lgkmcnt(9)
	v_mfma_f32_16x16x32_bf16 v[76:79], v[152:155], v[108:111], v[76:79]
	v_mfma_f32_16x16x32_bf16 v[72:75], v[156:159], v[108:111], v[72:75]
	ds_read_b128 v[200:203], v192 offset:20480
	s_waitcnt lgkmcnt(9)
	v_mfma_f32_16x16x32_bf16 v[68:71], v[152:155], v[112:115], v[68:71]
	v_mfma_f32_16x16x32_bf16 v[64:67], v[156:159], v[112:115], v[64:67]
	ds_read_b128 v[204:207], v192 offset:22528
	s_waitcnt lgkmcnt(9)
	v_mfma_f32_16x16x32_bf16 v[60:63], v[152:155], v[116:119], v[60:63]
	v_mfma_f32_16x16x32_bf16 v[56:59], v[156:159], v[116:119], v[56:59]
	ds_read_b128 v[160:163], v196
	s_waitcnt lgkmcnt(9)
	v_mfma_f32_16x16x32_bf16 v[52:55], v[152:155], v[120:123], v[52:55]
	v_mfma_f32_16x16x32_bf16 v[48:51], v[156:159], v[120:123], v[48:51]
	ds_read_b128 v[164:167], v196 offset:2048
	s_waitcnt lgkmcnt(9)
	v_mfma_f32_16x16x32_bf16 v[44:47], v[152:155], v[124:127], v[44:47]
	v_mfma_f32_16x16x32_bf16 v[40:43], v[156:159], v[124:127], v[40:43]
	ds_read_b128 v[168:171], v196 offset:4096
	s_waitcnt lgkmcnt(9)
	v_mfma_f32_16x16x32_bf16 v[36:39], v[152:155], v[132:135], v[36:39]
	v_mfma_f32_16x16x32_bf16 v[32:35], v[156:159], v[132:135], v[32:35]
	ds_read_b128 v[172:175], v196 offset:6144
	s_waitcnt lgkmcnt(9)
	v_mfma_f32_16x16x32_bf16 v[28:31], v[152:155], v[136:139], v[28:31]
	v_mfma_f32_16x16x32_bf16 v[24:27], v[156:159], v[136:139], v[24:27]
	ds_read_b128 v[176:179], v196 offset:8192
	s_waitcnt lgkmcnt(9)
	v_mfma_f32_16x16x32_bf16 v[20:23], v[152:155], v[140:143], v[20:23]
	v_mfma_f32_16x16x32_bf16 v[16:19], v[156:159], v[140:143], v[16:19]
	ds_read_b128 v[180:183], v196 offset:10240
	s_waitcnt lgkmcnt(9)
	v_mfma_f32_16x16x32_bf16 v[12:15], v[152:155], v[144:147], v[12:15]
	v_mfma_f32_16x16x32_bf16 v[8:11], v[156:159], v[144:147], v[8:11]
	ds_read_b128 v[184:187], v196 offset:12288
	s_waitcnt lgkmcnt(9)
	v_mfma_f32_16x16x32_bf16 v[4:7], v[152:155], v[148:151], v[4:7]
	v_mfma_f32_16x16x32_bf16 v[0:3], v[156:159], v[148:151], v[0:3]
	ds_read_b128 v[188:191], v196 offset:14336
	ds_read_b128 v[192:195], v196 offset:16384
	ds_read_b128 v[196:199], v196 offset:18432
	s_waitcnt lgkmcnt(9)
	v_mfma_f32_16x16x32_bf16 v[76:79], v[200:203], v[160:163], v[76:79]
	v_mfma_f32_16x16x32_bf16 v[72:75], v[204:207], v[160:163], v[72:75]
	s_waitcnt lgkmcnt(8)
	v_mfma_f32_16x16x32_bf16 v[68:71], v[200:203], v[164:167], v[68:71]
	v_mfma_f32_16x16x32_bf16 v[64:67], v[204:207], v[164:167], v[64:67]
	s_waitcnt lgkmcnt(7)
	v_mfma_f32_16x16x32_bf16 v[60:63], v[200:203], v[168:171], v[60:63]
	v_mfma_f32_16x16x32_bf16 v[56:59], v[204:207], v[168:171], v[56:59]
	s_waitcnt lgkmcnt(6)
	v_mfma_f32_16x16x32_bf16 v[52:55], v[200:203], v[172:175], v[52:55]
	v_mfma_f32_16x16x32_bf16 v[48:51], v[204:207], v[172:175], v[48:51]
	s_waitcnt lgkmcnt(5)
	v_mfma_f32_16x16x32_bf16 v[44:47], v[200:203], v[176:179], v[44:47]
	v_mfma_f32_16x16x32_bf16 v[40:43], v[204:207], v[176:179], v[40:43]
	s_waitcnt lgkmcnt(4)
	v_mfma_f32_16x16x32_bf16 v[36:39], v[200:203], v[180:183], v[36:39]
	v_mfma_f32_16x16x32_bf16 v[32:35], v[204:207], v[180:183], v[32:35]
	s_waitcnt lgkmcnt(3)
	v_mfma_f32_16x16x32_bf16 v[28:31], v[200:203], v[184:187], v[28:31]
	v_mfma_f32_16x16x32_bf16 v[24:27], v[204:207], v[184:187], v[24:27]
	s_waitcnt lgkmcnt(2)
	v_mfma_f32_16x16x32_bf16 v[20:23], v[200:203], v[188:191], v[20:23]
	v_mfma_f32_16x16x32_bf16 v[16:19], v[204:207], v[188:191], v[16:19]
	s_waitcnt lgkmcnt(1)
	v_mfma_f32_16x16x32_bf16 v[12:15], v[200:203], v[192:195], v[12:15]
	v_mfma_f32_16x16x32_bf16 v[8:11], v[204:207], v[192:195], v[8:11]
	s_waitcnt lgkmcnt(0)
	v_mfma_f32_16x16x32_bf16 v[4:7], v[200:203], v[196:199], v[4:7]
	v_mfma_f32_16x16x32_bf16 v[0:3], v[204:207], v[196:199], v[0:3]
	s_add_u32 s12, s99, 0x1a000
	s_cmp_ge_u32 s12, 0x27000
	s_cselect_b32 s13, 0x27000, 0
	s_sub_u32 s12, s12, s13
	v_add_u32_e32 v168, s12, v98
	s_add_u32 s12, s10, 0x80
	s_addc_u32 s13, s11, 0
	v_lshl_add_u64 v[94:95], v[90:91], 0, s[12:13]
	v_lshl_add_u64 v[186:187], v[92:93], 0, s[12:13]
	v_readfirstlane_b32 s98, v168
	v_lshl_add_u64 v[188:189], v[94:95], 0, s[78:79]
	s_mov_b32 m0, s98
	s_nop 0
	global_load_lds_dwordx4 v[188:189], off
	v_lshl_add_u64 v[188:189], v[94:95], 0, s[80:81]
	s_add_u32 m0, s98, 0x2000
	s_nop 0
	global_load_lds_dwordx4 v[188:189], off
	v_lshl_add_u64 v[188:189], v[94:95], 0, s[82:83]
	s_add_u32 m0, s98, 0x4000
	s_nop 0
	global_load_lds_dwordx4 v[188:189], off
	s_mov_b64 s[12:13], 0x360080
	v_lshl_add_u64 v[188:189], v[186:187], 0, s[12:13]
	s_add_u32 m0, s98, 0x5000
	s_nop 0
	global_load_lds_dwordx4 v[188:189], off
	s_mov_b64 s[12:13], 0x380080
	v_lshl_add_u64 v[188:189], v[186:187], 0, s[12:13]
	s_add_u32 m0, s98, 0x7000
	s_nop 0
	global_load_lds_dwordx4 v[188:189], off
	s_mov_b64 s[12:13], 0x3a0080
	v_lshl_add_u64 v[188:189], v[186:187], 0, s[12:13]
	s_add_u32 m0, s98, 0x9000
	s_nop 0
	global_load_lds_dwordx4 v[188:189], off
	s_mov_b64 s[12:13], 0x3c0080
	v_lshl_add_u64 v[188:189], v[186:187], 0, s[12:13]
	s_add_u32 m0, s98, 0xb000
	s_nop 0
	global_load_lds_dwordx4 v[188:189], off
	s_add_u32 s99, s99, 0xd000
	s_cmp_eq_u32 s99, 0x27000
	s_cselect_b32 s99, 0, s99
	s_add_u32 s10, s10, 0x80
	s_addc_u32 s11, s11, 0
	s_cmpk_eq_i32 s10, 0x700
	s_cbranch_scc0 .Lgxo_p
	v_add_u32_e32 v164, s99, v97
	v_add_u32_e32 v165, s99, v99
	v_add_u32_e32 v192, v164, v101
	v_add_u32_e32 v196, v165, v101
	v_add_u32_e32 v164, v164, v100
	v_add_u32_e32 v165, v165, v100
	s_waitcnt vmcnt(7) lgkmcnt(0)
	s_barrier
	ds_read_b128 v[152:155], v164 offset:20480
	ds_read_b128 v[156:159], v164 offset:22528
	ds_read_b128 v[108:111], v165
	ds_read_b128 v[112:115], v165 offset:2048
	ds_read_b128 v[116:119], v165 offset:4096
	ds_read_b128 v[120:123], v165 offset:6144
	ds_read_b128 v[124:127], v165 offset:8192
	ds_read_b128 v[132:135], v165 offset:10240
	ds_read_b128 v[136:139], v165 offset:12288
	ds_read_b128 v[140:143], v165 offset:14336
	ds_read_b128 v[144:147], v165 offset:16384
	ds_read_b128 v[148:151], v165 offset:18432
	s_waitcnt lgkmcnt(9)
	v_mfma_f32_16x16x32_bf16 v[76:79], v[152:155], v[108:111], v[76:79]
	v_mfma_f32_16x16x32_bf16 v[72:75], v[156:159], v[108:111], v[72:75]
	ds_read_b128 v[200:203], v192 offset:20480
	s_waitcnt lgkmcnt(9)
	v_mfma_f32_16x16x32_bf16 v[68:71], v[152:155], v[112:115], v[68:71]
	v_mfma_f32_16x16x32_bf16 v[64:67], v[156:159], v[112:115], v[64:67]
	ds_read_b128 v[204:207], v192 offset:22528
	s_waitcnt lgkmcnt(9)
	v_mfma_f32_16x16x32_bf16 v[60:63], v[152:155], v[116:119], v[60:63]
	v_mfma_f32_16x16x32_bf16 v[56:59], v[156:159], v[116:119], v[56:59]
	ds_read_b128 v[160:163], v196
	s_waitcnt lgkmcnt(9)
	v_mfma_f32_16x16x32_bf16 v[52:55], v[152:155], v[120:123], v[52:55]
	v_mfma_f32_16x16x32_bf16 v[48:51], v[156:159], v[120:123], v[48:51]
	ds_read_b128 v[164:167], v196 offset:2048
	s_waitcnt lgkmcnt(9)
	v_mfma_f32_16x16x32_bf16 v[44:47], v[152:155], v[124:127], v[44:47]
	v_mfma_f32_16x16x32_bf16 v[40:43], v[156:159], v[124:127], v[40:43]
	ds_read_b128 v[168:171], v196 offset:4096
	s_waitcnt lgkmcnt(9)
	v_mfma_f32_16x16x32_bf16 v[36:39], v[152:155], v[132:135], v[36:39]
	v_mfma_f32_16x16x32_bf16 v[32:35], v[156:159], v[132:135], v[32:35]
	ds_read_b128 v[172:175], v196 offset:6144
	s_waitcnt lgkmcnt(9)
	v_mfma_f32_16x16x32_bf16 v[28:31], v[152:155], v[136:139], v[28:31]
	v_mfma_f32_16x16x32_bf16 v[24:27], v[156:159], v[136:139], v[24:27]
	ds_read_b128 v[176:179], v196 offset:8192
	s_waitcnt lgkmcnt(9)
	v_mfma_f32_16x16x32_bf16 v[20:23], v[152:155], v[140:143], v[20:23]
	v_mfma_f32_16x16x32_bf16 v[16:19], v[156:159], v[140:143], v[16:19]
	ds_read_b128 v[180:183], v196 offset:10240
	s_waitcnt lgkmcnt(9)
	v_mfma_f32_16x16x32_bf16 v[12:15], v[152:155], v[144:147], v[12:15]
	v_mfma_f32_16x16x32_bf16 v[8:11], v[156:159], v[144:147], v[8:11]
	ds_read_b128 v[184:187], v196 offset:12288
	s_waitcnt lgkmcnt(9)
	v_mfma_f32_16x16x32_bf16 v[4:7], v[152:155], v[148:151], v[4:7]
	v_mfma_f32_16x16x32_bf16 v[0:3], v[156:159], v[148:151], v[0:3]
	ds_read_b128 v[188:191], v196 offset:14336
	ds_read_b128 v[192:195], v196 offset:16384
	ds_read_b128 v[196:199], v196 offset:18432
	s_waitcnt lgkmcnt(9)
	v_mfma_f32_16x16x32_bf16 v[76:79], v[200:203], v[160:163], v[76:79]
	v_mfma_f32_16x16x32_bf16 v[72:75], v[204:207], v[160:163], v[72:75]
	s_waitcnt lgkmcnt(8)
	v_mfma_f32_16x16x32_bf16 v[68:71], v[200:203], v[164:167], v[68:71]
	v_mfma_f32_16x16x32_bf16 v[64:67], v[204:207], v[164:167], v[64:67]
	s_waitcnt lgkmcnt(7)
	v_mfma_f32_16x16x32_bf16 v[60:63], v[200:203], v[168:171], v[60:63]
	v_mfma_f32_16x16x32_bf16 v[56:59], v[204:207], v[168:171], v[56:59]
	s_waitcnt lgkmcnt(6)
	v_mfma_f32_16x16x32_bf16 v[52:55], v[200:203], v[172:175], v[52:55]
	v_mfma_f32_16x16x32_bf16 v[48:51], v[204:207], v[172:175], v[48:51]
	s_waitcnt lgkmcnt(5)
	v_mfma_f32_16x16x32_bf16 v[44:47], v[200:203], v[176:179], v[44:47]
	v_mfma_f32_16x16x32_bf16 v[40:43], v[204:207], v[176:179], v[40:43]
	s_waitcnt lgkmcnt(4)
	v_mfma_f32_16x16x32_bf16 v[36:39], v[200:203], v[180:183], v[36:39]
	v_mfma_f32_16x16x32_bf16 v[32:35], v[204:207], v[180:183], v[32:35]
	s_waitcnt lgkmcnt(3)
	v_mfma_f32_16x16x32_bf16 v[28:31], v[200:203], v[184:187], v[28:31]
	v_mfma_f32_16x16x32_bf16 v[24:27], v[204:207], v[184:187], v[24:27]
	s_waitcnt lgkmcnt(2)
	v_mfma_f32_16x16x32_bf16 v[20:23], v[200:203], v[188:191], v[20:23]
	v_mfma_f32_16x16x32_bf16 v[16:19], v[204:207], v[188:191], v[16:19]
	s_waitcnt lgkmcnt(1)
	v_mfma_f32_16x16x32_bf16 v[12:15], v[200:203], v[192:195], v[12:15]
	v_mfma_f32_16x16x32_bf16 v[8:11], v[204:207], v[192:195], v[8:11]
	s_waitcnt lgkmcnt(0)
	v_mfma_f32_16x16x32_bf16 v[4:7], v[200:203], v[196:199], v[4:7]
	v_mfma_f32_16x16x32_bf16 v[0:3], v[204:207], v[196:199], v[0:3]
	s_cmp_eq_u32 s101, 0
	s_cbranch_scc1 .Lgxo_pbb
	s_add_u32 s12, s99, 0x1a000
	s_cmp_ge_u32 s12, 0x27000
	s_cselect_b32 s13, 0x27000, 0
	s_sub_u32 s12, s12, s13
	v_add_u32_e32 v168, s12, v98
	s_mov_b32 s12, 0xffffff80
	s_mov_b32 s13, -1
	v_lshl_add_u64 v[94:95], v[102:103], 0, s[12:13]
	v_lshl_add_u64 v[186:187], v[104:105], 0, s[12:13]
	v_readfirstlane_b32 s98, v168
	v_lshl_add_u64 v[188:189], v[94:95], 0, s[78:79]
	s_mov_b32 m0, s98
	s_nop 0
	global_load_lds_dwordx4 v[188:189], off
	v_lshl_add_u64 v[188:189], v[94:95], 0, s[80:81]
	s_add_u32 m0, s98, 0x2000
	s_nop 0
	global_load_lds_dwordx4 v[188:189], off
	v_lshl_add_u64 v[188:189], v[94:95], 0, s[82:83]
	s_add_u32 m0, s98, 0x4000
	s_nop 0
	global_load_lds_dwordx4 v[188:189], off
	s_mov_b64 s[12:13], 0x360080
	v_lshl_add_u64 v[188:189], v[186:187], 0, s[12:13]
	s_add_u32 m0, s98, 0x5000
	s_nop 0
	global_load_lds_dwordx4 v[188:189], off
	s_mov_b64 s[12:13], 0x380080
	v_lshl_add_u64 v[188:189], v[186:187], 0, s[12:13]
	s_add_u32 m0, s98, 0x7000
	s_nop 0
	global_load_lds_dwordx4 v[188:189], off
	s_mov_b64 s[12:13], 0x3a0080
	v_lshl_add_u64 v[188:189], v[186:187], 0, s[12:13]
	s_add_u32 m0, s98, 0x9000
	s_nop 0
	global_load_lds_dwordx4 v[188:189], off
	s_mov_b64 s[12:13], 0x3c0080
	v_lshl_add_u64 v[188:189], v[186:187], 0, s[12:13]
	s_add_u32 m0, s98, 0xb000
	s_nop 0
	global_load_lds_dwordx4 v[188:189], off
.Lgxo_pbb:
	s_add_u32 s99, s99, 0xd000
	s_cmp_eq_u32 s99, 0x27000
	s_cselect_b32 s99, 0, s99
	v_add_u32_e32 v164, s99, v97
	v_add_u32_e32 v165, s99, v99
	v_add_u32_e32 v192, v164, v101
	v_add_u32_e32 v196, v165, v101
	v_add_u32_e32 v164, v164, v100
	v_add_u32_e32 v165, v165, v100
	s_cmp_eq_u32 s101, 0
	s_cbranch_scc1 .Lgxo_pcw0
	s_waitcnt vmcnt(7)
	s_branch .Lgxo_pcw1

.Lgxo_pcw1:
	s_waitcnt lgkmcnt(0)
	s_barrier
	ds_read_b128 v[152:155], v164 offset:20480
	ds_read_b128 v[156:159], v164 offset:22528
	ds_read_b128 v[108:111], v165
	ds_read_b128 v[112:115], v165 offset:2048
	ds_read_b128 v[116:119], v165 offset:4096
	ds_read_b128 v[120:123], v165 offset:6144
	ds_read_b128 v[124:127], v165 offset:8192
	ds_read_b128 v[132:135], v165 offset:10240
	ds_read_b128 v[136:139], v165 offset:12288
	ds_read_b128 v[140:143], v165 offset:14336
	ds_read_b128 v[144:147], v165 offset:16384
	ds_read_b128 v[148:151], v165 offset:18432
	s_waitcnt lgkmcnt(9)
	v_mfma_f32_16x16x32_bf16 v[76:79], v[152:155], v[108:111], v[76:79]
	v_mfma_f32_16x16x32_bf16 v[72:75], v[156:159], v[108:111], v[72:75]
	ds_read_b128 v[200:203], v192 offset:20480
	s_waitcnt lgkmcnt(9)
	v_mfma_f32_16x16x32_bf16 v[68:71], v[152:155], v[112:115], v[68:71]
	v_mfma_f32_16x16x32_bf16 v[64:67], v[156:159], v[112:115], v[64:67]
	ds_read_b128 v[204:207], v192 offset:22528
	s_waitcnt lgkmcnt(9)
	v_mfma_f32_16x16x32_bf16 v[60:63], v[152:155], v[116:119], v[60:63]
	v_mfma_f32_16x16x32_bf16 v[56:59], v[156:159], v[116:119], v[56:59]
	ds_read_b128 v[160:163], v196
	s_waitcnt lgkmcnt(9)
	v_mfma_f32_16x16x32_bf16 v[52:55], v[152:155], v[120:123], v[52:55]
	v_mfma_f32_16x16x32_bf16 v[48:51], v[156:159], v[120:123], v[48:51]
	ds_read_b128 v[164:167], v196 offset:2048
	s_waitcnt lgkmcnt(9)
	v_mfma_f32_16x16x32_bf16 v[44:47], v[152:155], v[124:127], v[44:47]
	v_mfma_f32_16x16x32_bf16 v[40:43], v[156:159], v[124:127], v[40:43]
	ds_read_b128 v[168:171], v196 offset:4096
	s_waitcnt lgkmcnt(9)
	v_mfma_f32_16x16x32_bf16 v[36:39], v[152:155], v[132:135], v[36:39]
	v_mfma_f32_16x16x32_bf16 v[32:35], v[156:159], v[132:135], v[32:35]
	ds_read_b128 v[172:175], v196 offset:6144
	s_waitcnt lgkmcnt(9)
	v_mfma_f32_16x16x32_bf16 v[28:31], v[152:155], v[136:139], v[28:31]
	v_mfma_f32_16x16x32_bf16 v[24:27], v[156:159], v[136:139], v[24:27]
	ds_read_b128 v[176:179], v196 offset:8192
	s_waitcnt lgkmcnt(9)
	v_mfma_f32_16x16x32_bf16 v[20:23], v[152:155], v[140:143], v[20:23]
	v_mfma_f32_16x16x32_bf16 v[16:19], v[156:159], v[140:143], v[16:19]
	ds_read_b128 v[180:183], v196 offset:10240
	s_waitcnt lgkmcnt(9)
	v_mfma_f32_16x16x32_bf16 v[12:15], v[152:155], v[144:147], v[12:15]
	v_mfma_f32_16x16x32_bf16 v[8:11], v[156:159], v[144:147], v[8:11]
	ds_read_b128 v[184:187], v196 offset:12288
	s_waitcnt lgkmcnt(9)
	v_mfma_f32_16x16x32_bf16 v[4:7], v[152:155], v[148:151], v[4:7]
	v_mfma_f32_16x16x32_bf16 v[0:3], v[156:159], v[148:151], v[0:3]
	ds_read_b128 v[188:191], v196 offset:14336
	ds_read_b128 v[192:195], v196 offset:16384
	ds_read_b128 v[196:199], v196 offset:18432
	s_waitcnt lgkmcnt(9)
	v_mfma_f32_16x16x32_bf16 v[76:79], v[200:203], v[160:163], v[76:79]
	v_mfma_f32_16x16x32_bf16 v[72:75], v[204:207], v[160:163], v[72:75]
	s_waitcnt lgkmcnt(8)
	v_mfma_f32_16x16x32_bf16 v[68:71], v[200:203], v[164:167], v[68:71]
	v_mfma_f32_16x16x32_bf16 v[64:67], v[204:207], v[164:167], v[64:67]
	s_waitcnt lgkmcnt(7)
	v_mfma_f32_16x16x32_bf16 v[60:63], v[200:203], v[168:171], v[60:63]
	v_mfma_f32_16x16x32_bf16 v[56:59], v[204:207], v[168:171], v[56:59]
	s_waitcnt lgkmcnt(6)
	v_mfma_f32_16x16x32_bf16 v[52:55], v[200:203], v[172:175], v[52:55]
	v_mfma_f32_16x16x32_bf16 v[48:51], v[204:207], v[172:175], v[48:51]
	s_waitcnt lgkmcnt(5)
	v_mfma_f32_16x16x32_bf16 v[44:47], v[200:203], v[176:179], v[44:47]
	v_mfma_f32_16x16x32_bf16 v[40:43], v[204:207], v[176:179], v[40:43]
	s_waitcnt lgkmcnt(4)
	v_mfma_f32_16x16x32_bf16 v[36:39], v[200:203], v[180:183], v[36:39]
	v_mfma_f32_16x16x32_bf16 v[32:35], v[204:207], v[180:183], v[32:35]
	s_waitcnt lgkmcnt(3)
	v_mfma_f32_16x16x32_bf16 v[28:31], v[200:203], v[184:187], v[28:31]
	v_mfma_f32_16x16x32_bf16 v[24:27], v[204:207], v[184:187], v[24:27]
	s_waitcnt lgkmcnt(2)
	v_mfma_f32_16x16x32_bf16 v[20:23], v[200:203], v[188:191], v[20:23]
	v_mfma_f32_16x16x32_bf16 v[16:19], v[204:207], v[188:191], v[16:19]
	s_waitcnt lgkmcnt(1)
	v_mfma_f32_16x16x32_bf16 v[12:15], v[200:203], v[192:195], v[12:15]
	v_mfma_f32_16x16x32_bf16 v[8:11], v[204:207], v[192:195], v[8:11]
	s_waitcnt lgkmcnt(0)
	v_mfma_f32_16x16x32_bf16 v[4:7], v[200:203], v[196:199], v[4:7]
	v_mfma_f32_16x16x32_bf16 v[0:3], v[204:207], v[196:199], v[0:3]
	s_cmp_eq_u32 s101, 0
	s_cbranch_scc1 .Lgxo_pcb
	s_add_u32 s12, s99, 0x1a000
	s_cmp_ge_u32 s12, 0x27000
	s_cselect_b32 s13, 0x27000, 0
	s_sub_u32 s12, s12, s13
	v_add_u32_e32 v168, s12, v98
	s_mov_b64 s[12:13], 0
	v_lshl_add_u64 v[94:95], v[102:103], 0, s[12:13]
	v_lshl_add_u64 v[186:187], v[104:105], 0, s[12:13]
	v_readfirstlane_b32 s98, v168
	v_lshl_add_u64 v[188:189], v[94:95], 0, s[78:79]
	s_mov_b32 m0, s98
	s_nop 0
	global_load_lds_dwordx4 v[188:189], off
	v_lshl_add_u64 v[188:189], v[94:95], 0, s[80:81]
	s_add_u32 m0, s98, 0x2000
	s_nop 0
	global_load_lds_dwordx4 v[188:189], off
	v_lshl_add_u64 v[188:189], v[94:95], 0, s[82:83]
	s_add_u32 m0, s98, 0x4000
	s_nop 0
	global_load_lds_dwordx4 v[188:189], off
	s_mov_b64 s[12:13], 0x360080
	v_lshl_add_u64 v[188:189], v[186:187], 0, s[12:13]
	s_add_u32 m0, s98, 0x5000
	s_nop 0
	global_load_lds_dwordx4 v[188:189], off
	s_mov_b64 s[12:13], 0x380080
	v_lshl_add_u64 v[188:189], v[186:187], 0, s[12:13]
	s_add_u32 m0, s98, 0x7000
	s_nop 0
	global_load_lds_dwordx4 v[188:189], off
	s_mov_b64 s[12:13], 0x3a0080
	v_lshl_add_u64 v[188:189], v[186:187], 0, s[12:13]
	s_add_u32 m0, s98, 0x9000
	s_nop 0
	global_load_lds_dwordx4 v[188:189], off
	s_mov_b64 s[12:13], 0x3c0080
	v_lshl_add_u64 v[188:189], v[186:187], 0, s[12:13]
	s_add_u32 m0, s98, 0xb000
	s_nop 0
	global_load_lds_dwordx4 v[188:189], off

.Lgxo_q:
	s_add_u32 s12, s99, 0x1a000
	s_cmp_ge_u32 s12, 0x27000
	s_cselect_b32 s13, 0x27000, 0
	s_sub_u32 s12, s12, s13
	v_add_u32_e32 v168, s12, v98
	s_add_u32 s12, s10, 0x80
	s_addc_u32 s13, s11, 0
	v_lshl_add_u64 v[94:95], v[90:91], 0, s[12:13]
	v_lshl_add_u64 v[186:187], v[92:93], 0, s[12:13]
	v_readfirstlane_b32 s98, v168
	v_add_u32_e32 v164, s99, v97
	v_add_u32_e32 v165, s99, v99
	v_add_u32_e32 v192, v164, v101
	v_add_u32_e32 v196, v165, v101
	v_add_u32_e32 v164, v164, v100
	v_add_u32_e32 v165, v165, v100
	s_waitcnt vmcnt(6) lgkmcnt(0)
	s_barrier
	v_lshl_add_u64 v[188:189], v[94:95], 0, s[78:79]
	s_mov_b32 m0, s98
	s_nop 0
	global_load_lds_dwordx4 v[188:189], off
	v_lshl_add_u64 v[188:189], v[94:95], 0, s[80:81]
	s_add_u32 m0, s98, 0x2000
	s_nop 0
	global_load_lds_dwordx4 v[188:189], off
	s_mov_b64 s[12:13], 0x360080
	v_lshl_add_u64 v[188:189], v[186:187], 0, s[12:13]
	s_add_u32 m0, s98, 0x5000
	s_nop 0
	global_load_lds_dwordx4 v[188:189], off
	s_mov_b64 s[12:13], 0x380080
	v_lshl_add_u64 v[188:189], v[186:187], 0, s[12:13]
	s_add_u32 m0, s98, 0x7000
	s_nop 0
	global_load_lds_dwordx4 v[188:189], off
	s_mov_b64 s[12:13], 0x3a0080
	v_lshl_add_u64 v[188:189], v[186:187], 0, s[12:13]
	s_add_u32 m0, s98, 0x9000
	s_nop 0
	global_load_lds_dwordx4 v[188:189], off
	s_mov_b64 s[12:13], 0x3c0080
	v_lshl_add_u64 v[188:189], v[186:187], 0, s[12:13]
	s_add_u32 m0, s98, 0xb000
	s_nop 0
	global_load_lds_dwordx4 v[188:189], off
	ds_read_b128 v[152:155], v164 offset:20480
	ds_read_b128 v[156:159], v164 offset:22528
	ds_read_b128 v[108:111], v165
	ds_read_b128 v[112:115], v165 offset:2048
	ds_read_b128 v[116:119], v165 offset:4096
	ds_read_b128 v[120:123], v165 offset:6144
	ds_read_b128 v[124:127], v165 offset:8192
	ds_read_b128 v[132:135], v165 offset:10240
	ds_read_b128 v[136:139], v165 offset:12288
	ds_read_b128 v[140:143], v165 offset:14336
	ds_read_b128 v[144:147], v165 offset:16384
	ds_read_b128 v[148:151], v165 offset:18432
	s_waitcnt lgkmcnt(9)
	v_mfma_f32_16x16x32_bf16 v[76:79], v[152:155], v[108:111], v[76:79]
	v_mfma_f32_16x16x32_bf16 v[72:75], v[156:159], v[108:111], v[72:75]
	ds_read_b128 v[200:203], v192 offset:20480
	s_waitcnt lgkmcnt(9)
	v_mfma_f32_16x16x32_bf16 v[68:71], v[152:155], v[112:115], v[68:71]
	v_mfma_f32_16x16x32_bf16 v[64:67], v[156:159], v[112:115], v[64:67]
	ds_read_b128 v[204:207], v192 offset:22528
	s_waitcnt lgkmcnt(9)
	v_mfma_f32_16x16x32_bf16 v[60:63], v[152:155], v[116:119], v[60:63]
	v_mfma_f32_16x16x32_bf16 v[56:59], v[156:159], v[116:119], v[56:59]
	ds_read_b128 v[160:163], v196
	s_waitcnt lgkmcnt(9)
	v_mfma_f32_16x16x32_bf16 v[52:55], v[152:155], v[120:123], v[52:55]
	v_mfma_f32_16x16x32_bf16 v[48:51], v[156:159], v[120:123], v[48:51]
	ds_read_b128 v[164:167], v196 offset:2048
	s_waitcnt lgkmcnt(9)
	v_mfma_f32_16x16x32_bf16 v[44:47], v[152:155], v[124:127], v[44:47]
	v_mfma_f32_16x16x32_bf16 v[40:43], v[156:159], v[124:127], v[40:43]
	ds_read_b128 v[168:171], v196 offset:4096
	s_waitcnt lgkmcnt(9)
	v_mfma_f32_16x16x32_bf16 v[36:39], v[152:155], v[132:135], v[36:39]
	v_mfma_f32_16x16x32_bf16 v[32:35], v[156:159], v[132:135], v[32:35]
	ds_read_b128 v[172:175], v196 offset:6144
	s_waitcnt lgkmcnt(9)
	v_mfma_f32_16x16x32_bf16 v[28:31], v[152:155], v[136:139], v[28:31]
	v_mfma_f32_16x16x32_bf16 v[24:27], v[156:159], v[136:139], v[24:27]
	ds_read_b128 v[176:179], v196 offset:8192
	s_waitcnt lgkmcnt(9)
	v_mfma_f32_16x16x32_bf16 v[20:23], v[152:155], v[140:143], v[20:23]
	v_mfma_f32_16x16x32_bf16 v[16:19], v[156:159], v[140:143], v[16:19]
	ds_read_b128 v[180:183], v196 offset:10240
	s_waitcnt lgkmcnt(9)
	v_mfma_f32_16x16x32_bf16 v[12:15], v[152:155], v[144:147], v[12:15]
	v_mfma_f32_16x16x32_bf16 v[8:11], v[156:159], v[144:147], v[8:11]
	ds_read_b128 v[184:187], v196 offset:12288
	s_waitcnt lgkmcnt(9)
	v_mfma_f32_16x16x32_bf16 v[4:7], v[152:155], v[148:151], v[4:7]
	v_mfma_f32_16x16x32_bf16 v[0:3], v[156:159], v[148:151], v[0:3]
	ds_read_b128 v[188:191], v196 offset:14336
	ds_read_b128 v[192:195], v196 offset:16384
	ds_read_b128 v[196:199], v196 offset:18432
	s_waitcnt lgkmcnt(9)
	v_mfma_f32_16x16x32_bf16 v[76:79], v[200:203], v[160:163], v[76:79]
	v_mfma_f32_16x16x32_bf16 v[72:75], v[204:207], v[160:163], v[72:75]
	s_waitcnt lgkmcnt(8)
	v_mfma_f32_16x16x32_bf16 v[68:71], v[200:203], v[164:167], v[68:71]
	v_mfma_f32_16x16x32_bf16 v[64:67], v[204:207], v[164:167], v[64:67]
	s_waitcnt lgkmcnt(7)
	v_mfma_f32_16x16x32_bf16 v[60:63], v[200:203], v[168:171], v[60:63]
	v_mfma_f32_16x16x32_bf16 v[56:59], v[204:207], v[168:171], v[56:59]
	s_waitcnt lgkmcnt(6)
	v_mfma_f32_16x16x32_bf16 v[52:55], v[200:203], v[172:175], v[52:55]
	v_mfma_f32_16x16x32_bf16 v[48:51], v[204:207], v[172:175], v[48:51]
	s_waitcnt lgkmcnt(5)
	v_mfma_f32_16x16x32_bf16 v[44:47], v[200:203], v[176:179], v[44:47]
	v_mfma_f32_16x16x32_bf16 v[40:43], v[204:207], v[176:179], v[40:43]
	s_waitcnt lgkmcnt(4)
	v_mfma_f32_16x16x32_bf16 v[36:39], v[200:203], v[180:183], v[36:39]
	v_mfma_f32_16x16x32_bf16 v[32:35], v[204:207], v[180:183], v[32:35]
	s_waitcnt lgkmcnt(3)
	v_mfma_f32_16x16x32_bf16 v[28:31], v[200:203], v[184:187], v[28:31]
	v_mfma_f32_16x16x32_bf16 v[24:27], v[204:207], v[184:187], v[24:27]
	s_waitcnt lgkmcnt(2)
	v_mfma_f32_16x16x32_bf16 v[20:23], v[200:203], v[188:191], v[20:23]
	v_mfma_f32_16x16x32_bf16 v[16:19], v[204:207], v[188:191], v[16:19]
	s_waitcnt lgkmcnt(1)
	v_mfma_f32_16x16x32_bf16 v[12:15], v[200:203], v[192:195], v[12:15]
	v_mfma_f32_16x16x32_bf16 v[8:11], v[204:207], v[192:195], v[8:11]
	s_waitcnt lgkmcnt(0)
	v_mfma_f32_16x16x32_bf16 v[4:7], v[200:203], v[196:199], v[4:7]
	v_mfma_f32_16x16x32_bf16 v[0:3], v[204:207], v[196:199], v[0:3]
	s_add_u32 s99, s99, 0xd000
	s_cmp_eq_u32 s99, 0x27000
	s_cselect_b32 s99, 0, s99
	s_add_u32 s10, s10, 0x80
	s_addc_u32 s11, s11, 0
	s_cmpk_eq_i32 s10, 0x700
	s_cbranch_scc0 .Lgxo_q
	s_cmp_eq_u32 s101, 0
	s_cbranch_scc1 .Lgxo_qbp
	s_add_u32 s12, s99, 0x1a000
	s_cmp_ge_u32 s12, 0x27000
	s_cselect_b32 s13, 0x27000, 0
	s_sub_u32 s12, s12, s13
	v_add_u32_e32 v168, s12, v98
	s_mov_b32 s12, 0xffffff80
	s_mov_b32 s13, -1
	v_lshl_add_u64 v[94:95], v[102:103], 0, s[12:13]
	v_lshl_add_u64 v[186:187], v[104:105], 0, s[12:13]
	v_readfirstlane_b32 s98, v168
.Lgxo_qbp:
	v_add_u32_e32 v164, s99, v97
	v_add_u32_e32 v165, s99, v99
	v_add_u32_e32 v192, v164, v101
	v_add_u32_e32 v196, v165, v101
	v_add_u32_e32 v164, v164, v100
	v_add_u32_e32 v165, v165, v100
	s_waitcnt vmcnt(6) lgkmcnt(0)
	s_barrier
	s_cmp_eq_u32 s101, 0
	s_cbranch_scc1 .Lgxo_qbb
	v_lshl_add_u64 v[188:189], v[94:95], 0, s[78:79]
	s_mov_b32 m0, s98
	s_nop 0
	global_load_lds_dwordx4 v[188:189], off
	v_lshl_add_u64 v[188:189], v[94:95], 0, s[80:81]
	s_add_u32 m0, s98, 0x2000
	s_nop 0
	global_load_lds_dwordx4 v[188:189], off
	s_mov_b64 s[12:13], 0x360080
	v_lshl_add_u64 v[188:189], v[186:187], 0, s[12:13]
	s_add_u32 m0, s98, 0x5000
	s_nop 0
	global_load_lds_dwordx4 v[188:189], off
	s_mov_b64 s[12:13], 0x380080
	v_lshl_add_u64 v[188:189], v[186:187], 0, s[12:13]
	s_add_u32 m0, s98, 0x7000
	s_nop 0
	global_load_lds_dwordx4 v[188:189], off
	s_mov_b64 s[12:13], 0x3a0080
	v_lshl_add_u64 v[188:189], v[186:187], 0, s[12:13]
	s_add_u32 m0, s98, 0x9000
	s_nop 0
	global_load_lds_dwordx4 v[188:189], off
	s_mov_b64 s[12:13], 0x3c0080
	v_lshl_add_u64 v[188:189], v[186:187], 0, s[12:13]
	s_add_u32 m0, s98, 0xb000
	s_nop 0
	global_load_lds_dwordx4 v[188:189], off
.Lgxo_qbb:
	ds_read_b128 v[152:155], v164 offset:20480
	ds_read_b128 v[156:159], v164 offset:22528
	ds_read_b128 v[108:111], v165
	ds_read_b128 v[112:115], v165 offset:2048
	ds_read_b128 v[116:119], v165 offset:4096
	ds_read_b128 v[120:123], v165 offset:6144
	ds_read_b128 v[124:127], v165 offset:8192
	ds_read_b128 v[132:135], v165 offset:10240
	ds_read_b128 v[136:139], v165 offset:12288
	ds_read_b128 v[140:143], v165 offset:14336
	ds_read_b128 v[144:147], v165 offset:16384
	ds_read_b128 v[148:151], v165 offset:18432
	s_waitcnt lgkmcnt(9)
	v_mfma_f32_16x16x32_bf16 v[76:79], v[152:155], v[108:111], v[76:79]
	v_mfma_f32_16x16x32_bf16 v[72:75], v[156:159], v[108:111], v[72:75]
	ds_read_b128 v[200:203], v192 offset:20480
	s_waitcnt lgkmcnt(9)
	v_mfma_f32_16x16x32_bf16 v[68:71], v[152:155], v[112:115], v[68:71]
	v_mfma_f32_16x16x32_bf16 v[64:67], v[156:159], v[112:115], v[64:67]
	ds_read_b128 v[204:207], v192 offset:22528
	s_waitcnt lgkmcnt(9)
	v_mfma_f32_16x16x32_bf16 v[60:63], v[152:155], v[116:119], v[60:63]
	v_mfma_f32_16x16x32_bf16 v[56:59], v[156:159], v[116:119], v[56:59]
	ds_read_b128 v[160:163], v196
	s_waitcnt lgkmcnt(9)
	v_mfma_f32_16x16x32_bf16 v[52:55], v[152:155], v[120:123], v[52:55]
	v_mfma_f32_16x16x32_bf16 v[48:51], v[156:159], v[120:123], v[48:51]
	ds_read_b128 v[164:167], v196 offset:2048
	s_waitcnt lgkmcnt(9)
	v_mfma_f32_16x16x32_bf16 v[44:47], v[152:155], v[124:127], v[44:47]
	v_mfma_f32_16x16x32_bf16 v[40:43], v[156:159], v[124:127], v[40:43]
	ds_read_b128 v[168:171], v196 offset:4096
	s_waitcnt lgkmcnt(9)
	v_mfma_f32_16x16x32_bf16 v[36:39], v[152:155], v[132:135], v[36:39]
	v_mfma_f32_16x16x32_bf16 v[32:35], v[156:159], v[132:135], v[32:35]
	ds_read_b128 v[172:175], v196 offset:6144
	s_waitcnt lgkmcnt(9)
	v_mfma_f32_16x16x32_bf16 v[28:31], v[152:155], v[136:139], v[28:31]
	v_mfma_f32_16x16x32_bf16 v[24:27], v[156:159], v[136:139], v[24:27]
	ds_read_b128 v[176:179], v196 offset:8192
	s_waitcnt lgkmcnt(9)
	v_mfma_f32_16x16x32_bf16 v[20:23], v[152:155], v[140:143], v[20:23]
	v_mfma_f32_16x16x32_bf16 v[16:19], v[156:159], v[140:143], v[16:19]
	ds_read_b128 v[180:183], v196 offset:10240
	s_waitcnt lgkmcnt(9)
	v_mfma_f32_16x16x32_bf16 v[12:15], v[152:155], v[144:147], v[12:15]
	v_mfma_f32_16x16x32_bf16 v[8:11], v[156:159], v[144:147], v[8:11]
	ds_read_b128 v[184:187], v196 offset:12288
	s_waitcnt lgkmcnt(9)
	v_mfma_f32_16x16x32_bf16 v[4:7], v[152:155], v[148:151], v[4:7]
	v_mfma_f32_16x16x32_bf16 v[0:3], v[156:159], v[148:151], v[0:3]
	ds_read_b128 v[188:191], v196 offset:14336
	ds_read_b128 v[192:195], v196 offset:16384
	ds_read_b128 v[196:199], v196 offset:18432
	s_waitcnt lgkmcnt(9)
	v_mfma_f32_16x16x32_bf16 v[76:79], v[200:203], v[160:163], v[76:79]
	v_mfma_f32_16x16x32_bf16 v[72:75], v[204:207], v[160:163], v[72:75]
	s_waitcnt lgkmcnt(8)
	v_mfma_f32_16x16x32_bf16 v[68:71], v[200:203], v[164:167], v[68:71]
	v_mfma_f32_16x16x32_bf16 v[64:67], v[204:207], v[164:167], v[64:67]
	s_waitcnt lgkmcnt(7)
	v_mfma_f32_16x16x32_bf16 v[60:63], v[200:203], v[168:171], v[60:63]
	v_mfma_f32_16x16x32_bf16 v[56:59], v[204:207], v[168:171], v[56:59]
	s_waitcnt lgkmcnt(6)
	v_mfma_f32_16x16x32_bf16 v[52:55], v[200:203], v[172:175], v[52:55]
	v_mfma_f32_16x16x32_bf16 v[48:51], v[204:207], v[172:175], v[48:51]
	s_waitcnt lgkmcnt(5)
	v_mfma_f32_16x16x32_bf16 v[44:47], v[200:203], v[176:179], v[44:47]
	v_mfma_f32_16x16x32_bf16 v[40:43], v[204:207], v[176:179], v[40:43]
	s_waitcnt lgkmcnt(4)
	v_mfma_f32_16x16x32_bf16 v[36:39], v[200:203], v[180:183], v[36:39]
	v_mfma_f32_16x16x32_bf16 v[32:35], v[204:207], v[180:183], v[32:35]
	s_waitcnt lgkmcnt(3)
	v_mfma_f32_16x16x32_bf16 v[28:31], v[200:203], v[184:187], v[28:31]
	v_mfma_f32_16x16x32_bf16 v[24:27], v[204:207], v[184:187], v[24:27]
	s_waitcnt lgkmcnt(2)
	v_mfma_f32_16x16x32_bf16 v[20:23], v[200:203], v[188:191], v[20:23]
	v_mfma_f32_16x16x32_bf16 v[16:19], v[204:207], v[188:191], v[16:19]
	s_waitcnt lgkmcnt(1)
	v_mfma_f32_16x16x32_bf16 v[12:15], v[200:203], v[192:195], v[12:15]
	v_mfma_f32_16x16x32_bf16 v[8:11], v[204:207], v[192:195], v[8:11]
	s_waitcnt lgkmcnt(0)
	v_mfma_f32_16x16x32_bf16 v[4:7], v[200:203], v[196:199], v[4:7]
	v_mfma_f32_16x16x32_bf16 v[0:3], v[204:207], v[196:199], v[0:3]
	s_add_u32 s99, s99, 0xd000
	s_cmp_eq_u32 s99, 0x27000
	s_cselect_b32 s99, 0, s99
	s_cmp_eq_u32 s101, 0
	s_cbranch_scc1 .Lgxo_qcp
	s_add_u32 s12, s99, 0x1a000
	s_cmp_ge_u32 s12, 0x27000
	s_cselect_b32 s13, 0x27000, 0
	s_sub_u32 s12, s12, s13
	v_add_u32_e32 v168, s12, v98
	s_mov_b64 s[12:13], 0
	v_lshl_add_u64 v[94:95], v[102:103], 0, s[12:13]
	v_lshl_add_u64 v[186:187], v[104:105], 0, s[12:13]
	v_readfirstlane_b32 s98, v168
.Lgxo_qcp:
	v_add_u32_e32 v164, s99, v97
	v_add_u32_e32 v165, s99, v99
	v_add_u32_e32 v192, v164, v101
	v_add_u32_e32 v196, v165, v101
	v_add_u32_e32 v164, v164, v100
	v_add_u32_e32 v165, v165, v100
	s_cmp_eq_u32 s101, 0
	s_cbranch_scc1 .Lgxo_qcw0
	s_waitcnt vmcnt(6)
	s_branch .Lgxo_qcw1

.Lgxo_qcw1:
	s_waitcnt lgkmcnt(0)
	s_barrier
	s_cmp_eq_u32 s101, 0
	s_cbranch_scc1 .Lgxo_qcb
	v_lshl_add_u64 v[188:189], v[94:95], 0, s[78:79]
	s_mov_b32 m0, s98
	s_nop 0
	global_load_lds_dwordx4 v[188:189], off
	v_lshl_add_u64 v[188:189], v[94:95], 0, s[80:81]
	s_add_u32 m0, s98, 0x2000
	s_nop 0
	global_load_lds_dwordx4 v[188:189], off
	s_mov_b64 s[12:13], 0x360080
	v_lshl_add_u64 v[188:189], v[186:187], 0, s[12:13]
	s_add_u32 m0, s98, 0x5000
	s_nop 0
	global_load_lds_dwordx4 v[188:189], off
	s_mov_b64 s[12:13], 0x380080
	v_lshl_add_u64 v[188:189], v[186:187], 0, s[12:13]
	s_add_u32 m0, s98, 0x7000
	s_nop 0
	global_load_lds_dwordx4 v[188:189], off
	s_mov_b64 s[12:13], 0x3a0080
	v_lshl_add_u64 v[188:189], v[186:187], 0, s[12:13]
	s_add_u32 m0, s98, 0x9000
	s_nop 0
	global_load_lds_dwordx4 v[188:189], off
	s_mov_b64 s[12:13], 0x3c0080
	v_lshl_add_u64 v[188:189], v[186:187], 0, s[12:13]
	s_add_u32 m0, s98, 0xb000
	s_nop 0
	global_load_lds_dwordx4 v[188:189], off
.Lgxo_qcb:
	ds_read_b128 v[152:155], v164 offset:20480
	ds_read_b128 v[156:159], v164 offset:22528
	ds_read_b128 v[108:111], v165
	ds_read_b128 v[112:115], v165 offset:2048
	ds_read_b128 v[116:119], v165 offset:4096
	ds_read_b128 v[120:123], v165 offset:6144
	ds_read_b128 v[124:127], v165 offset:8192
	ds_read_b128 v[132:135], v165 offset:10240
	ds_read_b128 v[136:139], v165 offset:12288
	ds_read_b128 v[140:143], v165 offset:14336
	ds_read_b128 v[144:147], v165 offset:16384
	ds_read_b128 v[148:151], v165 offset:18432
	s_waitcnt lgkmcnt(9)
	v_mfma_f32_16x16x32_bf16 v[76:79], v[152:155], v[108:111], v[76:79]
	v_mfma_f32_16x16x32_bf16 v[72:75], v[156:159], v[108:111], v[72:75]
	ds_read_b128 v[200:203], v192 offset:20480
	s_waitcnt lgkmcnt(9)
	v_mfma_f32_16x16x32_bf16 v[68:71], v[152:155], v[112:115], v[68:71]
	v_mfma_f32_16x16x32_bf16 v[64:67], v[156:159], v[112:115], v[64:67]
	ds_read_b128 v[204:207], v192 offset:22528
	s_waitcnt lgkmcnt(9)
	v_mfma_f32_16x16x32_bf16 v[60:63], v[152:155], v[116:119], v[60:63]
	v_mfma_f32_16x16x32_bf16 v[56:59], v[156:159], v[116:119], v[56:59]
	ds_read_b128 v[160:163], v196
	s_waitcnt lgkmcnt(9)
	v_mfma_f32_16x16x32_bf16 v[52:55], v[152:155], v[120:123], v[52:55]
	v_mfma_f32_16x16x32_bf16 v[48:51], v[156:159], v[120:123], v[48:51]
	ds_read_b128 v[164:167], v196 offset:2048
	s_waitcnt lgkmcnt(9)
	v_mfma_f32_16x16x32_bf16 v[44:47], v[152:155], v[124:127], v[44:47]
	v_mfma_f32_16x16x32_bf16 v[40:43], v[156:159], v[124:127], v[40:43]
	ds_read_b128 v[168:171], v196 offset:4096
	s_waitcnt lgkmcnt(9)
	v_mfma_f32_16x16x32_bf16 v[36:39], v[152:155], v[132:135], v[36:39]
	v_mfma_f32_16x16x32_bf16 v[32:35], v[156:159], v[132:135], v[32:35]
	ds_read_b128 v[172:175], v196 offset:6144
	s_waitcnt lgkmcnt(9)
	v_mfma_f32_16x16x32_bf16 v[28:31], v[152:155], v[136:139], v[28:31]
	v_mfma_f32_16x16x32_bf16 v[24:27], v[156:159], v[136:139], v[24:27]
	ds_read_b128 v[176:179], v196 offset:8192
	s_waitcnt lgkmcnt(9)
	v_mfma_f32_16x16x32_bf16 v[20:23], v[152:155], v[140:143], v[20:23]
	v_mfma_f32_16x16x32_bf16 v[16:19], v[156:159], v[140:143], v[16:19]
	ds_read_b128 v[180:183], v196 offset:10240
	s_waitcnt lgkmcnt(9)
	v_mfma_f32_16x16x32_bf16 v[12:15], v[152:155], v[144:147], v[12:15]
	v_mfma_f32_16x16x32_bf16 v[8:11], v[156:159], v[144:147], v[8:11]
	ds_read_b128 v[184:187], v196 offset:12288
	s_waitcnt lgkmcnt(9)
	v_mfma_f32_16x16x32_bf16 v[4:7], v[152:155], v[148:151], v[4:7]
	v_mfma_f32_16x16x32_bf16 v[0:3], v[156:159], v[148:151], v[0:3]
	ds_read_b128 v[188:191], v196 offset:14336
	ds_read_b128 v[192:195], v196 offset:16384
	ds_read_b128 v[196:199], v196 offset:18432
	s_waitcnt lgkmcnt(9)
	v_mfma_f32_16x16x32_bf16 v[76:79], v[200:203], v[160:163], v[76:79]
	v_mfma_f32_16x16x32_bf16 v[72:75], v[204:207], v[160:163], v[72:75]
	s_waitcnt lgkmcnt(8)
	v_mfma_f32_16x16x32_bf16 v[68:71], v[200:203], v[164:167], v[68:71]
	v_mfma_f32_16x16x32_bf16 v[64:67], v[204:207], v[164:167], v[64:67]
	s_waitcnt lgkmcnt(7)
	v_mfma_f32_16x16x32_bf16 v[60:63], v[200:203], v[168:171], v[60:63]
	v_mfma_f32_16x16x32_bf16 v[56:59], v[204:207], v[168:171], v[56:59]
	s_waitcnt lgkmcnt(6)
	v_mfma_f32_16x16x32_bf16 v[52:55], v[200:203], v[172:175], v[52:55]
	v_mfma_f32_16x16x32_bf16 v[48:51], v[204:207], v[172:175], v[48:51]
	s_waitcnt lgkmcnt(5)
	v_mfma_f32_16x16x32_bf16 v[44:47], v[200:203], v[176:179], v[44:47]
	v_mfma_f32_16x16x32_bf16 v[40:43], v[204:207], v[176:179], v[40:43]
	s_waitcnt lgkmcnt(4)
	v_mfma_f32_16x16x32_bf16 v[36:39], v[200:203], v[180:183], v[36:39]
	v_mfma_f32_16x16x32_bf16 v[32:35], v[204:207], v[180:183], v[32:35]
	s_waitcnt lgkmcnt(3)
	v_mfma_f32_16x16x32_bf16 v[28:31], v[200:203], v[184:187], v[28:31]
	v_mfma_f32_16x16x32_bf16 v[24:27], v[204:207], v[184:187], v[24:27]
	s_waitcnt lgkmcnt(2)
	v_mfma_f32_16x16x32_bf16 v[20:23], v[200:203], v[188:191], v[20:23]
	v_mfma_f32_16x16x32_bf16 v[16:19], v[204:207], v[188:191], v[16:19]
	s_waitcnt lgkmcnt(1)
	v_mfma_f32_16x16x32_bf16 v[12:15], v[200:203], v[192:195], v[12:15]
	v_mfma_f32_16x16x32_bf16 v[8:11], v[204:207], v[192:195], v[8:11]
	s_waitcnt lgkmcnt(0)
	v_mfma_f32_16x16x32_bf16 v[4:7], v[200:203], v[196:199], v[4:7]
	v_mfma_f32_16x16x32_bf16 v[0:3], v[204:207], v[196:199], v[0:3]
	s_add_u32 s99, s99, 0xd000
	s_cmp_eq_u32 s99, 0x27000
	s_cselect_b32 s99, 0, s99
	s_branch .Lg160o_epi

.LBB0_830:
	s_mul_hi_i32 s42, s48, 0x2e8ba2e9
	s_lshr_b32 s43, s42, 31
	s_ashr_i32 s42, s42, 5
	s_add_i32 s42, s42, s43
	s_lshl_b32 s42, s42, 3
	s_and_b32 s43, s48, 7
	s_or_b32 s62, s42, s43
	s_ashr_i32 s42, s48, 3
	s_mul_hi_i32 s43, s42, 0x2e8ba2e9
	s_lshr_b32 s48, s43, 31
	s_ashr_i32 s43, s43, 2
	s_add_i32 s43, s43, s48
	s_mul_i32 s43, s43, 22
	s_sub_i32 s58, s42, s43
	s_ashr_i32 s63, s62, 31
	s_ashr_i32 s59, s58, 31
	s_lshl_b64 s[42:43], s[62:63], 19
	s_lshl_b64 s[48:49], s[58:59], 19
	v_readfirstlane_b32 s59, v178
	v_add_u32_e32 v4, 0x8000, v178
	v_lshl_add_u64 v[0:1], v[132:133], 0, s[42:43]
	s_mov_b32 m0, s59
	v_readfirstlane_b32 s59, v4
	v_add_u32_e32 v6, 0x2000, v178
	v_lshl_add_u64 v[2:3], v[134:135], 0, s[48:49]
	global_load_lds_dwordx4 v[0:1], off
	s_mov_b32 m0, s59
	s_mov_b64 s[96:97], 0x20000
	v_readfirstlane_b32 s59, v6
	v_add_u32_e32 v6, 0xa000, v178
	global_load_lds_dwordx4 v[2:3], off
	v_lshl_add_u64 v[4:5], v[0:1], 0, s[96:97]
	s_mov_b32 m0, s59
	v_readfirstlane_b32 s59, v6
	v_add_u32_e32 v6, 0x4000, v178
	global_load_lds_dwordx4 v[4:5], off
	v_lshl_add_u64 v[4:5], v[2:3], 0, s[96:97]
	s_mov_b32 m0, s59
	v_readfirstlane_b32 s59, v6
	v_add_u32_e32 v6, 0xc000, v178
	global_load_lds_dwordx4 v[4:5], off
	v_lshl_add_u64 v[4:5], v[0:1], 0, s[74:75]
	s_mov_b32 m0, s59
	v_readfirstlane_b32 s59, v6
	global_load_lds_dwordx4 v[4:5], off
	v_lshl_add_u64 v[4:5], v[2:3], 0, s[74:75]
	s_mov_b32 m0, s59
	s_mov_b64 s[96:97], 0x60000
	global_load_lds_dwordx4 v[4:5], off
	v_add_u32_e32 v4, 0x6000, v178
	v_lshl_add_u64 v[0:1], v[0:1], 0, s[96:97]
	v_readfirstlane_b32 s59, v4
	s_mov_b32 m0, s59
	s_mov_b64 s[72:73], 0x20000
	global_load_lds_dwordx4 v[0:1], off
	v_lshl_add_u64 v[0:1], v[2:3], 0, s[96:97]
	v_add_u32_e32 v2, 0xe000, v178
	v_lshl_add_u64 v[174:175], v[170:171], 0, s[48:49]
	v_readfirstlane_b32 s59, v2
	s_mov_b32 m0, s59
	v_lshl_add_u64 v[176:177], v[172:173], 0, s[42:43]
	global_load_lds_dwordx4 v[0:1], off
	v_mov_b32_e32 v0, 0
	s_mov_b32 s42, 0
	s_mov_b64 s[96:97], 0
	v_mov_b32_e32 v1, v0
	v_mov_b32_e32 v2, v0
	v_mov_b32_e32 v3, v0
	v_mov_b32_e32 v4, v0
	v_mov_b32_e32 v5, v0
	v_mov_b32_e32 v6, v0
	v_mov_b32_e32 v7, v0
	v_mov_b32_e32 v8, v0
	v_mov_b32_e32 v9, v0
	v_mov_b32_e32 v10, v0
	v_mov_b32_e32 v11, v0
	v_mov_b32_e32 v12, v0
	v_mov_b32_e32 v13, v0
	v_mov_b32_e32 v14, v0
	v_mov_b32_e32 v15, v0
	v_mov_b32_e32 v16, v0
	v_mov_b32_e32 v17, v0
	v_mov_b32_e32 v18, v0
	v_mov_b32_e32 v19, v0
	v_mov_b32_e32 v20, v0
	v_mov_b32_e32 v21, v0
	v_mov_b32_e32 v22, v0
	v_mov_b32_e32 v23, v0
	v_mov_b32_e32 v24, v0
	v_mov_b32_e32 v25, v0
	v_mov_b32_e32 v26, v0
	v_mov_b32_e32 v27, v0
	v_mov_b32_e32 v28, v0
	v_mov_b32_e32 v29, v0
	v_mov_b32_e32 v30, v0
	v_mov_b32_e32 v31, v0
	v_mov_b32_e32 v32, v0
	v_mov_b32_e32 v33, v0
	v_mov_b32_e32 v34, v0
	v_mov_b32_e32 v35, v0
	v_mov_b32_e32 v36, v0
	v_mov_b32_e32 v37, v0
	v_mov_b32_e32 v38, v0
	v_mov_b32_e32 v39, v0
	v_mov_b32_e32 v40, v0
	v_mov_b32_e32 v41, v0
	v_mov_b32_e32 v42, v0
	v_mov_b32_e32 v43, v0
	v_mov_b32_e32 v44, v0
	v_mov_b32_e32 v45, v0
	v_mov_b32_e32 v46, v0
	v_mov_b32_e32 v47, v0
	v_mov_b32_e32 v48, v0
	v_mov_b32_e32 v49, v0
	v_mov_b32_e32 v50, v0
	v_mov_b32_e32 v51, v0
	v_mov_b32_e32 v52, v0
	v_mov_b32_e32 v53, v0
	v_mov_b32_e32 v54, v0
	v_mov_b32_e32 v55, v0
	v_mov_b32_e32 v56, v0
	v_mov_b32_e32 v57, v0
	v_mov_b32_e32 v58, v0
	v_mov_b32_e32 v59, v0
	v_mov_b32_e32 v60, v0
	v_mov_b32_e32 v61, v0
	v_mov_b32_e32 v62, v0
	v_mov_b32_e32 v63, v0
	v_mov_b32_e32 v64, v0
	v_mov_b32_e32 v65, v0
	v_mov_b32_e32 v66, v0
	v_mov_b32_e32 v67, v0
	v_mov_b32_e32 v68, v0
	v_mov_b32_e32 v69, v0
	v_mov_b32_e32 v70, v0
	v_mov_b32_e32 v71, v0
	v_mov_b32_e32 v72, v0
	v_mov_b32_e32 v73, v0
	v_mov_b32_e32 v74, v0
	v_mov_b32_e32 v75, v0
	v_mov_b32_e32 v76, v0
	v_mov_b32_e32 v77, v0
	v_mov_b32_e32 v78, v0
	v_mov_b32_e32 v79, v0
	v_mov_b32_e32 v80, v0
	v_mov_b32_e32 v81, v0
	v_mov_b32_e32 v82, v0
	v_mov_b32_e32 v83, v0
	v_mov_b32_e32 v84, v0
	v_mov_b32_e32 v85, v0
	v_mov_b32_e32 v86, v0
	v_mov_b32_e32 v87, v0
	v_mov_b32_e32 v88, v0
	v_mov_b32_e32 v89, v0
	v_mov_b32_e32 v90, v0
	v_mov_b32_e32 v91, v0
	v_mov_b32_e32 v92, v0
	v_mov_b32_e32 v93, v0
	v_mov_b32_e32 v94, v0
	v_mov_b32_e32 v95, v0
	v_mov_b32_e32 v96, v0
	v_mov_b32_e32 v97, v0
	v_mov_b32_e32 v98, v0
	v_mov_b32_e32 v99, v0
	v_mov_b32_e32 v100, v0
	v_mov_b32_e32 v101, v0
	v_mov_b32_e32 v102, v0
	v_mov_b32_e32 v103, v0
	v_mov_b32_e32 v104, v0
	v_mov_b32_e32 v105, v0
	v_mov_b32_e32 v106, v0
	v_mov_b32_e32 v107, v0
	v_mov_b32_e32 v108, v0
	v_mov_b32_e32 v109, v0
	v_mov_b32_e32 v110, v0
	v_mov_b32_e32 v111, v0
	v_mov_b32_e32 v112, v0
	v_mov_b32_e32 v113, v0
	v_mov_b32_e32 v114, v0
	v_mov_b32_e32 v115, v0
	v_mov_b32_e32 v116, v0
	v_mov_b32_e32 v117, v0
	v_mov_b32_e32 v118, v0
	v_mov_b32_e32 v119, v0
	v_mov_b32_e32 v120, v0
	v_mov_b32_e32 v121, v0
	v_mov_b32_e32 v122, v0
	v_mov_b32_e32 v123, v0
	v_mov_b32_e32 v124, v0
	v_mov_b32_e32 v125, v0
	v_mov_b32_e32 v126, v0
	v_mov_b32_e32 v127, v0
	v_readfirstlane_b32 s99, v178
	v_add_u32_e32 v229, 0x10000, v178
	s_nop 0
	v_readfirstlane_b32 s98, v229
	s_nop 3
	s_add_u32 s48, s96, s78
	s_addc_u32 s49, s97, s79
	v_lshl_add_u64 v[220:221], v[176:177], 0, s[48:49]
	s_mov_b32 m0, s98
	s_nop 0
	global_load_lds_dwordx4 v[220:221], off
	s_add_u32 s48, s96, 0x560080
	s_addc_u32 s49, s97, 0
	v_lshl_add_u64 v[220:221], v[174:175], 0, s[48:49]
	s_add_u32 m0, s98, 0x8000
	s_nop 0
	global_load_lds_dwordx4 v[220:221], off
	s_add_u32 s48, s96, s80
	s_addc_u32 s49, s97, s81
	v_lshl_add_u64 v[220:221], v[176:177], 0, s[48:49]
	s_add_u32 m0, s98, 0x2000
	s_nop 0
	global_load_lds_dwordx4 v[220:221], off
	s_add_u32 s48, s96, 0x580080
	s_addc_u32 s49, s97, 0
	v_lshl_add_u64 v[220:221], v[174:175], 0, s[48:49]
	s_add_u32 m0, s98, 0xa000
	s_nop 0
	global_load_lds_dwordx4 v[220:221], off
	s_add_u32 s48, s96, s82
	s_addc_u32 s49, s97, s83
	v_lshl_add_u64 v[220:221], v[176:177], 0, s[48:49]
	s_add_u32 m0, s98, 0x4000
	s_nop 0
	global_load_lds_dwordx4 v[220:221], off
	s_add_u32 s48, s96, 0x5a0080
	s_addc_u32 s49, s97, 0
	v_lshl_add_u64 v[220:221], v[174:175], 0, s[48:49]
	s_add_u32 m0, s98, 0xc000
	s_nop 0
	global_load_lds_dwordx4 v[220:221], off
	s_add_u32 s48, s96, 0x2c91080
	s_addc_u32 s49, s97, 0
	v_lshl_add_u64 v[220:221], v[176:177], 0, s[48:49]
	s_add_u32 m0, s98, 0x6000
	s_nop 0
	global_load_lds_dwordx4 v[220:221], off
	s_add_u32 s48, s96, 0x5c0080
	s_addc_u32 s49, s97, 0
	v_lshl_add_u64 v[220:221], v[174:175], 0, s[48:49]
	s_add_u32 m0, s98, 0xe000
	s_nop 0
	global_load_lds_dwordx4 v[220:221], off

.LBB0_971:
	s_or_b64 exec, exec, s[36:37]
	v_readlane_b32 s4, v254, 0
	v_readlane_b32 s5, v254, 1
	s_waitcnt lgkmcnt(0)
	s_barrier
	s_load_dwordx2 s[8:9], s[4:5], 0xe0
	v_mov_b32_e32 v4, v222
	s_waitcnt lgkmcnt(0)
	s_add_u32 s6, s8, 0x15831000
	s_addc_u32 s7, s9, 0
	v_readlane_b32 s4, v254, 19
	v_ashrrev_i32_e32 v2, 1, v4
	v_and_b32_e32 v96, 15, v4
	v_readlane_b32 s5, v254, 20
	s_add_u32 s10, s8, s4
	v_lshrrev_b32_e32 v5, 4, v4
	v_and_b32_e32 v9, 0xffffffe0, v2
	s_addc_u32 s11, s9, s5
	v_xor_b32_e32 v6, v5, v4
	v_or_b32_e32 v2, v9, v96
	v_ashrrev_i32_e32 v7, 3, v4
	v_mov_b64_e32 v[0:1], s[10:11]
	v_lshlrev_b32_e32 v97, 7, v2
	v_mov_b64_e32 v[2:3], s[8:9]
	v_lshlrev_b32_e32 v6, 4, v6
	v_mad_i64_i32 v[0:1], s[4:5], v7, s88, v[0:1]
	v_mad_i64_i32 v[2:3], s[4:5], v7, s88, v[2:3]
	v_and_b32_e32 v128, 0x70, v6
	v_lshl_add_u64 v[2:3], v[2:3], 0, v[128:129]
	s_mov_b64 s[4:5], 0x7c31000
	v_lshl_add_u64 v[80:81], v[2:3], 0, s[4:5]
	v_lshl_add_u64 v[0:1], v[0:1], 0, v[128:129]
	s_mov_b64 s[4:5], 0x1060000
	v_bfe_u32 v8, v4, 1, 3
	v_lshl_add_u64 v[82:83], v[0:1], 0, s[4:5]
	v_bfe_u32 v0, v4, 4, 2
	v_bitop3_b32 v0, v0, v8, 4 bitop3:0x36
	v_lshlrev_b32_e32 v99, 7, v96
	v_bitop3_b32 v1, v5, v8, 3 bitop3:0x6c
	v_lshlrev_b32_e32 v101, 4, v0
	v_lshrrev_b32_e32 v0, 2, v4
	v_lshlrev_b32_e32 v100, 4, v1
	v_and_or_b32 v84, v0, 12, v9
	v_add_u32_e32 v0, 0, v99
	v_add_u32_e32 v1, 0, v97
	v_add_u32_e32 v102, 0xd000, v1
	v_add_u32_e32 v103, v0, v100
	v_add_u32_e32 v105, v0, v101
	v_mad_i64_i32 v[0:1], s[12:13], v7, s88, 0
	v_bitop3_b32 v2, v5, 7, v4 bitop3:0x48
	s_movk_i32 s4, 0x100
	v_lshl_or_b32 v0, v2, 4, v0
	v_cmp_gt_i32_e64 s[4:5], s4, v4
	v_lshl_add_u32 v98, v4, 4, 0
	v_ashrrev_i32_e32 v85, 31, v9
	v_add_u32_e32 v104, 0xd000, v103
	v_add_u32_e32 v106, 0xd000, v105
	v_lshl_add_u64 v[86:87], s[8:9], 0, v[0:1]
	v_lshl_add_u64 v[88:89], s[10:11], 0, v[0:1]
	s_mov_b32 s99, 0
	s_mov_b32 s100, 0
	s_mov_b32 s14, 0
	s_branch .LBB0_974

.LBB0_979:
	s_ashr_i32 s8, s10, 2
	s_and_b32 s11, s8, -8
	s_and_b32 s12, s10, 7
	s_or_b32 s15, s11, s12
	s_bfe_u32 s9, s10, 0x20003
	s_lshl_b32 s8, s10, 5
	s_and_b32 s8, s8, 0x300
	v_mad_i64_i32 v[90:91], s[16:17], s15, v227, v[86:87]
	v_mad_u64_u32 v[92:93], s[16:17], s9, v228, v[88:89]
	s_add_i32 s11, s14, 1
	s_lshl_b32 s12, s11, 8
	s_add_i32 s12, s12, s89
	s_mul_i32 s13, s11, s60
	s_add_i32 s13, s13, s2
	s_cmp_eq_u64 s[64:65], 0
	s_cselect_b32 s12, s12, s13
	s_cmpk_le_i32 s12, 0x3ff
	s_cselect_b32 s101, 1, 0
	s_ashr_i32 s13, s12, 2
	s_and_b32 s13, s13, -8
	s_and_b32 s11, s12, 7
	s_or_b32 s13, s13, s11
	v_mad_i64_i32 v[102:103], s[16:17], s13, v227, v[86:87]
	s_bfe_u32 s11, s12, 0x20003
	v_mad_u64_u32 v[104:105], s[16:17], s11, v228, v[88:89]
	s_mov_b64 s[10:11], 0
	v_mov_b32_e32 v0, 0
	v_mov_b32_e32 v1, v0
	v_mov_b32_e32 v2, v0
	v_mov_b32_e32 v3, v0
	v_mov_b32_e32 v4, v0
	v_mov_b32_e32 v5, v0
	v_mov_b32_e32 v6, v0
	v_mov_b32_e32 v7, v0
	v_mov_b32_e32 v8, v0
	v_mov_b32_e32 v9, v0
	v_mov_b32_e32 v10, v0
	v_mov_b32_e32 v11, v0
	v_mov_b32_e32 v12, v0
	v_mov_b32_e32 v13, v0
	v_mov_b32_e32 v14, v0
	v_mov_b32_e32 v15, v0
	v_mov_b32_e32 v16, v0
	v_mov_b32_e32 v17, v0
	v_mov_b32_e32 v18, v0
	v_mov_b32_e32 v19, v0
	v_mov_b32_e32 v20, v0
	v_mov_b32_e32 v21, v0
	v_mov_b32_e32 v22, v0
	v_mov_b32_e32 v23, v0
	v_mov_b32_e32 v24, v0
	v_mov_b32_e32 v25, v0
	v_mov_b32_e32 v26, v0
	v_mov_b32_e32 v27, v0
	v_mov_b32_e32 v28, v0
	v_mov_b32_e32 v29, v0
	v_mov_b32_e32 v30, v0
	v_mov_b32_e32 v31, v0
	v_mov_b32_e32 v32, v0
	v_mov_b32_e32 v33, v0
	v_mov_b32_e32 v34, v0
	v_mov_b32_e32 v35, v0
	v_mov_b32_e32 v36, v0
	v_mov_b32_e32 v37, v0
	v_mov_b32_e32 v38, v0
	v_mov_b32_e32 v39, v0
	v_mov_b32_e32 v40, v0
	v_mov_b32_e32 v41, v0
	v_mov_b32_e32 v42, v0
	v_mov_b32_e32 v43, v0
	v_mov_b32_e32 v44, v0
	v_mov_b32_e32 v45, v0
	v_mov_b32_e32 v46, v0
	v_mov_b32_e32 v47, v0
	v_mov_b32_e32 v48, v0
	v_mov_b32_e32 v49, v0
	v_mov_b32_e32 v50, v0
	v_mov_b32_e32 v51, v0
	v_mov_b32_e32 v52, v0
	v_mov_b32_e32 v53, v0
	v_mov_b32_e32 v54, v0
	v_mov_b32_e32 v55, v0
	v_mov_b32_e32 v56, v0
	v_mov_b32_e32 v57, v0
	v_mov_b32_e32 v58, v0
	v_mov_b32_e32 v59, v0
	v_mov_b32_e32 v60, v0
	v_mov_b32_e32 v61, v0
	v_mov_b32_e32 v62, v0
	v_mov_b32_e32 v63, v0
	v_mov_b32_e32 v64, v0
	v_mov_b32_e32 v65, v0
	v_mov_b32_e32 v66, v0
	v_mov_b32_e32 v67, v0
	v_mov_b32_e32 v68, v0
	v_mov_b32_e32 v69, v0
	v_mov_b32_e32 v70, v0
	v_mov_b32_e32 v71, v0
	v_mov_b32_e32 v72, v0
	v_mov_b32_e32 v73, v0
	v_mov_b32_e32 v74, v0
	v_mov_b32_e32 v75, v0
	v_mov_b32_e32 v76, v0
	v_mov_b32_e32 v77, v0
	v_mov_b32_e32 v78, v0
	v_mov_b32_e32 v79, v0
	s_cmp_eq_u32 s100, 0
	s_cbranch_scc0 .Lgxd_go
	s_add_u32 s12, s99, 0x0
	s_cmp_ge_u32 s12, 0x27000
	s_cselect_b32 s13, 0x27000, 0
	s_sub_u32 s12, s12, s13
	v_add_u32_e32 v168, s12, v98
	s_mov_b32 s12, 0xffffff80
	s_mov_b32 s13, -1
	v_lshl_add_u64 v[94:95], v[90:91], 0, s[12:13]
	v_lshl_add_u64 v[186:187], v[92:93], 0, s[12:13]
	v_readfirstlane_b32 s98, v168
	s_mov_b64 s[12:13], 0x7c31080
	v_lshl_add_u64 v[188:189], v[94:95], 0, s[12:13]
	s_mov_b32 m0, s98
	s_nop 0
	global_load_lds_dwordx4 v[188:189], off
	s_mov_b64 s[12:13], 0x7c89080
	v_lshl_add_u64 v[188:189], v[94:95], 0, s[12:13]
	s_add_u32 m0, s98, 0x2000
	s_nop 0
	global_load_lds_dwordx4 v[188:189], off
	s_cmp_eq_u64 s[4:5], 0
	s_cbranch_scc1 .Lgxd_ps0
	s_mov_b64 s[12:13], 0x7ce1080
	v_lshl_add_u64 v[188:189], v[94:95], 0, s[12:13]
	s_add_u32 m0, s98, 0x4000
	s_nop 0
	global_load_lds_dwordx4 v[188:189], off
.Lgxd_ps0:
	s_mov_b64 s[12:13], 0x1060080
	v_lshl_add_u64 v[188:189], v[186:187], 0, s[12:13]
	s_add_u32 m0, s98, 0x5000
	s_nop 0
	global_load_lds_dwordx4 v[188:189], off
	s_mov_b64 s[12:13], 0x10b8080
	v_lshl_add_u64 v[188:189], v[186:187], 0, s[12:13]
	s_add_u32 m0, s98, 0x7000
	s_nop 0
	global_load_lds_dwordx4 v[188:189], off
	s_mov_b64 s[12:13], 0x1110080
	v_lshl_add_u64 v[188:189], v[186:187], 0, s[12:13]
	s_add_u32 m0, s98, 0x9000
	s_nop 0
	global_load_lds_dwordx4 v[188:189], off
	s_mov_b64 s[12:13], 0x1168080
	v_lshl_add_u64 v[188:189], v[186:187], 0, s[12:13]
	s_add_u32 m0, s98, 0xb000
	s_nop 0
	global_load_lds_dwordx4 v[188:189], off
	s_add_u32 s12, s99, 0xd000
	s_cmp_ge_u32 s12, 0x27000
	s_cselect_b32 s13, 0x27000, 0
	s_sub_u32 s12, s12, s13
	v_add_u32_e32 v168, s12, v98
	s_mov_b64 s[12:13], 0
	v_lshl_add_u64 v[94:95], v[90:91], 0, s[12:13]
	v_lshl_add_u64 v[186:187], v[92:93], 0, s[12:13]
	v_readfirstlane_b32 s98, v168
	s_mov_b64 s[12:13], 0x7c31080
	v_lshl_add_u64 v[188:189], v[94:95], 0, s[12:13]
	s_mov_b32 m0, s98
	s_nop 0
	global_load_lds_dwordx4 v[188:189], off
	s_mov_b64 s[12:13], 0x7c89080
	v_lshl_add_u64 v[188:189], v[94:95], 0, s[12:13]
	s_add_u32 m0, s98, 0x2000
	s_nop 0
	global_load_lds_dwordx4 v[188:189], off
	s_cmp_eq_u64 s[4:5], 0
	s_cbranch_scc1 .Lgxd_ps1
	s_mov_b64 s[12:13], 0x7ce1080
	v_lshl_add_u64 v[188:189], v[94:95], 0, s[12:13]
	s_add_u32 m0, s98, 0x4000
	s_nop 0
	global_load_lds_dwordx4 v[188:189], off
.Lgxd_ps1:
	s_mov_b64 s[12:13], 0x1060080
	v_lshl_add_u64 v[188:189], v[186:187], 0, s[12:13]
	s_add_u32 m0, s98, 0x5000
	s_nop 0
	global_load_lds_dwordx4 v[188:189], off
	s_mov_b64 s[12:13], 0x10b8080
	v_lshl_add_u64 v[188:189], v[186:187], 0, s[12:13]
	s_add_u32 m0, s98, 0x7000
	s_nop 0
	global_load_lds_dwordx4 v[188:189], off
	s_mov_b64 s[12:13], 0x1110080
	v_lshl_add_u64 v[188:189], v[186:187], 0, s[12:13]
	s_add_u32 m0, s98, 0x9000
	s_nop 0
	global_load_lds_dwordx4 v[188:189], off
	s_mov_b64 s[12:13], 0x1168080
	v_lshl_add_u64 v[188:189], v[186:187], 0, s[12:13]
	s_add_u32 m0, s98, 0xb000
	s_nop 0
	global_load_lds_dwordx4 v[188:189], off

.Lgxd_p:
	v_add_u32_e32 v164, s99, v97
	v_add_u32_e32 v165, s99, v99
	v_add_u32_e32 v192, v164, v101
	v_add_u32_e32 v196, v165, v101
	v_add_u32_e32 v164, v164, v100
	v_add_u32_e32 v165, v165, v100
	s_waitcnt vmcnt(7) lgkmcnt(0)
	s_barrier
	ds_read_b128 v[152:155], v164 offset:20480
	ds_read_b128 v[156:159], v164 offset:22528
	ds_read_b128 v[108:111], v165
	ds_read_b128 v[112:115], v165 offset:2048
	ds_read_b128 v[116:119], v165 offset:4096
	ds_read_b128 v[120:123], v165 offset:6144
	ds_read_b128 v[124:127], v165 offset:8192
	ds_read_b128 v[132:135], v165 offset:10240
	ds_read_b128 v[136:139], v165 offset:12288
	ds_read_b128 v[140:143], v165 offset:14336
	ds_read_b128 v[144:147], v165 offset:16384
	ds_read_b128 v[148:151], v165 offset:18432
	s_waitcnt lgkmcnt(9)
	v_mfma_f32_16x16x32_bf16 v[76:79], v[152:155], v[108:111], v[76:79]
	v_mfma_f32_16x16x32_bf16 v[72:75], v[156:159], v[108:111], v[72:75]
	ds_read_b128 v[200:203], v192 offset:20480
	s_waitcnt lgkmcnt(9)
	v_mfma_f32_16x16x32_bf16 v[68:71], v[152:155], v[112:115], v[68:71]
	v_mfma_f32_16x16x32_bf16 v[64:67], v[156:159], v[112:115], v[64:67]
	ds_read_b128 v[204:207], v192 offset:22528
	s_waitcnt lgkmcnt(9)
	v_mfma_f32_16x16x32_bf16 v[60:63], v[152:155], v[116:119], v[60:63]
	v_mfma_f32_16x16x32_bf16 v[56:59], v[156:159], v[116:119], v[56:59]
	ds_read_b128 v[160:163], v196
	s_waitcnt lgkmcnt(9)
	v_mfma_f32_16x16x32_bf16 v[52:55], v[152:155], v[120:123], v[52:55]
	v_mfma_f32_16x16x32_bf16 v[48:51], v[156:159], v[120:123], v[48:51]
	ds_read_b128 v[164:167], v196 offset:2048
	s_waitcnt lgkmcnt(9)
	v_mfma_f32_16x16x32_bf16 v[44:47], v[152:155], v[124:127], v[44:47]
	v_mfma_f32_16x16x32_bf16 v[40:43], v[156:159], v[124:127], v[40:43]
	ds_read_b128 v[168:171], v196 offset:4096
	s_waitcnt lgkmcnt(9)
	v_mfma_f32_16x16x32_bf16 v[36:39], v[152:155], v[132:135], v[36:39]
	v_mfma_f32_16x16x32_bf16 v[32:35], v[156:159], v[132:135], v[32:35]
	ds_read_b128 v[172:175], v196 offset:6144
	s_waitcnt lgkmcnt(9)
	v_mfma_f32_16x16x32_bf16 v[28:31], v[152:155], v[136:139], v[28:31]
	v_mfma_f32_16x16x32_bf16 v[24:27], v[156:159], v[136:139], v[24:27]
	ds_read_b128 v[176:179], v196 offset:8192
	s_waitcnt lgkmcnt(9)
	v_mfma_f32_16x16x32_bf16 v[20:23], v[152:155], v[140:143], v[20:23]
	v_mfma_f32_16x16x32_bf16 v[16:19], v[156:159], v[140:143], v[16:19]
	ds_read_b128 v[180:183], v196 offset:10240
	s_waitcnt lgkmcnt(9)
	v_mfma_f32_16x16x32_bf16 v[12:15], v[152:155], v[144:147], v[12:15]
	v_mfma_f32_16x16x32_bf16 v[8:11], v[156:159], v[144:147], v[8:11]
	ds_read_b128 v[184:187], v196 offset:12288
	s_waitcnt lgkmcnt(9)
	v_mfma_f32_16x16x32_bf16 v[4:7], v[152:155], v[148:151], v[4:7]
	v_mfma_f32_16x16x32_bf16 v[0:3], v[156:159], v[148:151], v[0:3]
	ds_read_b128 v[188:191], v196 offset:14336
	ds_read_b128 v[192:195], v196 offset:16384
	ds_read_b128 v[196:199], v196 offset:18432
	s_waitcnt lgkmcnt(9)
	v_mfma_f32_16x16x32_bf16 v[76:79], v[200:203], v[160:163], v[76:79]
	v_mfma_f32_16x16x32_bf16 v[72:75], v[204:207], v[160:163], v[72:75]
	s_waitcnt lgkmcnt(8)
	v_mfma_f32_16x16x32_bf16 v[68:71], v[200:203], v[164:167], v[68:71]
	v_mfma_f32_16x16x32_bf16 v[64:67], v[204:207], v[164:167], v[64:67]
	s_waitcnt lgkmcnt(7)
	v_mfma_f32_16x16x32_bf16 v[60:63], v[200:203], v[168:171], v[60:63]
	v_mfma_f32_16x16x32_bf16 v[56:59], v[204:207], v[168:171], v[56:59]
	s_waitcnt lgkmcnt(6)
	v_mfma_f32_16x16x32_bf16 v[52:55], v[200:203], v[172:175], v[52:55]
	v_mfma_f32_16x16x32_bf16 v[48:51], v[204:207], v[172:175], v[48:51]
	s_waitcnt lgkmcnt(5)
	v_mfma_f32_16x16x32_bf16 v[44:47], v[200:203], v[176:179], v[44:47]
	v_mfma_f32_16x16x32_bf16 v[40:43], v[204:207], v[176:179], v[40:43]
	s_waitcnt lgkmcnt(4)
	v_mfma_f32_16x16x32_bf16 v[36:39], v[200:203], v[180:183], v[36:39]
	v_mfma_f32_16x16x32_bf16 v[32:35], v[204:207], v[180:183], v[32:35]
	s_waitcnt lgkmcnt(3)
	v_mfma_f32_16x16x32_bf16 v[28:31], v[200:203], v[184:187], v[28:31]
	v_mfma_f32_16x16x32_bf16 v[24:27], v[204:207], v[184:187], v[24:27]
	s_waitcnt lgkmcnt(2)
	v_mfma_f32_16x16x32_bf16 v[20:23], v[200:203], v[188:191], v[20:23]
	v_mfma_f32_16x16x32_bf16 v[16:19], v[204:207], v[188:191], v[16:19]
	s_waitcnt lgkmcnt(1)
	v_mfma_f32_16x16x32_bf16 v[12:15], v[200:203], v[192:195], v[12:15]
	v_mfma_f32_16x16x32_bf16 v[8:11], v[204:207], v[192:195], v[8:11]
	s_waitcnt lgkmcnt(0)
	v_mfma_f32_16x16x32_bf16 v[4:7], v[200:203], v[196:199], v[4:7]
	v_mfma_f32_16x16x32_bf16 v[0:3], v[204:207], v[196:199], v[0:3]
	s_add_u32 s12, s99, 0x1a000
	s_cmp_ge_u32 s12, 0x27000
	s_cselect_b32 s13, 0x27000, 0
	s_sub_u32 s12, s12, s13
	v_add_u32_e32 v168, s12, v98
	s_add_u32 s12, s10, 0x80
	s_addc_u32 s13, s11, 0
	v_lshl_add_u64 v[94:95], v[90:91], 0, s[12:13]
	v_lshl_add_u64 v[186:187], v[92:93], 0, s[12:13]
	v_readfirstlane_b32 s98, v168
	s_mov_b64 s[12:13], 0x7c31080
	v_lshl_add_u64 v[188:189], v[94:95], 0, s[12:13]
	s_mov_b32 m0, s98
	s_nop 0
	global_load_lds_dwordx4 v[188:189], off
	s_mov_b64 s[12:13], 0x7c89080
	v_lshl_add_u64 v[188:189], v[94:95], 0, s[12:13]
	s_add_u32 m0, s98, 0x2000
	s_nop 0
	global_load_lds_dwordx4 v[188:189], off
	s_mov_b64 s[12:13], 0x7ce1080
	v_lshl_add_u64 v[188:189], v[94:95], 0, s[12:13]
	s_add_u32 m0, s98, 0x4000
	s_nop 0
	global_load_lds_dwordx4 v[188:189], off
	s_mov_b64 s[12:13], 0x1060080
	v_lshl_add_u64 v[188:189], v[186:187], 0, s[12:13]
	s_add_u32 m0, s98, 0x5000
	s_nop 0
	global_load_lds_dwordx4 v[188:189], off
	s_mov_b64 s[12:13], 0x10b8080
	v_lshl_add_u64 v[188:189], v[186:187], 0, s[12:13]
	s_add_u32 m0, s98, 0x7000
	s_nop 0
	global_load_lds_dwordx4 v[188:189], off
	s_mov_b64 s[12:13], 0x1110080
	v_lshl_add_u64 v[188:189], v[186:187], 0, s[12:13]
	s_add_u32 m0, s98, 0x9000
	s_nop 0
	global_load_lds_dwordx4 v[188:189], off
	s_mov_b64 s[12:13], 0x1168080
	v_lshl_add_u64 v[188:189], v[186:187], 0, s[12:13]
	s_add_u32 m0, s98, 0xb000
	s_nop 0
	global_load_lds_dwordx4 v[188:189], off
	s_add_u32 s99, s99, 0xd000
	s_cmp_eq_u32 s99, 0x27000
	s_cselect_b32 s99, 0, s99
	s_add_u32 s10, s10, 0x80
	s_addc_u32 s11, s11, 0
	s_cmpk_eq_i32 s10, 0x1500
	s_cbranch_scc0 .Lgxd_p
	v_add_u32_e32 v164, s99, v97
	v_add_u32_e32 v165, s99, v99
	v_add_u32_e32 v192, v164, v101
	v_add_u32_e32 v196, v165, v101
	v_add_u32_e32 v164, v164, v100
	v_add_u32_e32 v165, v165, v100
	s_waitcnt vmcnt(7) lgkmcnt(0)
	s_barrier
	ds_read_b128 v[152:155], v164 offset:20480
	ds_read_b128 v[156:159], v164 offset:22528
	ds_read_b128 v[108:111], v165
	ds_read_b128 v[112:115], v165 offset:2048
	ds_read_b128 v[116:119], v165 offset:4096
	ds_read_b128 v[120:123], v165 offset:6144
	ds_read_b128 v[124:127], v165 offset:8192
	ds_read_b128 v[132:135], v165 offset:10240
	ds_read_b128 v[136:139], v165 offset:12288
	ds_read_b128 v[140:143], v165 offset:14336
	ds_read_b128 v[144:147], v165 offset:16384
	ds_read_b128 v[148:151], v165 offset:18432
	s_waitcnt lgkmcnt(9)
	v_mfma_f32_16x16x32_bf16 v[76:79], v[152:155], v[108:111], v[76:79]
	v_mfma_f32_16x16x32_bf16 v[72:75], v[156:159], v[108:111], v[72:75]
	ds_read_b128 v[200:203], v192 offset:20480
	s_waitcnt lgkmcnt(9)
	v_mfma_f32_16x16x32_bf16 v[68:71], v[152:155], v[112:115], v[68:71]
	v_mfma_f32_16x16x32_bf16 v[64:67], v[156:159], v[112:115], v[64:67]
	ds_read_b128 v[204:207], v192 offset:22528
	s_waitcnt lgkmcnt(9)
	v_mfma_f32_16x16x32_bf16 v[60:63], v[152:155], v[116:119], v[60:63]
	v_mfma_f32_16x16x32_bf16 v[56:59], v[156:159], v[116:119], v[56:59]
	ds_read_b128 v[160:163], v196
	s_waitcnt lgkmcnt(9)
	v_mfma_f32_16x16x32_bf16 v[52:55], v[152:155], v[120:123], v[52:55]
	v_mfma_f32_16x16x32_bf16 v[48:51], v[156:159], v[120:123], v[48:51]
	ds_read_b128 v[164:167], v196 offset:2048
	s_waitcnt lgkmcnt(9)
	v_mfma_f32_16x16x32_bf16 v[44:47], v[152:155], v[124:127], v[44:47]
	v_mfma_f32_16x16x32_bf16 v[40:43], v[156:159], v[124:127], v[40:43]
	ds_read_b128 v[168:171], v196 offset:4096
	s_waitcnt lgkmcnt(9)
	v_mfma_f32_16x16x32_bf16 v[36:39], v[152:155], v[132:135], v[36:39]
	v_mfma_f32_16x16x32_bf16 v[32:35], v[156:159], v[132:135], v[32:35]
	ds_read_b128 v[172:175], v196 offset:6144
	s_waitcnt lgkmcnt(9)
	v_mfma_f32_16x16x32_bf16 v[28:31], v[152:155], v[136:139], v[28:31]
	v_mfma_f32_16x16x32_bf16 v[24:27], v[156:159], v[136:139], v[24:27]
	ds_read_b128 v[176:179], v196 offset:8192
	s_waitcnt lgkmcnt(9)
	v_mfma_f32_16x16x32_bf16 v[20:23], v[152:155], v[140:143], v[20:23]
	v_mfma_f32_16x16x32_bf16 v[16:19], v[156:159], v[140:143], v[16:19]
	ds_read_b128 v[180:183], v196 offset:10240
	s_waitcnt lgkmcnt(9)
	v_mfma_f32_16x16x32_bf16 v[12:15], v[152:155], v[144:147], v[12:15]
	v_mfma_f32_16x16x32_bf16 v[8:11], v[156:159], v[144:147], v[8:11]
	ds_read_b128 v[184:187], v196 offset:12288
	s_waitcnt lgkmcnt(9)
	v_mfma_f32_16x16x32_bf16 v[4:7], v[152:155], v[148:151], v[4:7]
	v_mfma_f32_16x16x32_bf16 v[0:3], v[156:159], v[148:151], v[0:3]
	ds_read_b128 v[188:191], v196 offset:14336
	ds_read_b128 v[192:195], v196 offset:16384
	ds_read_b128 v[196:199], v196 offset:18432
	s_waitcnt lgkmcnt(9)
	v_mfma_f32_16x16x32_bf16 v[76:79], v[200:203], v[160:163], v[76:79]
	v_mfma_f32_16x16x32_bf16 v[72:75], v[204:207], v[160:163], v[72:75]
	s_waitcnt lgkmcnt(8)
	v_mfma_f32_16x16x32_bf16 v[68:71], v[200:203], v[164:167], v[68:71]
	v_mfma_f32_16x16x32_bf16 v[64:67], v[204:207], v[164:167], v[64:67]
	s_waitcnt lgkmcnt(7)
	v_mfma_f32_16x16x32_bf16 v[60:63], v[200:203], v[168:171], v[60:63]
	v_mfma_f32_16x16x32_bf16 v[56:59], v[204:207], v[168:171], v[56:59]
	s_waitcnt lgkmcnt(6)
	v_mfma_f32_16x16x32_bf16 v[52:55], v[200:203], v[172:175], v[52:55]
	v_mfma_f32_16x16x32_bf16 v[48:51], v[204:207], v[172:175], v[48:51]
	s_waitcnt lgkmcnt(5)
	v_mfma_f32_16x16x32_bf16 v[44:47], v[200:203], v[176:179], v[44:47]
	v_mfma_f32_16x16x32_bf16 v[40:43], v[204:207], v[176:179], v[40:43]
	s_waitcnt lgkmcnt(4)
	v_mfma_f32_16x16x32_bf16 v[36:39], v[200:203], v[180:183], v[36:39]
	v_mfma_f32_16x16x32_bf16 v[32:35], v[204:207], v[180:183], v[32:35]
	s_waitcnt lgkmcnt(3)
	v_mfma_f32_16x16x32_bf16 v[28:31], v[200:203], v[184:187], v[28:31]
	v_mfma_f32_16x16x32_bf16 v[24:27], v[204:207], v[184:187], v[24:27]
	s_waitcnt lgkmcnt(2)
	v_mfma_f32_16x16x32_bf16 v[20:23], v[200:203], v[188:191], v[20:23]
	v_mfma_f32_16x16x32_bf16 v[16:19], v[204:207], v[188:191], v[16:19]
	s_waitcnt lgkmcnt(1)
	v_mfma_f32_16x16x32_bf16 v[12:15], v[200:203], v[192:195], v[12:15]
	v_mfma_f32_16x16x32_bf16 v[8:11], v[204:207], v[192:195], v[8:11]
	s_waitcnt lgkmcnt(0)
	v_mfma_f32_16x16x32_bf16 v[4:7], v[200:203], v[196:199], v[4:7]
	v_mfma_f32_16x16x32_bf16 v[0:3], v[204:207], v[196:199], v[0:3]
	s_cmp_eq_u32 s101, 0
	s_cbranch_scc1 .Lgxd_pbb
	s_add_u32 s12, s99, 0x1a000
	s_cmp_ge_u32 s12, 0x27000
	s_cselect_b32 s13, 0x27000, 0
	s_sub_u32 s12, s12, s13
	v_add_u32_e32 v168, s12, v98
	s_mov_b32 s12, 0xffffff80
	s_mov_b32 s13, -1
	v_lshl_add_u64 v[94:95], v[102:103], 0, s[12:13]
	v_lshl_add_u64 v[186:187], v[104:105], 0, s[12:13]
	v_readfirstlane_b32 s98, v168
	s_mov_b64 s[12:13], 0x7c31080
	v_lshl_add_u64 v[188:189], v[94:95], 0, s[12:13]
	s_mov_b32 m0, s98
	s_nop 0
	global_load_lds_dwordx4 v[188:189], off
	s_mov_b64 s[12:13], 0x7c89080
	v_lshl_add_u64 v[188:189], v[94:95], 0, s[12:13]
	s_add_u32 m0, s98, 0x2000
	s_nop 0
	global_load_lds_dwordx4 v[188:189], off
	s_mov_b64 s[12:13], 0x7ce1080
	v_lshl_add_u64 v[188:189], v[94:95], 0, s[12:13]
	s_add_u32 m0, s98, 0x4000
	s_nop 0
	global_load_lds_dwordx4 v[188:189], off
	s_mov_b64 s[12:13], 0x1060080
	v_lshl_add_u64 v[188:189], v[186:187], 0, s[12:13]
	s_add_u32 m0, s98, 0x5000
	s_nop 0
	global_load_lds_dwordx4 v[188:189], off
	s_mov_b64 s[12:13], 0x10b8080
	v_lshl_add_u64 v[188:189], v[186:187], 0, s[12:13]
	s_add_u32 m0, s98, 0x7000
	s_nop 0
	global_load_lds_dwordx4 v[188:189], off
	s_mov_b64 s[12:13], 0x1110080
	v_lshl_add_u64 v[188:189], v[186:187], 0, s[12:13]
	s_add_u32 m0, s98, 0x9000
	s_nop 0
	global_load_lds_dwordx4 v[188:189], off
	s_mov_b64 s[12:13], 0x1168080
	v_lshl_add_u64 v[188:189], v[186:187], 0, s[12:13]
	s_add_u32 m0, s98, 0xb000
	s_nop 0
	global_load_lds_dwordx4 v[188:189], off

.Lgxd_pcw1:
	s_waitcnt lgkmcnt(0)
	s_barrier
	ds_read_b128 v[152:155], v164 offset:20480
	ds_read_b128 v[156:159], v164 offset:22528
	ds_read_b128 v[108:111], v165
	ds_read_b128 v[112:115], v165 offset:2048
	ds_read_b128 v[116:119], v165 offset:4096
	ds_read_b128 v[120:123], v165 offset:6144
	ds_read_b128 v[124:127], v165 offset:8192
	ds_read_b128 v[132:135], v165 offset:10240
	ds_read_b128 v[136:139], v165 offset:12288
	ds_read_b128 v[140:143], v165 offset:14336
	ds_read_b128 v[144:147], v165 offset:16384
	ds_read_b128 v[148:151], v165 offset:18432
	s_waitcnt lgkmcnt(9)
	v_mfma_f32_16x16x32_bf16 v[76:79], v[152:155], v[108:111], v[76:79]
	v_mfma_f32_16x16x32_bf16 v[72:75], v[156:159], v[108:111], v[72:75]
	ds_read_b128 v[200:203], v192 offset:20480
	s_waitcnt lgkmcnt(9)
	v_mfma_f32_16x16x32_bf16 v[68:71], v[152:155], v[112:115], v[68:71]
	v_mfma_f32_16x16x32_bf16 v[64:67], v[156:159], v[112:115], v[64:67]
	ds_read_b128 v[204:207], v192 offset:22528
	s_waitcnt lgkmcnt(9)
	v_mfma_f32_16x16x32_bf16 v[60:63], v[152:155], v[116:119], v[60:63]
	v_mfma_f32_16x16x32_bf16 v[56:59], v[156:159], v[116:119], v[56:59]
	ds_read_b128 v[160:163], v196
	s_waitcnt lgkmcnt(9)
	v_mfma_f32_16x16x32_bf16 v[52:55], v[152:155], v[120:123], v[52:55]
	v_mfma_f32_16x16x32_bf16 v[48:51], v[156:159], v[120:123], v[48:51]
	ds_read_b128 v[164:167], v196 offset:2048
	s_waitcnt lgkmcnt(9)
	v_mfma_f32_16x16x32_bf16 v[44:47], v[152:155], v[124:127], v[44:47]
	v_mfma_f32_16x16x32_bf16 v[40:43], v[156:159], v[124:127], v[40:43]
	ds_read_b128 v[168:171], v196 offset:4096
	s_waitcnt lgkmcnt(9)
	v_mfma_f32_16x16x32_bf16 v[36:39], v[152:155], v[132:135], v[36:39]
	v_mfma_f32_16x16x32_bf16 v[32:35], v[156:159], v[132:135], v[32:35]
	ds_read_b128 v[172:175], v196 offset:6144
	s_waitcnt lgkmcnt(9)
	v_mfma_f32_16x16x32_bf16 v[28:31], v[152:155], v[136:139], v[28:31]
	v_mfma_f32_16x16x32_bf16 v[24:27], v[156:159], v[136:139], v[24:27]
	ds_read_b128 v[176:179], v196 offset:8192
	s_waitcnt lgkmcnt(9)
	v_mfma_f32_16x16x32_bf16 v[20:23], v[152:155], v[140:143], v[20:23]
	v_mfma_f32_16x16x32_bf16 v[16:19], v[156:159], v[140:143], v[16:19]
	ds_read_b128 v[180:183], v196 offset:10240
	s_waitcnt lgkmcnt(9)
	v_mfma_f32_16x16x32_bf16 v[12:15], v[152:155], v[144:147], v[12:15]
	v_mfma_f32_16x16x32_bf16 v[8:11], v[156:159], v[144:147], v[8:11]
	ds_read_b128 v[184:187], v196 offset:12288
	s_waitcnt lgkmcnt(9)
	v_mfma_f32_16x16x32_bf16 v[4:7], v[152:155], v[148:151], v[4:7]
	v_mfma_f32_16x16x32_bf16 v[0:3], v[156:159], v[148:151], v[0:3]
	ds_read_b128 v[188:191], v196 offset:14336
	ds_read_b128 v[192:195], v196 offset:16384
	ds_read_b128 v[196:199], v196 offset:18432
	s_waitcnt lgkmcnt(9)
	v_mfma_f32_16x16x32_bf16 v[76:79], v[200:203], v[160:163], v[76:79]
	v_mfma_f32_16x16x32_bf16 v[72:75], v[204:207], v[160:163], v[72:75]
	s_waitcnt lgkmcnt(8)
	v_mfma_f32_16x16x32_bf16 v[68:71], v[200:203], v[164:167], v[68:71]
	v_mfma_f32_16x16x32_bf16 v[64:67], v[204:207], v[164:167], v[64:67]
	s_waitcnt lgkmcnt(7)
	v_mfma_f32_16x16x32_bf16 v[60:63], v[200:203], v[168:171], v[60:63]
	v_mfma_f32_16x16x32_bf16 v[56:59], v[204:207], v[168:171], v[56:59]
	s_waitcnt lgkmcnt(6)
	v_mfma_f32_16x16x32_bf16 v[52:55], v[200:203], v[172:175], v[52:55]
	v_mfma_f32_16x16x32_bf16 v[48:51], v[204:207], v[172:175], v[48:51]
	s_waitcnt lgkmcnt(5)
	v_mfma_f32_16x16x32_bf16 v[44:47], v[200:203], v[176:179], v[44:47]
	v_mfma_f32_16x16x32_bf16 v[40:43], v[204:207], v[176:179], v[40:43]
	s_waitcnt lgkmcnt(4)
	v_mfma_f32_16x16x32_bf16 v[36:39], v[200:203], v[180:183], v[36:39]
	v_mfma_f32_16x16x32_bf16 v[32:35], v[204:207], v[180:183], v[32:35]
	s_waitcnt lgkmcnt(3)
	v_mfma_f32_16x16x32_bf16 v[28:31], v[200:203], v[184:187], v[28:31]
	v_mfma_f32_16x16x32_bf16 v[24:27], v[204:207], v[184:187], v[24:27]
	s_waitcnt lgkmcnt(2)
	v_mfma_f32_16x16x32_bf16 v[20:23], v[200:203], v[188:191], v[20:23]
	v_mfma_f32_16x16x32_bf16 v[16:19], v[204:207], v[188:191], v[16:19]
	s_waitcnt lgkmcnt(1)
	v_mfma_f32_16x16x32_bf16 v[12:15], v[200:203], v[192:195], v[12:15]
	v_mfma_f32_16x16x32_bf16 v[8:11], v[204:207], v[192:195], v[8:11]
	s_waitcnt lgkmcnt(0)
	v_mfma_f32_16x16x32_bf16 v[4:7], v[200:203], v[196:199], v[4:7]
	v_mfma_f32_16x16x32_bf16 v[0:3], v[204:207], v[196:199], v[0:3]
	s_cmp_eq_u32 s101, 0
	s_cbranch_scc1 .Lgxd_pcb
	s_add_u32 s12, s99, 0x1a000
	s_cmp_ge_u32 s12, 0x27000
	s_cselect_b32 s13, 0x27000, 0
	s_sub_u32 s12, s12, s13
	v_add_u32_e32 v168, s12, v98
	s_mov_b64 s[12:13], 0
	v_lshl_add_u64 v[94:95], v[102:103], 0, s[12:13]
	v_lshl_add_u64 v[186:187], v[104:105], 0, s[12:13]
	v_readfirstlane_b32 s98, v168
	s_mov_b64 s[12:13], 0x7c31080
	v_lshl_add_u64 v[188:189], v[94:95], 0, s[12:13]
	s_mov_b32 m0, s98
	s_nop 0
	global_load_lds_dwordx4 v[188:189], off
	s_mov_b64 s[12:13], 0x7c89080
	v_lshl_add_u64 v[188:189], v[94:95], 0, s[12:13]
	s_add_u32 m0, s98, 0x2000
	s_nop 0
	global_load_lds_dwordx4 v[188:189], off
	s_mov_b64 s[12:13], 0x7ce1080
	v_lshl_add_u64 v[188:189], v[94:95], 0, s[12:13]
	s_add_u32 m0, s98, 0x4000
	s_nop 0
	global_load_lds_dwordx4 v[188:189], off
	s_mov_b64 s[12:13], 0x1060080
	v_lshl_add_u64 v[188:189], v[186:187], 0, s[12:13]
	s_add_u32 m0, s98, 0x5000
	s_nop 0
	global_load_lds_dwordx4 v[188:189], off
	s_mov_b64 s[12:13], 0x10b8080
	v_lshl_add_u64 v[188:189], v[186:187], 0, s[12:13]
	s_add_u32 m0, s98, 0x7000
	s_nop 0
	global_load_lds_dwordx4 v[188:189], off
	s_mov_b64 s[12:13], 0x1110080
	v_lshl_add_u64 v[188:189], v[186:187], 0, s[12:13]
	s_add_u32 m0, s98, 0x9000
	s_nop 0
	global_load_lds_dwordx4 v[188:189], off
	s_mov_b64 s[12:13], 0x1168080
	v_lshl_add_u64 v[188:189], v[186:187], 0, s[12:13]
	s_add_u32 m0, s98, 0xb000
	s_nop 0
	global_load_lds_dwordx4 v[188:189], off

.Lgxd_q:
	s_add_u32 s12, s99, 0x1a000
	s_cmp_ge_u32 s12, 0x27000
	s_cselect_b32 s13, 0x27000, 0
	s_sub_u32 s12, s12, s13
	v_add_u32_e32 v168, s12, v98
	s_add_u32 s12, s10, 0x80
	s_addc_u32 s13, s11, 0
	v_lshl_add_u64 v[94:95], v[90:91], 0, s[12:13]
	v_lshl_add_u64 v[186:187], v[92:93], 0, s[12:13]
	v_readfirstlane_b32 s98, v168
	v_add_u32_e32 v164, s99, v97
	v_add_u32_e32 v165, s99, v99
	v_add_u32_e32 v192, v164, v101
	v_add_u32_e32 v196, v165, v101
	v_add_u32_e32 v164, v164, v100
	v_add_u32_e32 v165, v165, v100
	s_waitcnt vmcnt(6) lgkmcnt(0)
	s_barrier
	s_mov_b64 s[12:13], 0x7c31080
	v_lshl_add_u64 v[188:189], v[94:95], 0, s[12:13]
	s_mov_b32 m0, s98
	s_nop 0
	global_load_lds_dwordx4 v[188:189], off
	s_mov_b64 s[12:13], 0x7c89080
	v_lshl_add_u64 v[188:189], v[94:95], 0, s[12:13]
	s_add_u32 m0, s98, 0x2000
	s_nop 0
	global_load_lds_dwordx4 v[188:189], off
	s_mov_b64 s[12:13], 0x1060080
	v_lshl_add_u64 v[188:189], v[186:187], 0, s[12:13]
	s_add_u32 m0, s98, 0x5000
	s_nop 0
	global_load_lds_dwordx4 v[188:189], off
	s_mov_b64 s[12:13], 0x10b8080
	v_lshl_add_u64 v[188:189], v[186:187], 0, s[12:13]
	s_add_u32 m0, s98, 0x7000
	s_nop 0
	global_load_lds_dwordx4 v[188:189], off
	s_mov_b64 s[12:13], 0x1110080
	v_lshl_add_u64 v[188:189], v[186:187], 0, s[12:13]
	s_add_u32 m0, s98, 0x9000
	s_nop 0
	global_load_lds_dwordx4 v[188:189], off
	s_mov_b64 s[12:13], 0x1168080
	v_lshl_add_u64 v[188:189], v[186:187], 0, s[12:13]
	s_add_u32 m0, s98, 0xb000
	s_nop 0
	global_load_lds_dwordx4 v[188:189], off
	ds_read_b128 v[152:155], v164 offset:20480
	ds_read_b128 v[156:159], v164 offset:22528
	ds_read_b128 v[108:111], v165
	ds_read_b128 v[112:115], v165 offset:2048
	ds_read_b128 v[116:119], v165 offset:4096
	ds_read_b128 v[120:123], v165 offset:6144
	ds_read_b128 v[124:127], v165 offset:8192
	ds_read_b128 v[132:135], v165 offset:10240
	ds_read_b128 v[136:139], v165 offset:12288
	ds_read_b128 v[140:143], v165 offset:14336
	ds_read_b128 v[144:147], v165 offset:16384
	ds_read_b128 v[148:151], v165 offset:18432
	s_waitcnt lgkmcnt(9)
	v_mfma_f32_16x16x32_bf16 v[76:79], v[152:155], v[108:111], v[76:79]
	v_mfma_f32_16x16x32_bf16 v[72:75], v[156:159], v[108:111], v[72:75]
	ds_read_b128 v[200:203], v192 offset:20480
	s_waitcnt lgkmcnt(9)
	v_mfma_f32_16x16x32_bf16 v[68:71], v[152:155], v[112:115], v[68:71]
	v_mfma_f32_16x16x32_bf16 v[64:67], v[156:159], v[112:115], v[64:67]
	ds_read_b128 v[204:207], v192 offset:22528
	s_waitcnt lgkmcnt(9)
	v_mfma_f32_16x16x32_bf16 v[60:63], v[152:155], v[116:119], v[60:63]
	v_mfma_f32_16x16x32_bf16 v[56:59], v[156:159], v[116:119], v[56:59]
	ds_read_b128 v[160:163], v196
	s_waitcnt lgkmcnt(9)
	v_mfma_f32_16x16x32_bf16 v[52:55], v[152:155], v[120:123], v[52:55]
	v_mfma_f32_16x16x32_bf16 v[48:51], v[156:159], v[120:123], v[48:51]
	ds_read_b128 v[164:167], v196 offset:2048
	s_waitcnt lgkmcnt(9)
	v_mfma_f32_16x16x32_bf16 v[44:47], v[152:155], v[124:127], v[44:47]
	v_mfma_f32_16x16x32_bf16 v[40:43], v[156:159], v[124:127], v[40:43]
	ds_read_b128 v[168:171], v196 offset:4096
	s_waitcnt lgkmcnt(9)
	v_mfma_f32_16x16x32_bf16 v[36:39], v[152:155], v[132:135], v[36:39]
	v_mfma_f32_16x16x32_bf16 v[32:35], v[156:159], v[132:135], v[32:35]
	ds_read_b128 v[172:175], v196 offset:6144
	s_waitcnt lgkmcnt(9)
	v_mfma_f32_16x16x32_bf16 v[28:31], v[152:155], v[136:139], v[28:31]
	v_mfma_f32_16x16x32_bf16 v[24:27], v[156:159], v[136:139], v[24:27]
	ds_read_b128 v[176:179], v196 offset:8192
	s_waitcnt lgkmcnt(9)
	v_mfma_f32_16x16x32_bf16 v[20:23], v[152:155], v[140:143], v[20:23]
	v_mfma_f32_16x16x32_bf16 v[16:19], v[156:159], v[140:143], v[16:19]
	ds_read_b128 v[180:183], v196 offset:10240
	s_waitcnt lgkmcnt(9)
	v_mfma_f32_16x16x32_bf16 v[12:15], v[152:155], v[144:147], v[12:15]
	v_mfma_f32_16x16x32_bf16 v[8:11], v[156:159], v[144:147], v[8:11]
	ds_read_b128 v[184:187], v196 offset:12288
	s_waitcnt lgkmcnt(9)
	v_mfma_f32_16x16x32_bf16 v[4:7], v[152:155], v[148:151], v[4:7]
	v_mfma_f32_16x16x32_bf16 v[0:3], v[156:159], v[148:151], v[0:3]
	ds_read_b128 v[188:191], v196 offset:14336
	ds_read_b128 v[192:195], v196 offset:16384
	ds_read_b128 v[196:199], v196 offset:18432
	s_waitcnt lgkmcnt(9)
	v_mfma_f32_16x16x32_bf16 v[76:79], v[200:203], v[160:163], v[76:79]
	v_mfma_f32_16x16x32_bf16 v[72:75], v[204:207], v[160:163], v[72:75]
	s_waitcnt lgkmcnt(8)
	v_mfma_f32_16x16x32_bf16 v[68:71], v[200:203], v[164:167], v[68:71]
	v_mfma_f32_16x16x32_bf16 v[64:67], v[204:207], v[164:167], v[64:67]
	s_waitcnt lgkmcnt(7)
	v_mfma_f32_16x16x32_bf16 v[60:63], v[200:203], v[168:171], v[60:63]
	v_mfma_f32_16x16x32_bf16 v[56:59], v[204:207], v[168:171], v[56:59]
	s_waitcnt lgkmcnt(6)
	v_mfma_f32_16x16x32_bf16 v[52:55], v[200:203], v[172:175], v[52:55]
	v_mfma_f32_16x16x32_bf16 v[48:51], v[204:207], v[172:175], v[48:51]
	s_waitcnt lgkmcnt(5)
	v_mfma_f32_16x16x32_bf16 v[44:47], v[200:203], v[176:179], v[44:47]
	v_mfma_f32_16x16x32_bf16 v[40:43], v[204:207], v[176:179], v[40:43]
	s_waitcnt lgkmcnt(4)
	v_mfma_f32_16x16x32_bf16 v[36:39], v[200:203], v[180:183], v[36:39]
	v_mfma_f32_16x16x32_bf16 v[32:35], v[204:207], v[180:183], v[32:35]
	s_waitcnt lgkmcnt(3)
	v_mfma_f32_16x16x32_bf16 v[28:31], v[200:203], v[184:187], v[28:31]
	v_mfma_f32_16x16x32_bf16 v[24:27], v[204:207], v[184:187], v[24:27]
	s_waitcnt lgkmcnt(2)
	v_mfma_f32_16x16x32_bf16 v[20:23], v[200:203], v[188:191], v[20:23]
	v_mfma_f32_16x16x32_bf16 v[16:19], v[204:207], v[188:191], v[16:19]
	s_waitcnt lgkmcnt(1)
	v_mfma_f32_16x16x32_bf16 v[12:15], v[200:203], v[192:195], v[12:15]
	v_mfma_f32_16x16x32_bf16 v[8:11], v[204:207], v[192:195], v[8:11]
	s_waitcnt lgkmcnt(0)
	v_mfma_f32_16x16x32_bf16 v[4:7], v[200:203], v[196:199], v[4:7]
	v_mfma_f32_16x16x32_bf16 v[0:3], v[204:207], v[196:199], v[0:3]
	s_add_u32 s99, s99, 0xd000
	s_cmp_eq_u32 s99, 0x27000
	s_cselect_b32 s99, 0, s99
	s_add_u32 s10, s10, 0x80
	s_addc_u32 s11, s11, 0
	s_cmpk_eq_i32 s10, 0x1500
	s_cbranch_scc0 .Lgxd_q
	s_cmp_eq_u32 s101, 0
	s_cbranch_scc1 .Lgxd_qbp
	s_add_u32 s12, s99, 0x1a000
	s_cmp_ge_u32 s12, 0x27000
	s_cselect_b32 s13, 0x27000, 0
	s_sub_u32 s12, s12, s13
	v_add_u32_e32 v168, s12, v98
	s_mov_b32 s12, 0xffffff80
	s_mov_b32 s13, -1
	v_lshl_add_u64 v[94:95], v[102:103], 0, s[12:13]
	v_lshl_add_u64 v[186:187], v[104:105], 0, s[12:13]
	v_readfirstlane_b32 s98, v168
.Lgxd_qbp:
	v_add_u32_e32 v164, s99, v97
	v_add_u32_e32 v165, s99, v99
	v_add_u32_e32 v192, v164, v101
	v_add_u32_e32 v196, v165, v101
	v_add_u32_e32 v164, v164, v100
	v_add_u32_e32 v165, v165, v100
	s_waitcnt vmcnt(6) lgkmcnt(0)
	s_barrier
	s_cmp_eq_u32 s101, 0
	s_cbranch_scc1 .Lgxd_qbb
	s_mov_b64 s[12:13], 0x7c31080
	v_lshl_add_u64 v[188:189], v[94:95], 0, s[12:13]
	s_mov_b32 m0, s98
	s_nop 0
	global_load_lds_dwordx4 v[188:189], off
	s_mov_b64 s[12:13], 0x7c89080
	v_lshl_add_u64 v[188:189], v[94:95], 0, s[12:13]
	s_add_u32 m0, s98, 0x2000
	s_nop 0
	global_load_lds_dwordx4 v[188:189], off
	s_mov_b64 s[12:13], 0x1060080
	v_lshl_add_u64 v[188:189], v[186:187], 0, s[12:13]
	s_add_u32 m0, s98, 0x5000
	s_nop 0
	global_load_lds_dwordx4 v[188:189], off
	s_mov_b64 s[12:13], 0x10b8080
	v_lshl_add_u64 v[188:189], v[186:187], 0, s[12:13]
	s_add_u32 m0, s98, 0x7000
	s_nop 0
	global_load_lds_dwordx4 v[188:189], off
	s_mov_b64 s[12:13], 0x1110080
	v_lshl_add_u64 v[188:189], v[186:187], 0, s[12:13]
	s_add_u32 m0, s98, 0x9000
	s_nop 0
	global_load_lds_dwordx4 v[188:189], off
	s_mov_b64 s[12:13], 0x1168080
	v_lshl_add_u64 v[188:189], v[186:187], 0, s[12:13]
	s_add_u32 m0, s98, 0xb000
	s_nop 0
	global_load_lds_dwordx4 v[188:189], off

.Lgxd_qcw1:
	s_waitcnt lgkmcnt(0)
	s_barrier
	s_cmp_eq_u32 s101, 0
	s_cbranch_scc1 .Lgxd_qcb
	s_mov_b64 s[12:13], 0x7c31080
	v_lshl_add_u64 v[188:189], v[94:95], 0, s[12:13]
	s_mov_b32 m0, s98
	s_nop 0
	global_load_lds_dwordx4 v[188:189], off
	s_mov_b64 s[12:13], 0x7c89080
	v_lshl_add_u64 v[188:189], v[94:95], 0, s[12:13]
	s_add_u32 m0, s98, 0x2000
	s_nop 0
	global_load_lds_dwordx4 v[188:189], off
	s_mov_b64 s[12:13], 0x1060080
	v_lshl_add_u64 v[188:189], v[186:187], 0, s[12:13]
	s_add_u32 m0, s98, 0x5000
	s_nop 0
	global_load_lds_dwordx4 v[188:189], off
	s_mov_b64 s[12:13], 0x10b8080
	v_lshl_add_u64 v[188:189], v[186:187], 0, s[12:13]
	s_add_u32 m0, s98, 0x7000
	s_nop 0
	global_load_lds_dwordx4 v[188:189], off
	s_mov_b64 s[12:13], 0x1110080
	v_lshl_add_u64 v[188:189], v[186:187], 0, s[12:13]
	s_add_u32 m0, s98, 0x9000
	s_nop 0
	global_load_lds_dwordx4 v[188:189], off
	s_mov_b64 s[12:13], 0x1168080
	v_lshl_add_u64 v[188:189], v[186:187], 0, s[12:13]
	s_add_u32 m0, s98, 0xb000
	s_nop 0
	global_load_lds_dwordx4 v[188:189], off
